# speedup vs baseline: 1.0077x; 1.0077x over previous
.LBB0_386:
	s_or_b64 exec, exec, s[0:1]
	v_readlane_b32 s80, v249, 5
	s_waitcnt lgkmcnt(0)
	v_lshlrev_b32_e32 v8, 2, v0
	v_lshl_add_u32 v4, v5, 4, v3
	v_readlane_b32 s81, v249, 6
	ds_read2_b32 v[6:7], v4 offset1:32
	s_nop 3
	global_load_dword v9, v8, s[80:81]
	global_load_dword v12, v8, s[80:81] offset:128
	global_load_dword v13, v8, s[80:81] offset:256
	global_load_dword v14, v8, s[80:81] offset:384
	v_ashrrev_i32_e32 v2, 1, v2
	v_and_b32_e32 v2, 0xffffffe0, v2
	s_lshl_b64 s[0:1], s[6:7], 22
	s_waitcnt lgkmcnt(0)
	v_mul_f32_e32 v3, v96, v7
	v_fma_f32 v8, v128, v6, -v3
	v_mul_f32_e32 v3, v80, v7
	v_fma_f32 v15, v112, v6, -v3
	v_mul_f32_e32 v3, v15, v15
	v_mul_f32_e32 v10, v32, v7
	v_fmac_f32_e32 v3, v8, v8
	v_fma_f32 v32, v64, v6, -v10
	v_mul_f32_e32 v7, v16, v7
	v_fmac_f32_e32 v3, v32, v32
	v_fma_f32 v16, v48, v6, -v7
	v_fmac_f32_e32 v3, v16, v16
	ds_swizzle_b32 v6, v3 offset:swizzle(SWAP,1)
	v_add_u32_e32 v2, s79, v2
	s_add_u32 s0, s44, s0
	s_addc_u32 s1, s45, s1
	v_lshlrev_b32_e32 v0, 1, v0
	s_waitcnt lgkmcnt(0)
	v_add_f32_e32 v3, v3, v6
	ds_swizzle_b32 v6, v3 offset:swizzle(SWAP,2)
	v_readlane_b32 s82, v249, 7
	v_readlane_b32 s83, v249, 8
	v_readlane_b32 s84, v249, 9
	v_readlane_b32 s85, v249, 10
	s_waitcnt lgkmcnt(0)
	v_add_f32_e32 v3, v3, v6
	ds_swizzle_b32 v6, v3 offset:swizzle(SWAP,4)
	v_readlane_b32 s86, v249, 11
	v_readlane_b32 s87, v249, 12
	v_readlane_b32 s88, v249, 13
	v_readlane_b32 s89, v249, 14
	s_waitcnt lgkmcnt(0)
	v_add_f32_e32 v3, v3, v6
	ds_swizzle_b32 v6, v3 offset:swizzle(SWAP,8)
	v_readlane_b32 s90, v249, 15
	v_readlane_b32 s91, v249, 16
	v_readlane_b32 s92, v249, 17
	v_readlane_b32 s93, v249, 18
	s_waitcnt lgkmcnt(0)
	v_add_f32_e32 v6, v3, v6
	ds_swizzle_b32 v7, v6 offset:swizzle(SWAP,16)
	v_ashrrev_i32_e32 v3, 31, v2
	v_lshlrev_b64 v[2:3], 11, v[2:3]
	v_lshl_add_u64 v[2:3], s[0:1], 0, v[2:3]
	v_readlane_b32 s0, v249, 55
	s_waitcnt lgkmcnt(0)
	v_add_f32_e32 v6, v6, v7
	v_fmamk_f32 v6, v6, 0x3c000000, v230
	v_mul_f32_e32 v7, 0x4f800000, v6
	v_cmp_gt_f32_e32 vcc, s69, v6
	v_readlane_b32 s1, v249, 56
	v_readlane_b32 s94, v249, 19
	v_cndmask_b32_e32 v6, v6, v7, vcc
	v_sqrt_f32_e32 v7, v6
	v_lshl_add_u64 v[2:3], s[0:1], 1, v[2:3]
	v_lshl_add_u64 v[2:3], v[2:3], 0, v[0:1]
	v_lshlrev_b32_e32 v0, 13, v5
	v_add_u32_e32 v5, -1, v7
	v_add_u32_e32 v10, 1, v7
	v_fma_f32 v11, -v5, v7, v6
	v_fma_f32 v48, -v10, v7, v6
	v_cmp_ge_f32_e64 s[8:9], 0, v11
	v_readlane_b32 s95, v249, 20
	s_nop 0
	v_cndmask_b32_e64 v5, v7, v5, s[8:9]
	v_cmp_lt_f32_e64 s[8:9], 0, v48
	s_nop 1
	v_cndmask_b32_e64 v5, v5, v10, s[8:9]
	v_mul_f32_e32 v7, 0x37800000, v5
	v_cndmask_b32_e32 v5, v5, v7, vcc
	v_cmp_class_f32_e32 vcc, v6, v231
	v_lshl_add_u64 v[10:11], v[2:3], 0, v[0:1]
	s_nop 0
	v_cndmask_b32_e32 v5, v5, v6, vcc
	v_div_scale_f32 v6, s[0:1], v5, v5, 1.0
	v_rcp_f32_e32 v7, v6
	v_div_scale_f32 v48, vcc, 1.0, v5, 1.0
	v_fma_f32 v64, -v6, v7, 1.0
	v_fmac_f32_e32 v7, v64, v7
	v_mul_f32_e32 v64, v48, v7
	v_fma_f32 v80, -v6, v64, v48
	v_fmac_f32_e32 v64, v80, v7
	v_fma_f32 v6, -v6, v64, v48
	v_div_fmas_f32 v6, v6, v7, v64
	v_div_fixup_f32 v48, v6, v5, 1.0
	v_mul_f32_e32 v64, v8, v48
	s_waitcnt vmcnt(0)
	v_mul_f32_e32 v7, 0x3f4ccccd, v9
	v_mul_f32_e32 v9, v7, v64
	v_mul_f32_e32 v15, v15, v48
	v_mul_f32_e32 v8, 0x3f4ccccd, v12
	v_cvt_pk_bf16_f32 v9, v9, v1
	v_mul_f32_e32 v12, v8, v15
	global_store_short v[10:11], v9, off
	v_cvt_pk_bf16_f32 v9, v12, v1
	v_mul_f32_e32 v6, 0x3f4ccccd, v13
	global_store_short v[10:11], v9, off offset:64
	v_mul_f32_e32 v9, v32, v48
	v_mul_f32_e32 v9, v6, v9
	v_cvt_pk_bf16_f32 v9, v9, v1
	v_mul_f32_e32 v5, 0x3f4ccccd, v14
	global_store_short v[10:11], v9, off offset:128
	v_mul_f32_e32 v9, v16, v48
	v_mul_f32_e32 v9, v5, v9
	v_cvt_pk_bf16_f32 v9, v9, v1
	ds_read2_b32 v[12:13], v4 offset0:1 offset1:33
	global_store_short v[10:11], v9, off offset:192
	s_waitcnt lgkmcnt(0)
	v_mul_f32_e32 v15, v81, v13
	v_mul_f32_e32 v14, v97, v13
	v_fma_f32 v15, v113, v12, -v15
	v_fma_f32 v14, v129, v12, -v14
	v_mul_f32_e32 v16, v15, v15
	v_mul_f32_e32 v32, v33, v13
	v_fmac_f32_e32 v16, v14, v14
	v_fma_f32 v32, v65, v12, -v32
	v_mul_f32_e32 v13, v17, v13
	v_fmac_f32_e32 v16, v32, v32
	v_fma_f32 v17, v49, v12, -v13
	v_fmac_f32_e32 v16, v17, v17
	s_nop 1
	v_add_f32_dpp v12, v16, v16 quad_perm:[1,0,3,2] row_mask:0xf bank_mask:0xf
	s_nop 1
	v_add_f32_dpp v12, v12, v12 quad_perm:[2,3,0,1] row_mask:0xf bank_mask:0xf
	s_nop 1
	v_add_f32_dpp v12, v12, v12 row_half_mirror row_mask:0xf bank_mask:0xf
	s_nop 1
	v_add_f32_dpp v12, v12, v12 row_mirror row_mask:0xf bank_mask:0xf
	ds_swizzle_b32 v13, v12 offset:swizzle(SWAP,16)
	s_waitcnt lgkmcnt(0)
	v_add_f32_e32 v12, v12, v13
	v_fmamk_f32 v12, v12, 0x3c000000, v230
	v_mul_f32_e32 v13, 0x4f800000, v12
	v_cmp_gt_f32_e32 vcc, s69, v12
	s_nop 1
	v_cndmask_b32_e32 v16, v12, v13, vcc
	v_sqrt_f32_e32 v33, v16
	v_mov_b32_e32 v13, v1
	v_or_b32_e32 v12, 0x800, v0
	v_lshl_add_u64 v[12:13], v[2:3], 0, v[12:13]
	v_add_u32_e32 v48, -1, v33
	v_add_u32_e32 v49, 1, v33
	v_fma_f32 v64, -v48, v33, v16
	v_fma_f32 v65, -v49, v33, v16
	v_cmp_ge_f32_e64 s[8:9], 0, v64
	s_nop 1
	v_cndmask_b32_e64 v33, v33, v48, s[8:9]
	v_cmp_lt_f32_e64 s[8:9], 0, v65
	s_nop 1
	v_cndmask_b32_e64 v33, v33, v49, s[8:9]
	v_mul_f32_e32 v48, 0x37800000, v33
	v_cndmask_b32_e32 v33, v33, v48, vcc
	v_cmp_class_f32_e32 vcc, v16, v231
	s_nop 1
	v_cndmask_b32_e32 v16, v33, v16, vcc
	v_div_scale_f32 v33, s[0:1], v16, v16, 1.0
	v_rcp_f32_e32 v48, v33
	v_div_scale_f32 v9, vcc, 1.0, v16, 1.0
	v_fma_f32 v10, -v33, v48, 1.0
	v_fmac_f32_e32 v48, v10, v48
	v_mul_f32_e32 v10, v9, v48
	v_fma_f32 v11, -v33, v10, v9
	v_fmac_f32_e32 v10, v11, v48
	v_fma_f32 v9, -v33, v10, v9
	v_div_fmas_f32 v9, v9, v48, v10
	v_div_fixup_f32 v9, v9, v16, 1.0
	v_mul_f32_e32 v10, v14, v9
	v_mul_f32_e32 v10, v7, v10
	v_mul_f32_e32 v11, v15, v9
	v_cvt_pk_bf16_f32 v10, v10, v1
	v_mul_f32_e32 v11, v8, v11
	global_store_short v[12:13], v10, off
	v_cvt_pk_bf16_f32 v10, v11, v1
	global_store_short v[12:13], v10, off offset:64
	v_mul_f32_e32 v10, v32, v9
	v_mul_f32_e32 v10, v6, v10
	v_mul_f32_e32 v9, v17, v9
	v_cvt_pk_bf16_f32 v10, v10, v1
	v_mul_f32_e32 v9, v5, v9
	global_store_short v[12:13], v10, off offset:128
	v_cvt_pk_bf16_f32 v9, v9, v1
	ds_read2_b32 v[10:11], v4 offset0:2 offset1:34
	global_store_short v[12:13], v9, off offset:192
	s_waitcnt lgkmcnt(0)
	v_mul_f32_e32 v15, v82, v11
	v_mul_f32_e32 v14, v98, v11
	v_fma_f32 v15, v114, v10, -v15
	v_fma_f32 v14, v130, v10, -v14
	v_mul_f32_e32 v16, v15, v15
	v_mul_f32_e32 v17, v34, v11
	v_fmac_f32_e32 v16, v14, v14
	v_fma_f32 v17, v66, v10, -v17
	v_mul_f32_e32 v11, v18, v11
	v_fmac_f32_e32 v16, v17, v17
	v_fma_f32 v18, v50, v10, -v11
	v_fmac_f32_e32 v16, v18, v18
	s_nop 1
	v_add_f32_dpp v10, v16, v16 quad_perm:[1,0,3,2] row_mask:0xf bank_mask:0xf
	s_nop 1
	v_add_f32_dpp v10, v10, v10 quad_perm:[2,3,0,1] row_mask:0xf bank_mask:0xf
	s_nop 1
	v_add_f32_dpp v10, v10, v10 row_half_mirror row_mask:0xf bank_mask:0xf
	s_nop 1
	v_add_f32_dpp v10, v10, v10 row_mirror row_mask:0xf bank_mask:0xf
	ds_swizzle_b32 v11, v10 offset:swizzle(SWAP,16)
	s_waitcnt lgkmcnt(0)
	v_add_f32_e32 v10, v10, v11
	v_fmamk_f32 v10, v10, 0x3c000000, v230
	v_mul_f32_e32 v11, 0x4f800000, v10
	v_cmp_gt_f32_e32 vcc, s69, v10
	s_nop 1
	v_cndmask_b32_e32 v16, v10, v11, vcc
	v_sqrt_f32_e32 v32, v16
	v_mov_b32_e32 v11, v1
	v_or_b32_e32 v10, 0x1000, v0
	v_lshl_add_u64 v[10:11], v[2:3], 0, v[10:11]
	v_add_u32_e32 v33, -1, v32
	v_add_u32_e32 v34, 1, v32
	v_fma_f32 v48, -v33, v32, v16
	v_fma_f32 v49, -v34, v32, v16
	v_cmp_ge_f32_e64 s[8:9], 0, v48
	s_nop 1
	v_cndmask_b32_e64 v32, v32, v33, s[8:9]
	v_cmp_lt_f32_e64 s[8:9], 0, v49
	s_nop 1
	v_cndmask_b32_e64 v32, v32, v34, s[8:9]
	v_mul_f32_e32 v33, 0x37800000, v32
	v_cndmask_b32_e32 v32, v32, v33, vcc
	v_cmp_class_f32_e32 vcc, v16, v231
	s_nop 1
	v_cndmask_b32_e32 v16, v32, v16, vcc
	v_div_scale_f32 v32, s[0:1], v16, v16, 1.0
	v_rcp_f32_e32 v33, v32
	v_div_scale_f32 v9, vcc, 1.0, v16, 1.0
	v_fma_f32 v12, -v32, v33, 1.0
	v_fmac_f32_e32 v33, v12, v33
	v_mul_f32_e32 v12, v9, v33
	v_fma_f32 v13, -v32, v12, v9
	v_fmac_f32_e32 v12, v13, v33
	v_fma_f32 v9, -v32, v12, v9
	v_div_fmas_f32 v9, v9, v33, v12
	v_div_fixup_f32 v9, v9, v16, 1.0
	v_mul_f32_e32 v12, v14, v9
	v_mul_f32_e32 v12, v7, v12
	v_mul_f32_e32 v13, v15, v9
	v_cvt_pk_bf16_f32 v12, v12, v1
	v_mul_f32_e32 v13, v8, v13
	global_store_short v[10:11], v12, off
	v_cvt_pk_bf16_f32 v12, v13, v1
	global_store_short v[10:11], v12, off offset:64
	v_mul_f32_e32 v12, v17, v9
	v_mul_f32_e32 v12, v6, v12
	v_mul_f32_e32 v9, v18, v9
	v_cvt_pk_bf16_f32 v12, v12, v1
	v_mul_f32_e32 v9, v5, v9
	global_store_short v[10:11], v12, off offset:128
	v_cvt_pk_bf16_f32 v9, v9, v1
	ds_read2_b32 v[12:13], v4 offset0:3 offset1:35
	global_store_short v[10:11], v9, off offset:192
	s_waitcnt lgkmcnt(0)
	v_mul_f32_e32 v15, v83, v13
	v_mul_f32_e32 v14, v99, v13
	v_fma_f32 v15, v115, v12, -v15
	v_fma_f32 v14, v131, v12, -v14
	v_mul_f32_e32 v16, v15, v15
	v_mul_f32_e32 v17, v35, v13
	v_fmac_f32_e32 v16, v14, v14
	v_fma_f32 v17, v67, v12, -v17
	v_mul_f32_e32 v13, v19, v13
	v_fmac_f32_e32 v16, v17, v17
	v_fma_f32 v18, v51, v12, -v13
	v_fmac_f32_e32 v16, v18, v18
	s_nop 1
	v_add_f32_dpp v12, v16, v16 quad_perm:[1,0,3,2] row_mask:0xf bank_mask:0xf
	s_nop 1
	v_add_f32_dpp v12, v12, v12 quad_perm:[2,3,0,1] row_mask:0xf bank_mask:0xf
	s_nop 1
	v_add_f32_dpp v12, v12, v12 row_half_mirror row_mask:0xf bank_mask:0xf
	s_nop 1
	v_add_f32_dpp v12, v12, v12 row_mirror row_mask:0xf bank_mask:0xf
	ds_swizzle_b32 v13, v12 offset:swizzle(SWAP,16)
	s_waitcnt lgkmcnt(0)
	v_add_f32_e32 v12, v12, v13
	v_fmamk_f32 v12, v12, 0x3c000000, v230
	v_mul_f32_e32 v13, 0x4f800000, v12
	v_cmp_gt_f32_e32 vcc, s69, v12
	s_nop 1
	v_cndmask_b32_e32 v16, v12, v13, vcc
	v_sqrt_f32_e32 v19, v16
	v_mov_b32_e32 v13, v1
	v_or_b32_e32 v12, 0x1800, v0
	v_lshl_add_u64 v[12:13], v[2:3], 0, v[12:13]
	v_add_u32_e32 v32, -1, v19
	v_add_u32_e32 v33, 1, v19
	v_fma_f32 v34, -v32, v19, v16
	v_fma_f32 v35, -v33, v19, v16
	v_cmp_ge_f32_e64 s[8:9], 0, v34
	s_nop 1
	v_cndmask_b32_e64 v19, v19, v32, s[8:9]
	v_cmp_lt_f32_e64 s[8:9], 0, v35
	s_nop 1
	v_cndmask_b32_e64 v19, v19, v33, s[8:9]
	v_mul_f32_e32 v32, 0x37800000, v19
	v_cndmask_b32_e32 v19, v19, v32, vcc
	v_cmp_class_f32_e32 vcc, v16, v231
	s_nop 1
	v_cndmask_b32_e32 v16, v19, v16, vcc
	v_div_scale_f32 v19, s[0:1], v16, v16, 1.0
	v_rcp_f32_e32 v32, v19
	v_div_scale_f32 v9, vcc, 1.0, v16, 1.0
	v_fma_f32 v10, -v19, v32, 1.0
	v_fmac_f32_e32 v32, v10, v32
	v_mul_f32_e32 v10, v9, v32
	v_fma_f32 v11, -v19, v10, v9
	v_fmac_f32_e32 v10, v11, v32
	v_fma_f32 v9, -v19, v10, v9
	v_div_fmas_f32 v9, v9, v32, v10
	v_div_fixup_f32 v9, v9, v16, 1.0
	v_mul_f32_e32 v10, v14, v9
	v_mul_f32_e32 v10, v7, v10
	v_mul_f32_e32 v11, v15, v9
	v_cvt_pk_bf16_f32 v10, v10, v1
	v_mul_f32_e32 v11, v8, v11
	global_store_short v[12:13], v10, off
	v_cvt_pk_bf16_f32 v10, v11, v1
	global_store_short v[12:13], v10, off offset:64
	v_mul_f32_e32 v10, v17, v9
	v_mul_f32_e32 v10, v6, v10
	v_mul_f32_e32 v9, v18, v9
	v_cvt_pk_bf16_f32 v10, v10, v1
	v_mul_f32_e32 v9, v5, v9
	global_store_short v[12:13], v10, off offset:128
	v_cvt_pk_bf16_f32 v9, v9, v1
	ds_read2_b32 v[10:11], v4 offset0:8 offset1:40
	global_store_short v[12:13], v9, off offset:192
	s_waitcnt lgkmcnt(0)
	v_mul_f32_e32 v15, v84, v11
	v_mul_f32_e32 v14, v100, v11
	v_fma_f32 v15, v116, v10, -v15
	v_fma_f32 v14, v132, v10, -v14
	v_mul_f32_e32 v16, v15, v15
	v_mul_f32_e32 v17, v36, v11
	v_fmac_f32_e32 v16, v14, v14
	v_fma_f32 v17, v68, v10, -v17
	v_mul_f32_e32 v11, v20, v11
	v_fmac_f32_e32 v16, v17, v17
	v_fma_f32 v18, v52, v10, -v11
	v_fmac_f32_e32 v16, v18, v18
	s_nop 1
	v_add_f32_dpp v10, v16, v16 quad_perm:[1,0,3,2] row_mask:0xf bank_mask:0xf
	s_nop 1
	v_add_f32_dpp v10, v10, v10 quad_perm:[2,3,0,1] row_mask:0xf bank_mask:0xf
	s_nop 1
	v_add_f32_dpp v10, v10, v10 row_half_mirror row_mask:0xf bank_mask:0xf
	s_nop 1
	v_add_f32_dpp v10, v10, v10 row_mirror row_mask:0xf bank_mask:0xf
	ds_swizzle_b32 v11, v10 offset:swizzle(SWAP,16)
	s_waitcnt lgkmcnt(0)
	v_add_f32_e32 v10, v10, v11
	v_fmamk_f32 v10, v10, 0x3c000000, v230
	v_mul_f32_e32 v11, 0x4f800000, v10
	v_cmp_gt_f32_e32 vcc, s69, v10
	s_nop 1
	v_cndmask_b32_e32 v16, v10, v11, vcc
	v_sqrt_f32_e32 v19, v16
	v_mov_b32_e32 v11, v1
	v_or_b32_e32 v10, 0x4000, v0
	v_lshl_add_u64 v[10:11], v[2:3], 0, v[10:11]
	v_add_u32_e32 v20, -1, v19
	v_add_u32_e32 v32, 1, v19
	v_fma_f32 v33, -v20, v19, v16
	v_fma_f32 v34, -v32, v19, v16
	v_cmp_ge_f32_e64 s[8:9], 0, v33
	s_nop 1
	v_cndmask_b32_e64 v19, v19, v20, s[8:9]
	v_cmp_lt_f32_e64 s[8:9], 0, v34
	s_nop 1
	v_cndmask_b32_e64 v19, v19, v32, s[8:9]
	v_mul_f32_e32 v20, 0x37800000, v19
	v_cndmask_b32_e32 v19, v19, v20, vcc
	v_cmp_class_f32_e32 vcc, v16, v231
	s_nop 1
	v_cndmask_b32_e32 v16, v19, v16, vcc
	v_div_scale_f32 v19, s[0:1], v16, v16, 1.0
	v_rcp_f32_e32 v20, v19
	v_div_scale_f32 v9, vcc, 1.0, v16, 1.0
	v_fma_f32 v12, -v19, v20, 1.0
	v_fmac_f32_e32 v20, v12, v20
	v_mul_f32_e32 v12, v9, v20
	v_fma_f32 v13, -v19, v12, v9
	v_fmac_f32_e32 v12, v13, v20
	v_fma_f32 v9, -v19, v12, v9
	v_div_fmas_f32 v9, v9, v20, v12
	v_div_fixup_f32 v9, v9, v16, 1.0
	v_mul_f32_e32 v12, v14, v9
	v_mul_f32_e32 v12, v7, v12
	v_mul_f32_e32 v13, v15, v9
	v_cvt_pk_bf16_f32 v12, v12, v1
	v_mul_f32_e32 v13, v8, v13
	global_store_short v[10:11], v12, off
	v_cvt_pk_bf16_f32 v12, v13, v1
	global_store_short v[10:11], v12, off offset:64
	v_mul_f32_e32 v12, v17, v9
	v_mul_f32_e32 v12, v6, v12
	v_mul_f32_e32 v9, v18, v9
	v_cvt_pk_bf16_f32 v12, v12, v1
	v_mul_f32_e32 v9, v5, v9
	global_store_short v[10:11], v12, off offset:128
	v_cvt_pk_bf16_f32 v9, v9, v1
	ds_read2_b32 v[12:13], v4 offset0:9 offset1:41
	global_store_short v[10:11], v9, off offset:192
	s_waitcnt lgkmcnt(0)
	v_mul_f32_e32 v15, v85, v13
	v_mul_f32_e32 v14, v101, v13
	v_fma_f32 v15, v117, v12, -v15
	v_fma_f32 v14, v133, v12, -v14
	v_mul_f32_e32 v16, v15, v15
	v_mul_f32_e32 v17, v37, v13
	v_fmac_f32_e32 v16, v14, v14
	v_fma_f32 v17, v69, v12, -v17
	v_mul_f32_e32 v13, v21, v13
	v_fmac_f32_e32 v16, v17, v17
	v_fma_f32 v18, v53, v12, -v13
	v_fmac_f32_e32 v16, v18, v18
	s_nop 1
	v_add_f32_dpp v12, v16, v16 quad_perm:[1,0,3,2] row_mask:0xf bank_mask:0xf
	s_nop 1
	v_add_f32_dpp v12, v12, v12 quad_perm:[2,3,0,1] row_mask:0xf bank_mask:0xf
	s_nop 1
	v_add_f32_dpp v12, v12, v12 row_half_mirror row_mask:0xf bank_mask:0xf
	s_nop 1
	v_add_f32_dpp v12, v12, v12 row_mirror row_mask:0xf bank_mask:0xf
	ds_swizzle_b32 v13, v12 offset:swizzle(SWAP,16)
	s_waitcnt lgkmcnt(0)
	v_add_f32_e32 v12, v12, v13
	v_fmamk_f32 v12, v12, 0x3c000000, v230
	v_mul_f32_e32 v13, 0x4f800000, v12
	v_cmp_gt_f32_e32 vcc, s69, v12
	s_nop 1
	v_cndmask_b32_e32 v16, v12, v13, vcc
	v_sqrt_f32_e32 v19, v16
	v_mov_b32_e32 v13, v1
	v_or_b32_e32 v12, 0x4800, v0
	v_lshl_add_u64 v[12:13], v[2:3], 0, v[12:13]
	v_add_u32_e32 v20, -1, v19
	v_add_u32_e32 v21, 1, v19
	v_fma_f32 v32, -v20, v19, v16
	v_fma_f32 v33, -v21, v19, v16
	v_cmp_ge_f32_e64 s[8:9], 0, v32
	s_nop 1
	v_cndmask_b32_e64 v19, v19, v20, s[8:9]
	v_cmp_lt_f32_e64 s[8:9], 0, v33
	s_nop 1
	v_cndmask_b32_e64 v19, v19, v21, s[8:9]
	v_mul_f32_e32 v20, 0x37800000, v19
	v_cndmask_b32_e32 v19, v19, v20, vcc
	v_cmp_class_f32_e32 vcc, v16, v231
	s_nop 1
	v_cndmask_b32_e32 v16, v19, v16, vcc
	v_div_scale_f32 v19, s[0:1], v16, v16, 1.0
	v_rcp_f32_e32 v20, v19
	v_div_scale_f32 v9, vcc, 1.0, v16, 1.0
	v_fma_f32 v10, -v19, v20, 1.0
	v_fmac_f32_e32 v20, v10, v20
	v_mul_f32_e32 v10, v9, v20
	v_fma_f32 v11, -v19, v10, v9
	v_fmac_f32_e32 v10, v11, v20
	v_fma_f32 v9, -v19, v10, v9
	v_div_fmas_f32 v9, v9, v20, v10
	v_div_fixup_f32 v9, v9, v16, 1.0
	v_mul_f32_e32 v10, v14, v9
	v_mul_f32_e32 v10, v7, v10
	v_mul_f32_e32 v11, v15, v9
	v_cvt_pk_bf16_f32 v10, v10, v1
	v_mul_f32_e32 v11, v8, v11
	global_store_short v[12:13], v10, off
	v_cvt_pk_bf16_f32 v10, v11, v1
	global_store_short v[12:13], v10, off offset:64
	v_mul_f32_e32 v10, v17, v9
	v_mul_f32_e32 v10, v6, v10
	v_mul_f32_e32 v9, v18, v9
	v_cvt_pk_bf16_f32 v10, v10, v1
	v_mul_f32_e32 v9, v5, v9
	global_store_short v[12:13], v10, off offset:128
	v_cvt_pk_bf16_f32 v9, v9, v1
	ds_read2_b32 v[10:11], v4 offset0:10 offset1:42
	global_store_short v[12:13], v9, off offset:192
	s_waitcnt lgkmcnt(0)
	v_mul_f32_e32 v15, v86, v11
	v_mul_f32_e32 v14, v102, v11
	v_fma_f32 v15, v118, v10, -v15
	v_fma_f32 v14, v134, v10, -v14
	v_mul_f32_e32 v16, v15, v15
	v_mul_f32_e32 v17, v38, v11
	v_fmac_f32_e32 v16, v14, v14
	v_fma_f32 v17, v70, v10, -v17
	v_mul_f32_e32 v11, v22, v11
	v_fmac_f32_e32 v16, v17, v17
	v_fma_f32 v18, v54, v10, -v11
	v_fmac_f32_e32 v16, v18, v18
	s_nop 1
	v_add_f32_dpp v10, v16, v16 quad_perm:[1,0,3,2] row_mask:0xf bank_mask:0xf
	s_nop 1
	v_add_f32_dpp v10, v10, v10 quad_perm:[2,3,0,1] row_mask:0xf bank_mask:0xf
	s_nop 1
	v_add_f32_dpp v10, v10, v10 row_half_mirror row_mask:0xf bank_mask:0xf
	s_nop 1
	v_add_f32_dpp v10, v10, v10 row_mirror row_mask:0xf bank_mask:0xf
	ds_swizzle_b32 v11, v10 offset:swizzle(SWAP,16)
	s_waitcnt lgkmcnt(0)
	v_add_f32_e32 v10, v10, v11
	v_fmamk_f32 v10, v10, 0x3c000000, v230
	v_mul_f32_e32 v11, 0x4f800000, v10
	v_cmp_gt_f32_e32 vcc, s69, v10
	s_nop 1
	v_cndmask_b32_e32 v16, v10, v11, vcc
	v_sqrt_f32_e32 v19, v16
	v_mov_b32_e32 v11, v1
	v_or_b32_e32 v10, 0x5000, v0
	v_lshl_add_u64 v[10:11], v[2:3], 0, v[10:11]
	v_add_u32_e32 v20, -1, v19
	v_add_u32_e32 v21, 1, v19
	v_fma_f32 v22, -v20, v19, v16
	v_fma_f32 v32, -v21, v19, v16
	v_cmp_ge_f32_e64 s[8:9], 0, v22
	s_nop 1
	v_cndmask_b32_e64 v19, v19, v20, s[8:9]
	v_cmp_lt_f32_e64 s[8:9], 0, v32
	s_nop 1
	v_cndmask_b32_e64 v19, v19, v21, s[8:9]
	v_mul_f32_e32 v20, 0x37800000, v19
	v_cndmask_b32_e32 v19, v19, v20, vcc
	v_cmp_class_f32_e32 vcc, v16, v231
	s_nop 1
	v_cndmask_b32_e32 v16, v19, v16, vcc
	v_div_scale_f32 v19, s[0:1], v16, v16, 1.0
	v_rcp_f32_e32 v20, v19
	v_div_scale_f32 v9, vcc, 1.0, v16, 1.0
	v_fma_f32 v12, -v19, v20, 1.0
	v_fmac_f32_e32 v20, v12, v20
	v_mul_f32_e32 v12, v9, v20
	v_fma_f32 v13, -v19, v12, v9
	v_fmac_f32_e32 v12, v13, v20
	v_fma_f32 v9, -v19, v12, v9
	v_div_fmas_f32 v9, v9, v20, v12
	v_div_fixup_f32 v9, v9, v16, 1.0
	v_mul_f32_e32 v12, v14, v9
	v_mul_f32_e32 v12, v7, v12
	v_mul_f32_e32 v13, v15, v9
	v_cvt_pk_bf16_f32 v12, v12, v1
	v_mul_f32_e32 v13, v8, v13
	global_store_short v[10:11], v12, off
	v_cvt_pk_bf16_f32 v12, v13, v1
	global_store_short v[10:11], v12, off offset:64
	v_mul_f32_e32 v12, v17, v9
	v_mul_f32_e32 v12, v6, v12
	v_mul_f32_e32 v9, v18, v9
	v_cvt_pk_bf16_f32 v12, v12, v1
	v_mul_f32_e32 v9, v5, v9
	global_store_short v[10:11], v12, off offset:128
	v_cvt_pk_bf16_f32 v9, v9, v1
	ds_read2_b32 v[12:13], v4 offset0:11 offset1:43
	global_store_short v[10:11], v9, off offset:192
	s_waitcnt lgkmcnt(0)
	v_mul_f32_e32 v15, v87, v13
	v_mul_f32_e32 v14, v103, v13
	v_fma_f32 v15, v119, v12, -v15
	v_fma_f32 v14, v135, v12, -v14
	v_mul_f32_e32 v16, v15, v15
	v_mul_f32_e32 v17, v39, v13
	v_fmac_f32_e32 v16, v14, v14
	v_fma_f32 v17, v71, v12, -v17
	v_mul_f32_e32 v13, v23, v13
	v_fmac_f32_e32 v16, v17, v17
	v_fma_f32 v18, v55, v12, -v13
	v_fmac_f32_e32 v16, v18, v18
	s_nop 1
	v_add_f32_dpp v12, v16, v16 quad_perm:[1,0,3,2] row_mask:0xf bank_mask:0xf
	s_nop 1
	v_add_f32_dpp v12, v12, v12 quad_perm:[2,3,0,1] row_mask:0xf bank_mask:0xf
	s_nop 1
	v_add_f32_dpp v12, v12, v12 row_half_mirror row_mask:0xf bank_mask:0xf
	s_nop 1
	v_add_f32_dpp v12, v12, v12 row_mirror row_mask:0xf bank_mask:0xf
	ds_swizzle_b32 v13, v12 offset:swizzle(SWAP,16)
	s_waitcnt lgkmcnt(0)
	v_add_f32_e32 v12, v12, v13
	v_fmamk_f32 v12, v12, 0x3c000000, v230
	v_mul_f32_e32 v13, 0x4f800000, v12
	v_cmp_gt_f32_e32 vcc, s69, v12
	s_nop 1
	v_cndmask_b32_e32 v16, v12, v13, vcc
	v_sqrt_f32_e32 v19, v16
	v_mov_b32_e32 v13, v1
	v_or_b32_e32 v12, 0x5800, v0
	v_lshl_add_u64 v[12:13], v[2:3], 0, v[12:13]
	v_add_u32_e32 v20, -1, v19
	v_add_u32_e32 v21, 1, v19
	v_fma_f32 v22, -v20, v19, v16
	v_fma_f32 v23, -v21, v19, v16
	v_cmp_ge_f32_e64 s[8:9], 0, v22
	s_nop 1
	v_cndmask_b32_e64 v19, v19, v20, s[8:9]
	v_cmp_lt_f32_e64 s[8:9], 0, v23
	s_nop 1
	v_cndmask_b32_e64 v19, v19, v21, s[8:9]
	v_mul_f32_e32 v20, 0x37800000, v19
	v_cndmask_b32_e32 v19, v19, v20, vcc
	v_cmp_class_f32_e32 vcc, v16, v231
	s_nop 1
	v_cndmask_b32_e32 v16, v19, v16, vcc
	v_div_scale_f32 v19, s[0:1], v16, v16, 1.0
	v_rcp_f32_e32 v20, v19
	v_div_scale_f32 v9, vcc, 1.0, v16, 1.0
	v_fma_f32 v10, -v19, v20, 1.0
	v_fmac_f32_e32 v20, v10, v20
	v_mul_f32_e32 v10, v9, v20
	v_fma_f32 v11, -v19, v10, v9
	v_fmac_f32_e32 v10, v11, v20
	v_fma_f32 v9, -v19, v10, v9
	v_div_fmas_f32 v9, v9, v20, v10
	v_div_fixup_f32 v9, v9, v16, 1.0
	v_mul_f32_e32 v10, v14, v9
	v_mul_f32_e32 v10, v7, v10
	v_mul_f32_e32 v11, v15, v9
	v_cvt_pk_bf16_f32 v10, v10, v1
	v_mul_f32_e32 v11, v8, v11
	global_store_short v[12:13], v10, off
	v_cvt_pk_bf16_f32 v10, v11, v1
	global_store_short v[12:13], v10, off offset:64
	v_mul_f32_e32 v10, v17, v9
	v_mul_f32_e32 v10, v6, v10
	v_mul_f32_e32 v9, v18, v9
	v_cvt_pk_bf16_f32 v10, v10, v1
	v_mul_f32_e32 v9, v5, v9
	global_store_short v[12:13], v10, off offset:128
	v_cvt_pk_bf16_f32 v9, v9, v1
	ds_read2_b32 v[10:11], v4 offset0:16 offset1:48
	global_store_short v[12:13], v9, off offset:192
	s_waitcnt lgkmcnt(0)
	v_mul_f32_e32 v15, v88, v11
	v_mul_f32_e32 v14, v104, v11
	v_fma_f32 v15, v120, v10, -v15
	v_fma_f32 v14, v136, v10, -v14
	v_mul_f32_e32 v16, v15, v15
	v_mul_f32_e32 v17, v40, v11
	v_fmac_f32_e32 v16, v14, v14
	v_fma_f32 v17, v72, v10, -v17
	v_mul_f32_e32 v11, v24, v11
	v_fmac_f32_e32 v16, v17, v17
	v_fma_f32 v18, v56, v10, -v11
	v_fmac_f32_e32 v16, v18, v18
	s_nop 1
	v_add_f32_dpp v10, v16, v16 quad_perm:[1,0,3,2] row_mask:0xf bank_mask:0xf
	s_nop 1
	v_add_f32_dpp v10, v10, v10 quad_perm:[2,3,0,1] row_mask:0xf bank_mask:0xf
	s_nop 1
	v_add_f32_dpp v10, v10, v10 row_half_mirror row_mask:0xf bank_mask:0xf
	s_nop 1
	v_add_f32_dpp v10, v10, v10 row_mirror row_mask:0xf bank_mask:0xf
	ds_swizzle_b32 v11, v10 offset:swizzle(SWAP,16)
	s_waitcnt lgkmcnt(0)
	v_add_f32_e32 v10, v10, v11
	v_fmamk_f32 v10, v10, 0x3c000000, v230
	v_mul_f32_e32 v11, 0x4f800000, v10
	v_cmp_gt_f32_e32 vcc, s69, v10
	s_nop 1
	v_cndmask_b32_e32 v16, v10, v11, vcc
	v_sqrt_f32_e32 v19, v16
	v_mov_b32_e32 v11, v1
	v_or_b32_e32 v10, 0x8000, v0
	v_lshl_add_u64 v[10:11], v[2:3], 0, v[10:11]
	v_add_u32_e32 v20, -1, v19
	v_add_u32_e32 v21, 1, v19
	v_fma_f32 v22, -v20, v19, v16
	v_fma_f32 v23, -v21, v19, v16
	v_cmp_ge_f32_e64 s[8:9], 0, v22
	s_nop 1
	v_cndmask_b32_e64 v19, v19, v20, s[8:9]
	v_cmp_lt_f32_e64 s[8:9], 0, v23
	s_nop 1
	v_cndmask_b32_e64 v19, v19, v21, s[8:9]
	v_mul_f32_e32 v20, 0x37800000, v19
	v_cndmask_b32_e32 v19, v19, v20, vcc
	v_cmp_class_f32_e32 vcc, v16, v231
	s_nop 1
	v_cndmask_b32_e32 v16, v19, v16, vcc
	v_div_scale_f32 v19, s[0:1], v16, v16, 1.0
	v_rcp_f32_e32 v20, v19
	v_div_scale_f32 v9, vcc, 1.0, v16, 1.0
	v_fma_f32 v12, -v19, v20, 1.0
	v_fmac_f32_e32 v20, v12, v20
	v_mul_f32_e32 v12, v9, v20
	v_fma_f32 v13, -v19, v12, v9
	v_fmac_f32_e32 v12, v13, v20
	v_fma_f32 v9, -v19, v12, v9
	v_div_fmas_f32 v9, v9, v20, v12
	v_div_fixup_f32 v9, v9, v16, 1.0
	v_mul_f32_e32 v12, v14, v9
	v_mul_f32_e32 v12, v7, v12
	v_mul_f32_e32 v13, v15, v9
	v_cvt_pk_bf16_f32 v12, v12, v1
	v_mul_f32_e32 v13, v8, v13
	global_store_short v[10:11], v12, off
	v_cvt_pk_bf16_f32 v12, v13, v1
	global_store_short v[10:11], v12, off offset:64
	v_mul_f32_e32 v12, v17, v9
	v_mul_f32_e32 v12, v6, v12
	v_mul_f32_e32 v9, v18, v9
	v_cvt_pk_bf16_f32 v12, v12, v1
	v_mul_f32_e32 v9, v5, v9
	global_store_short v[10:11], v12, off offset:128
	v_cvt_pk_bf16_f32 v9, v9, v1
	ds_read2_b32 v[12:13], v4 offset0:17 offset1:49
	global_store_short v[10:11], v9, off offset:192
	s_waitcnt lgkmcnt(0)
	v_mul_f32_e32 v15, v89, v13
	v_mul_f32_e32 v14, v105, v13
	v_fma_f32 v15, v121, v12, -v15
	v_fma_f32 v14, v137, v12, -v14
	v_mul_f32_e32 v16, v15, v15
	v_mul_f32_e32 v17, v41, v13
	v_fmac_f32_e32 v16, v14, v14
	v_fma_f32 v17, v73, v12, -v17
	v_mul_f32_e32 v13, v25, v13
	v_fmac_f32_e32 v16, v17, v17
	v_fma_f32 v18, v57, v12, -v13
	v_fmac_f32_e32 v16, v18, v18
	s_nop 1
	v_add_f32_dpp v12, v16, v16 quad_perm:[1,0,3,2] row_mask:0xf bank_mask:0xf
	s_nop 1
	v_add_f32_dpp v12, v12, v12 quad_perm:[2,3,0,1] row_mask:0xf bank_mask:0xf
	s_nop 1
	v_add_f32_dpp v12, v12, v12 row_half_mirror row_mask:0xf bank_mask:0xf
	s_nop 1
	v_add_f32_dpp v12, v12, v12 row_mirror row_mask:0xf bank_mask:0xf
	ds_swizzle_b32 v13, v12 offset:swizzle(SWAP,16)
	s_waitcnt lgkmcnt(0)
	v_add_f32_e32 v12, v12, v13
	v_fmamk_f32 v12, v12, 0x3c000000, v230
	v_mul_f32_e32 v13, 0x4f800000, v12
	v_cmp_gt_f32_e32 vcc, s69, v12
	s_nop 1
	v_cndmask_b32_e32 v16, v12, v13, vcc
	v_sqrt_f32_e32 v19, v16
	v_mov_b32_e32 v13, v1
	v_or_b32_e32 v12, 0x8800, v0
	v_lshl_add_u64 v[12:13], v[2:3], 0, v[12:13]
	v_add_u32_e32 v20, -1, v19
	v_add_u32_e32 v21, 1, v19
	v_fma_f32 v22, -v20, v19, v16
	v_fma_f32 v23, -v21, v19, v16
	v_cmp_ge_f32_e64 s[8:9], 0, v22
	s_nop 1
	v_cndmask_b32_e64 v19, v19, v20, s[8:9]
	v_cmp_lt_f32_e64 s[8:9], 0, v23
	s_nop 1
	v_cndmask_b32_e64 v19, v19, v21, s[8:9]
	v_mul_f32_e32 v20, 0x37800000, v19
	v_cndmask_b32_e32 v19, v19, v20, vcc
	v_cmp_class_f32_e32 vcc, v16, v231
	s_nop 1
	v_cndmask_b32_e32 v16, v19, v16, vcc
	v_div_scale_f32 v19, s[0:1], v16, v16, 1.0
	v_rcp_f32_e32 v20, v19
	v_div_scale_f32 v9, vcc, 1.0, v16, 1.0
	v_fma_f32 v10, -v19, v20, 1.0
	v_fmac_f32_e32 v20, v10, v20
	v_mul_f32_e32 v10, v9, v20
	v_fma_f32 v11, -v19, v10, v9
	v_fmac_f32_e32 v10, v11, v20
	v_fma_f32 v9, -v19, v10, v9
	v_div_fmas_f32 v9, v9, v20, v10
	v_div_fixup_f32 v9, v9, v16, 1.0
	v_mul_f32_e32 v10, v14, v9
	v_mul_f32_e32 v10, v7, v10
	v_mul_f32_e32 v11, v15, v9
	v_cvt_pk_bf16_f32 v10, v10, v1
	v_mul_f32_e32 v11, v8, v11
	global_store_short v[12:13], v10, off
	v_cvt_pk_bf16_f32 v10, v11, v1
	global_store_short v[12:13], v10, off offset:64
	v_mul_f32_e32 v10, v17, v9
	v_mul_f32_e32 v10, v6, v10
	v_mul_f32_e32 v9, v18, v9
	v_cvt_pk_bf16_f32 v10, v10, v1
	v_mul_f32_e32 v9, v5, v9
	global_store_short v[12:13], v10, off offset:128
	v_cvt_pk_bf16_f32 v9, v9, v1
	ds_read2_b32 v[10:11], v4 offset0:18 offset1:50
	global_store_short v[12:13], v9, off offset:192
	s_waitcnt lgkmcnt(0)
	v_mul_f32_e32 v15, v90, v11
	v_mul_f32_e32 v14, v106, v11
	v_fma_f32 v15, v122, v10, -v15
	v_fma_f32 v14, v138, v10, -v14
	v_mul_f32_e32 v16, v15, v15
	v_mul_f32_e32 v17, v42, v11
	v_fmac_f32_e32 v16, v14, v14
	v_fma_f32 v17, v74, v10, -v17
	v_mul_f32_e32 v11, v26, v11
	v_fmac_f32_e32 v16, v17, v17
	v_fma_f32 v18, v58, v10, -v11
	v_fmac_f32_e32 v16, v18, v18
	s_nop 1
	v_add_f32_dpp v10, v16, v16 quad_perm:[1,0,3,2] row_mask:0xf bank_mask:0xf
	s_nop 1
	v_add_f32_dpp v10, v10, v10 quad_perm:[2,3,0,1] row_mask:0xf bank_mask:0xf
	s_nop 1
	v_add_f32_dpp v10, v10, v10 row_half_mirror row_mask:0xf bank_mask:0xf
	s_nop 1
	v_add_f32_dpp v10, v10, v10 row_mirror row_mask:0xf bank_mask:0xf
	ds_swizzle_b32 v11, v10 offset:swizzle(SWAP,16)
	s_waitcnt lgkmcnt(0)
	v_add_f32_e32 v10, v10, v11
	v_fmamk_f32 v10, v10, 0x3c000000, v230
	v_mul_f32_e32 v11, 0x4f800000, v10
	v_cmp_gt_f32_e32 vcc, s69, v10
	s_nop 1
	v_cndmask_b32_e32 v16, v10, v11, vcc
	v_sqrt_f32_e32 v19, v16
	v_mov_b32_e32 v11, v1
	v_or_b32_e32 v10, 0x9000, v0
	v_lshl_add_u64 v[10:11], v[2:3], 0, v[10:11]
	v_add_u32_e32 v20, -1, v19
	v_add_u32_e32 v21, 1, v19
	v_fma_f32 v22, -v20, v19, v16
	v_fma_f32 v23, -v21, v19, v16
	v_cmp_ge_f32_e64 s[8:9], 0, v22
	s_nop 1
	v_cndmask_b32_e64 v19, v19, v20, s[8:9]
	v_cmp_lt_f32_e64 s[8:9], 0, v23
	s_nop 1
	v_cndmask_b32_e64 v19, v19, v21, s[8:9]
	v_mul_f32_e32 v20, 0x37800000, v19
	v_cndmask_b32_e32 v19, v19, v20, vcc
	v_cmp_class_f32_e32 vcc, v16, v231
	s_nop 1
	v_cndmask_b32_e32 v16, v19, v16, vcc
	v_div_scale_f32 v19, s[0:1], v16, v16, 1.0
	v_rcp_f32_e32 v20, v19
	v_div_scale_f32 v9, vcc, 1.0, v16, 1.0
	v_fma_f32 v12, -v19, v20, 1.0
	v_fmac_f32_e32 v20, v12, v20
	v_mul_f32_e32 v12, v9, v20
	v_fma_f32 v13, -v19, v12, v9
	v_fmac_f32_e32 v12, v13, v20
	v_fma_f32 v9, -v19, v12, v9
	v_div_fmas_f32 v9, v9, v20, v12
	v_div_fixup_f32 v9, v9, v16, 1.0
	v_mul_f32_e32 v12, v14, v9
	v_mul_f32_e32 v12, v7, v12
	v_mul_f32_e32 v13, v15, v9
	v_cvt_pk_bf16_f32 v12, v12, v1
	v_mul_f32_e32 v13, v8, v13
	global_store_short v[10:11], v12, off
	v_cvt_pk_bf16_f32 v12, v13, v1
	global_store_short v[10:11], v12, off offset:64
	v_mul_f32_e32 v12, v17, v9
	v_mul_f32_e32 v12, v6, v12
	v_mul_f32_e32 v9, v18, v9
	v_cvt_pk_bf16_f32 v12, v12, v1
	v_mul_f32_e32 v9, v5, v9
	global_store_short v[10:11], v12, off offset:128
	v_cvt_pk_bf16_f32 v9, v9, v1
	ds_read2_b32 v[12:13], v4 offset0:19 offset1:51
	global_store_short v[10:11], v9, off offset:192
	s_waitcnt lgkmcnt(0)
	v_mul_f32_e32 v15, v91, v13
	v_mul_f32_e32 v14, v107, v13
	v_fma_f32 v15, v123, v12, -v15
	v_fma_f32 v14, v139, v12, -v14
	v_mul_f32_e32 v16, v15, v15
	v_mul_f32_e32 v17, v43, v13
	v_fmac_f32_e32 v16, v14, v14
	v_fma_f32 v17, v75, v12, -v17
	v_mul_f32_e32 v13, v27, v13
	v_fmac_f32_e32 v16, v17, v17
	v_fma_f32 v18, v59, v12, -v13
	v_fmac_f32_e32 v16, v18, v18
	s_nop 1
	v_add_f32_dpp v12, v16, v16 quad_perm:[1,0,3,2] row_mask:0xf bank_mask:0xf
	s_nop 1
	v_add_f32_dpp v12, v12, v12 quad_perm:[2,3,0,1] row_mask:0xf bank_mask:0xf
	s_nop 1
	v_add_f32_dpp v12, v12, v12 row_half_mirror row_mask:0xf bank_mask:0xf
	s_nop 1
	v_add_f32_dpp v12, v12, v12 row_mirror row_mask:0xf bank_mask:0xf
	ds_swizzle_b32 v13, v12 offset:swizzle(SWAP,16)
	s_waitcnt lgkmcnt(0)
	v_add_f32_e32 v12, v12, v13
	v_fmamk_f32 v12, v12, 0x3c000000, v230
	v_mul_f32_e32 v13, 0x4f800000, v12
	v_cmp_gt_f32_e32 vcc, s69, v12
	s_nop 1
	v_cndmask_b32_e32 v16, v12, v13, vcc
	v_sqrt_f32_e32 v19, v16
	v_mov_b32_e32 v13, v1
	v_or_b32_e32 v12, 0x9800, v0
	v_lshl_add_u64 v[12:13], v[2:3], 0, v[12:13]
	v_add_u32_e32 v20, -1, v19
	v_add_u32_e32 v21, 1, v19
	v_fma_f32 v22, -v20, v19, v16
	v_fma_f32 v23, -v21, v19, v16
	v_cmp_ge_f32_e64 s[8:9], 0, v22
	s_nop 1
	v_cndmask_b32_e64 v19, v19, v20, s[8:9]
	v_cmp_lt_f32_e64 s[8:9], 0, v23
	s_nop 1
	v_cndmask_b32_e64 v19, v19, v21, s[8:9]
	v_mul_f32_e32 v20, 0x37800000, v19
	v_cndmask_b32_e32 v19, v19, v20, vcc
	v_cmp_class_f32_e32 vcc, v16, v231
	s_nop 1
	v_cndmask_b32_e32 v16, v19, v16, vcc
	v_div_scale_f32 v19, s[0:1], v16, v16, 1.0
	v_rcp_f32_e32 v20, v19
	v_div_scale_f32 v9, vcc, 1.0, v16, 1.0
	v_fma_f32 v10, -v19, v20, 1.0
	v_fmac_f32_e32 v20, v10, v20
	v_mul_f32_e32 v10, v9, v20
	v_fma_f32 v11, -v19, v10, v9
	v_fmac_f32_e32 v10, v11, v20
	v_fma_f32 v9, -v19, v10, v9
	v_div_fmas_f32 v9, v9, v20, v10
	v_div_fixup_f32 v9, v9, v16, 1.0
	v_mul_f32_e32 v10, v14, v9
	v_mul_f32_e32 v10, v7, v10
	v_mul_f32_e32 v11, v15, v9
	v_cvt_pk_bf16_f32 v10, v10, v1
	v_mul_f32_e32 v11, v8, v11
	global_store_short v[12:13], v10, off
	v_cvt_pk_bf16_f32 v10, v11, v1
	global_store_short v[12:13], v10, off offset:64
	v_mul_f32_e32 v10, v17, v9
	v_mul_f32_e32 v10, v6, v10
	v_mul_f32_e32 v9, v18, v9
	v_cvt_pk_bf16_f32 v10, v10, v1
	v_mul_f32_e32 v9, v5, v9
	global_store_short v[12:13], v10, off offset:128
	v_cvt_pk_bf16_f32 v9, v9, v1
	ds_read2_b32 v[10:11], v4 offset0:24 offset1:56
	global_store_short v[12:13], v9, off offset:192
	s_waitcnt lgkmcnt(0)
	v_mul_f32_e32 v15, v92, v11
	v_mul_f32_e32 v14, v108, v11
	v_fma_f32 v15, v124, v10, -v15
	v_fma_f32 v14, v140, v10, -v14
	v_mul_f32_e32 v16, v15, v15
	v_mul_f32_e32 v17, v44, v11
	v_fmac_f32_e32 v16, v14, v14
	v_fma_f32 v17, v76, v10, -v17
	v_mul_f32_e32 v11, v28, v11
	v_fmac_f32_e32 v16, v17, v17
	v_fma_f32 v18, v60, v10, -v11
	v_fmac_f32_e32 v16, v18, v18
	s_nop 1
	v_add_f32_dpp v10, v16, v16 quad_perm:[1,0,3,2] row_mask:0xf bank_mask:0xf
	s_nop 1
	v_add_f32_dpp v10, v10, v10 quad_perm:[2,3,0,1] row_mask:0xf bank_mask:0xf
	s_nop 1
	v_add_f32_dpp v10, v10, v10 row_half_mirror row_mask:0xf bank_mask:0xf
	s_nop 1
	v_add_f32_dpp v10, v10, v10 row_mirror row_mask:0xf bank_mask:0xf
	ds_swizzle_b32 v11, v10 offset:swizzle(SWAP,16)
	s_waitcnt lgkmcnt(0)
	v_add_f32_e32 v10, v10, v11
	v_fmamk_f32 v10, v10, 0x3c000000, v230
	v_mul_f32_e32 v11, 0x4f800000, v10
	v_cmp_gt_f32_e32 vcc, s69, v10
	s_nop 1
	v_cndmask_b32_e32 v16, v10, v11, vcc
	v_sqrt_f32_e32 v19, v16
	v_mov_b32_e32 v11, v1
	v_or_b32_e32 v10, 0xc000, v0
	v_lshl_add_u64 v[10:11], v[2:3], 0, v[10:11]
	v_add_u32_e32 v20, -1, v19
	v_add_u32_e32 v21, 1, v19
	v_fma_f32 v22, -v20, v19, v16
	v_fma_f32 v23, -v21, v19, v16
	v_cmp_ge_f32_e64 s[8:9], 0, v22
	s_nop 1
	v_cndmask_b32_e64 v19, v19, v20, s[8:9]
	v_cmp_lt_f32_e64 s[8:9], 0, v23
	s_nop 1
	v_cndmask_b32_e64 v19, v19, v21, s[8:9]
	v_mul_f32_e32 v20, 0x37800000, v19
	v_cndmask_b32_e32 v19, v19, v20, vcc
	v_cmp_class_f32_e32 vcc, v16, v231
	s_nop 1
	v_cndmask_b32_e32 v16, v19, v16, vcc
	v_div_scale_f32 v19, s[0:1], v16, v16, 1.0
	v_rcp_f32_e32 v20, v19
	v_div_scale_f32 v9, vcc, 1.0, v16, 1.0
	v_fma_f32 v12, -v19, v20, 1.0
	v_fmac_f32_e32 v20, v12, v20
	v_mul_f32_e32 v12, v9, v20
	v_fma_f32 v13, -v19, v12, v9
	v_fmac_f32_e32 v12, v13, v20
	v_fma_f32 v9, -v19, v12, v9
	v_div_fmas_f32 v9, v9, v20, v12
	v_div_fixup_f32 v9, v9, v16, 1.0
	v_mul_f32_e32 v12, v14, v9
	v_mul_f32_e32 v12, v7, v12
	v_mul_f32_e32 v13, v15, v9
	v_cvt_pk_bf16_f32 v12, v12, v1
	v_mul_f32_e32 v13, v8, v13
	global_store_short v[10:11], v12, off
	v_cvt_pk_bf16_f32 v12, v13, v1
	global_store_short v[10:11], v12, off offset:64
	v_mul_f32_e32 v12, v17, v9
	v_mul_f32_e32 v12, v6, v12
	v_mul_f32_e32 v9, v18, v9
	v_cvt_pk_bf16_f32 v12, v12, v1
	v_mul_f32_e32 v9, v5, v9
	global_store_short v[10:11], v12, off offset:128
	v_cvt_pk_bf16_f32 v9, v9, v1
	ds_read2_b32 v[12:13], v4 offset0:25 offset1:57
	global_store_short v[10:11], v9, off offset:192
	s_waitcnt lgkmcnt(0)
	v_mul_f32_e32 v15, v93, v13
	v_mul_f32_e32 v14, v109, v13
	v_fma_f32 v15, v125, v12, -v15
	v_fma_f32 v14, v141, v12, -v14
	v_mul_f32_e32 v16, v15, v15
	v_mul_f32_e32 v17, v45, v13
	v_fmac_f32_e32 v16, v14, v14
	v_fma_f32 v17, v77, v12, -v17
	v_mul_f32_e32 v13, v29, v13
	v_fmac_f32_e32 v16, v17, v17
	v_fma_f32 v18, v61, v12, -v13
	v_fmac_f32_e32 v16, v18, v18
	s_nop 1
	v_add_f32_dpp v12, v16, v16 quad_perm:[1,0,3,2] row_mask:0xf bank_mask:0xf
	s_nop 1
	v_add_f32_dpp v12, v12, v12 quad_perm:[2,3,0,1] row_mask:0xf bank_mask:0xf
	s_nop 1
	v_add_f32_dpp v12, v12, v12 row_half_mirror row_mask:0xf bank_mask:0xf
	s_nop 1
	v_add_f32_dpp v12, v12, v12 row_mirror row_mask:0xf bank_mask:0xf
	ds_swizzle_b32 v13, v12 offset:swizzle(SWAP,16)
	s_waitcnt lgkmcnt(0)
	v_add_f32_e32 v12, v12, v13
	v_fmamk_f32 v12, v12, 0x3c000000, v230
	v_mul_f32_e32 v13, 0x4f800000, v12
	v_cmp_gt_f32_e32 vcc, s69, v12
	s_nop 1
	v_cndmask_b32_e32 v16, v12, v13, vcc
	v_sqrt_f32_e32 v19, v16
	v_mov_b32_e32 v13, v1
	v_or_b32_e32 v12, 0xc800, v0
	v_lshl_add_u64 v[12:13], v[2:3], 0, v[12:13]
	v_add_u32_e32 v20, -1, v19
	v_add_u32_e32 v21, 1, v19
	v_fma_f32 v22, -v20, v19, v16
	v_fma_f32 v23, -v21, v19, v16
	v_cmp_ge_f32_e64 s[8:9], 0, v22
	s_nop 1
	v_cndmask_b32_e64 v19, v19, v20, s[8:9]
	v_cmp_lt_f32_e64 s[8:9], 0, v23
	s_nop 1
	v_cndmask_b32_e64 v19, v19, v21, s[8:9]
	v_mul_f32_e32 v20, 0x37800000, v19
	v_cndmask_b32_e32 v19, v19, v20, vcc
	v_cmp_class_f32_e32 vcc, v16, v231
	s_nop 1
	v_cndmask_b32_e32 v16, v19, v16, vcc
	v_div_scale_f32 v19, s[0:1], v16, v16, 1.0
	v_rcp_f32_e32 v20, v19
	v_div_scale_f32 v9, vcc, 1.0, v16, 1.0
	v_fma_f32 v10, -v19, v20, 1.0
	v_fmac_f32_e32 v20, v10, v20
	v_mul_f32_e32 v10, v9, v20
	v_fma_f32 v11, -v19, v10, v9
	v_fmac_f32_e32 v10, v11, v20
	v_fma_f32 v9, -v19, v10, v9
	v_div_fmas_f32 v9, v9, v20, v10
	v_div_fixup_f32 v9, v9, v16, 1.0
	v_mul_f32_e32 v10, v14, v9
	v_mul_f32_e32 v10, v7, v10
	v_mul_f32_e32 v11, v15, v9
	v_cvt_pk_bf16_f32 v10, v10, v1
	v_mul_f32_e32 v11, v8, v11
	global_store_short v[12:13], v10, off
	v_cvt_pk_bf16_f32 v10, v11, v1
	global_store_short v[12:13], v10, off offset:64
	v_mul_f32_e32 v10, v17, v9
	v_mul_f32_e32 v10, v6, v10
	v_mul_f32_e32 v9, v18, v9
	v_cvt_pk_bf16_f32 v10, v10, v1
	v_mul_f32_e32 v9, v5, v9
	global_store_short v[12:13], v10, off offset:128
	v_cvt_pk_bf16_f32 v9, v9, v1
	ds_read2_b32 v[10:11], v4 offset0:26 offset1:58
	global_store_short v[12:13], v9, off offset:192
	s_waitcnt lgkmcnt(0)
	v_mul_f32_e32 v15, v94, v11
	v_mul_f32_e32 v14, v110, v11
	v_fma_f32 v15, v126, v10, -v15
	v_fma_f32 v14, v142, v10, -v14
	v_mul_f32_e32 v16, v15, v15
	v_mul_f32_e32 v17, v46, v11
	v_fmac_f32_e32 v16, v14, v14
	v_fma_f32 v17, v78, v10, -v17
	v_mul_f32_e32 v11, v30, v11
	v_fmac_f32_e32 v16, v17, v17
	v_fma_f32 v18, v62, v10, -v11
	v_fmac_f32_e32 v16, v18, v18
	s_nop 1
	v_add_f32_dpp v10, v16, v16 quad_perm:[1,0,3,2] row_mask:0xf bank_mask:0xf
	s_nop 1
	v_add_f32_dpp v10, v10, v10 quad_perm:[2,3,0,1] row_mask:0xf bank_mask:0xf
	s_nop 1
	v_add_f32_dpp v10, v10, v10 row_half_mirror row_mask:0xf bank_mask:0xf
	s_nop 1
	v_add_f32_dpp v10, v10, v10 row_mirror row_mask:0xf bank_mask:0xf
	ds_swizzle_b32 v11, v10 offset:swizzle(SWAP,16)
	s_waitcnt lgkmcnt(0)
	v_add_f32_e32 v10, v10, v11
	v_fmamk_f32 v10, v10, 0x3c000000, v230
	v_mul_f32_e32 v11, 0x4f800000, v10
	v_cmp_gt_f32_e32 vcc, s69, v10
	s_nop 1
	v_cndmask_b32_e32 v16, v10, v11, vcc
	v_sqrt_f32_e32 v19, v16
	v_mov_b32_e32 v11, v1
	v_or_b32_e32 v10, 0xd000, v0
	v_lshl_add_u64 v[10:11], v[2:3], 0, v[10:11]
	v_add_u32_e32 v20, -1, v19
	v_add_u32_e32 v21, 1, v19
	v_fma_f32 v22, -v20, v19, v16
	v_fma_f32 v23, -v21, v19, v16
	v_cmp_ge_f32_e64 s[8:9], 0, v22
	v_or_b32_e32 v0, 0xd800, v0
	v_lshl_add_u64 v[2:3], v[2:3], 0, v[0:1]
	v_cndmask_b32_e64 v19, v19, v20, s[8:9]
	v_cmp_lt_f32_e64 s[8:9], 0, v23
	s_nop 1
	v_cndmask_b32_e64 v19, v19, v21, s[8:9]
	v_mul_f32_e32 v20, 0x37800000, v19
	v_cndmask_b32_e32 v19, v19, v20, vcc
	v_cmp_class_f32_e32 vcc, v16, v231
	s_nop 1
	v_cndmask_b32_e32 v16, v19, v16, vcc
	v_div_scale_f32 v19, s[0:1], v16, v16, 1.0
	v_rcp_f32_e32 v20, v19
	v_div_scale_f32 v9, vcc, 1.0, v16, 1.0
	v_fma_f32 v12, -v19, v20, 1.0
	v_fmac_f32_e32 v20, v12, v20
	v_mul_f32_e32 v12, v9, v20
	v_fma_f32 v13, -v19, v12, v9
	v_fmac_f32_e32 v12, v13, v20
	v_fma_f32 v9, -v19, v12, v9
	v_div_fmas_f32 v9, v9, v20, v12
	v_div_fixup_f32 v9, v9, v16, 1.0
	v_mul_f32_e32 v12, v14, v9
	v_mul_f32_e32 v12, v7, v12
	v_mul_f32_e32 v13, v15, v9
	v_cvt_pk_bf16_f32 v12, v12, v1
	v_mul_f32_e32 v13, v8, v13
	global_store_short v[10:11], v12, off
	v_cvt_pk_bf16_f32 v12, v13, v1
	global_store_short v[10:11], v12, off offset:64
	v_mul_f32_e32 v12, v17, v9
	v_mul_f32_e32 v12, v6, v12
	v_mul_f32_e32 v9, v18, v9
	v_cvt_pk_bf16_f32 v12, v12, v1
	v_mul_f32_e32 v9, v5, v9
	global_store_short v[10:11], v12, off offset:128
	v_cvt_pk_bf16_f32 v9, v9, v1
	ds_read2_b32 v[12:13], v4 offset0:27 offset1:59
	global_store_short v[10:11], v9, off offset:192
	s_waitcnt lgkmcnt(0)
	v_mul_f32_e32 v14, v95, v13
	v_mul_f32_e32 v4, v111, v13
	v_fma_f32 v14, v127, v12, -v14
	v_fma_f32 v4, v143, v12, -v4
	v_mul_f32_e32 v15, v14, v14
	v_mul_f32_e32 v16, v47, v13
	v_fmac_f32_e32 v15, v4, v4
	v_fma_f32 v16, v79, v12, -v16
	v_mul_f32_e32 v13, v31, v13
	v_fmac_f32_e32 v15, v16, v16
	v_fma_f32 v12, v63, v12, -v13
	v_fmac_f32_e32 v15, v12, v12
	s_nop 1
	v_add_f32_dpp v13, v15, v15 quad_perm:[1,0,3,2] row_mask:0xf bank_mask:0xf
	s_nop 1
	v_add_f32_dpp v13, v13, v13 quad_perm:[2,3,0,1] row_mask:0xf bank_mask:0xf
	s_nop 1
	v_add_f32_dpp v13, v13, v13 row_half_mirror row_mask:0xf bank_mask:0xf
	s_nop 1
	v_add_f32_dpp v13, v13, v13 row_mirror row_mask:0xf bank_mask:0xf
	ds_swizzle_b32 v15, v13 offset:swizzle(SWAP,16)
	s_waitcnt lgkmcnt(0)
	v_add_f32_e32 v13, v13, v15
	v_fmamk_f32 v13, v13, 0x3c000000, v230
	v_mul_f32_e32 v15, 0x4f800000, v13
	v_cmp_gt_f32_e32 vcc, s69, v13
	s_nop 1
	v_cndmask_b32_e32 v13, v13, v15, vcc
	v_sqrt_f32_e32 v15, v13
	s_nop 0
	v_add_u32_e32 v0, -1, v15
	v_add_u32_e32 v17, 1, v15
	v_fma_f32 v18, -v0, v15, v13
	v_fma_f32 v19, -v17, v15, v13
	v_cmp_ge_f32_e64 s[8:9], 0, v18
	s_nop 1
	v_cndmask_b32_e64 v0, v15, v0, s[8:9]
	v_cmp_lt_f32_e64 s[8:9], 0, v19
	s_nop 1
	v_cndmask_b32_e64 v0, v0, v17, s[8:9]
	v_mul_f32_e32 v15, 0x37800000, v0
	v_cndmask_b32_e32 v0, v0, v15, vcc
	v_cmp_class_f32_e32 vcc, v13, v231
	s_nop 1
	v_cndmask_b32_e32 v0, v0, v13, vcc
	v_div_scale_f32 v13, s[0:1], v0, v0, 1.0
	v_rcp_f32_e32 v15, v13
	v_div_scale_f32 v9, vcc, 1.0, v0, 1.0
	v_readlane_b32 s0, v249, 54
	v_fma_f32 v10, -v13, v15, 1.0
	v_fmac_f32_e32 v15, v10, v15
	v_mul_f32_e32 v10, v9, v15
	v_fma_f32 v11, -v13, v10, v9
	v_fmac_f32_e32 v10, v11, v15
	v_fma_f32 v9, -v13, v10, v9
	v_div_fmas_f32 v9, v9, v15, v10
	v_div_fixup_f32 v0, v9, v0, 1.0
	v_mul_f32_e32 v4, v4, v0
	v_mul_f32_e32 v4, v7, v4
	v_mul_f32_e32 v9, v14, v0
	v_cvt_pk_bf16_f32 v4, v4, v1
	v_mul_f32_e32 v7, v8, v9
	global_store_short v[2:3], v4, off
	v_cvt_pk_bf16_f32 v4, v7, v1
	global_store_short v[2:3], v4, off offset:64
	v_mul_f32_e32 v4, v16, v0
	v_mul_f32_e32 v0, v12, v0
	s_add_i32 s78, s78, s0
	v_mul_f32_e32 v4, v6, v4
	v_mul_f32_e32 v0, v5, v0
	s_cmp_gt_i32 s78, 63
	v_cvt_pk_bf16_f32 v4, v4, v1
	global_store_short v[2:3], v4, off offset:128
	v_cvt_pk_bf16_f32 v0, v0, v1
	global_store_short v[2:3], v0, off offset:192
	s_cbranch_scc1 .LBB0_467

.LBB0_1240:
	s_or_b64 exec, exec, s[8:9]
	v_readlane_b32 s72, v249, 5
	s_waitcnt lgkmcnt(0)
	v_lshlrev_b32_e32 v3, 2, v0
	v_readlane_b32 s73, v249, 6
	v_ashrrev_i32_e32 v2, 1, v2
	v_and_b32_e32 v2, 0xffffffe0, v2
	s_lshl_b64 s[0:1], s[6:7], 25
	v_add_u32_e32 v2, s56, v2
	v_lshl_add_u32 v8, v9, 4, v8
	global_load_dword v4, v3, s[72:73]
	s_add_u32 s0, s3, s0
	ds_read2_b32 v[10:11], v8 offset1:32
	s_addc_u32 s1, s10, s1
	v_lshlrev_b32_e32 v0, 1, v0
	v_readlane_b32 s74, v249, 7
	v_readlane_b32 s75, v249, 8
	s_waitcnt lgkmcnt(0)
	v_mul_f32_e32 v14, v48, v11
	v_fma_f32 v14, v64, v10, -v14
	v_readlane_b32 s76, v249, 9
	v_readlane_b32 s77, v249, 10
	v_readlane_b32 s78, v249, 11
	v_readlane_b32 s79, v249, 12
	v_readlane_b32 s80, v249, 13
	v_readlane_b32 s81, v249, 14
	v_readlane_b32 s82, v249, 15
	v_readlane_b32 s83, v249, 16
	v_readlane_b32 s84, v249, 17
	v_readlane_b32 s85, v249, 18
	v_readlane_b32 s86, v249, 19
	v_readlane_b32 s87, v249, 20
	s_waitcnt vmcnt(0)
	v_mul_f32_e32 v7, 0x3f4ccccd, v4
	global_load_dword v6, v3, s[72:73] offset:128
	global_load_dword v5, v3, s[72:73] offset:256
	global_load_dword v4, v3, s[72:73] offset:384
	s_waitcnt vmcnt(0)
	v_mul_f32_e32 v6, 0x3f4ccccd, v6
	v_mul_f32_e32 v5, 0x3f4ccccd, v5
	v_mul_f32_e32 v4, 0x3f4ccccd, v4
	v_ashrrev_i32_e32 v3, 31, v2
	v_lshlrev_b64 v[2:3], 11, v[2:3]
	v_lshl_add_u64 v[2:3], s[0:1], 0, v[2:3]
	v_readlane_b32 s0, v249, 55
	v_readlane_b32 s1, v249, 56
	s_nop 1
	v_lshl_add_u64 v[2:3], s[0:1], 1, v[2:3]
	v_lshl_add_u64 v[2:3], v[2:3], 0, v[0:1]
	v_mul_f32_e32 v0, v96, v11
	v_fma_f32 v12, v128, v10, -v0
	v_mul_f32_e32 v0, v80, v11
	v_fma_f32 v13, v112, v10, -v0
	v_mul_f32_e32 v0, v13, v13
	v_fmac_f32_e32 v0, v12, v12
	v_mul_f32_e32 v11, v16, v11
	v_fmac_f32_e32 v0, v14, v14
	v_fma_f32 v15, v32, v10, -v11
	v_fmac_f32_e32 v0, v15, v15
	s_nop 1
	v_add_f32_dpp v0, v0, v0 quad_perm:[1,0,3,2] row_mask:0xf bank_mask:0xf
	s_nop 1
	v_add_f32_dpp v0, v0, v0 quad_perm:[2,3,0,1] row_mask:0xf bank_mask:0xf
	s_nop 1
	v_add_f32_dpp v0, v0, v0 row_half_mirror row_mask:0xf bank_mask:0xf
	s_nop 1
	v_add_f32_dpp v0, v0, v0 row_mirror row_mask:0xf bank_mask:0xf
	ds_swizzle_b32 v10, v0 offset:swizzle(SWAP,16)
	s_waitcnt lgkmcnt(0)
	v_add_f32_e32 v0, v0, v10
	v_fmamk_f32 v0, v0, 0x3c000000, v230
	v_cmp_gt_f32_e32 vcc, s59, v0
	v_mul_f32_e32 v10, 0x4f800000, v0
	s_nop 0
	v_cndmask_b32_e32 v0, v0, v10, vcc
	v_sqrt_f32_e32 v10, v0
	s_nop 0
	v_add_u32_e32 v11, -1, v10
	v_fma_f32 v16, -v11, v10, v0
	v_cmp_ge_f32_e64 s[8:9], 0, v16
	v_add_u32_e32 v16, 1, v10
	s_nop 0
	v_cndmask_b32_e64 v11, v10, v11, s[8:9]
	v_fma_f32 v10, -v16, v10, v0
	v_cmp_lt_f32_e64 s[8:9], 0, v10
	s_nop 1
	v_cndmask_b32_e64 v10, v11, v16, s[8:9]
	v_mul_f32_e32 v11, 0x37800000, v10
	v_cndmask_b32_e32 v10, v10, v11, vcc
	v_cmp_class_f32_e32 vcc, v0, v231
	s_nop 1
	v_cndmask_b32_e32 v0, v10, v0, vcc
	v_div_scale_f32 v10, s[0:1], v0, v0, 1.0
	v_rcp_f32_e32 v11, v10
	s_nop 0
	v_fma_f32 v16, -v10, v11, 1.0
	v_fmac_f32_e32 v11, v16, v11
	v_div_scale_f32 v16, vcc, 1.0, v0, 1.0
	v_mul_f32_e32 v32, v16, v11
	v_fma_f32 v48, -v10, v32, v16
	v_fmac_f32_e32 v32, v48, v11
	v_fma_f32 v10, -v10, v32, v16
	v_div_fmas_f32 v10, v10, v11, v32
	v_div_fixup_f32 v16, v10, v0, 1.0
	v_lshlrev_b32_e32 v0, 13, v9
	v_mul_f32_e32 v9, v12, v16
	v_mul_f32_e32 v9, v7, v9
	v_lshl_add_u64 v[10:11], v[2:3], 0, v[0:1]
	v_cvt_pk_bf16_f32 v9, v9, v1
	global_store_short v[10:11], v9, off
	v_mul_f32_e32 v9, v13, v16
	v_mul_f32_e32 v9, v6, v9
	v_cvt_pk_bf16_f32 v9, v9, v1
	global_store_short v[10:11], v9, off offset:64
	v_mul_f32_e32 v9, v14, v16
	v_mul_f32_e32 v9, v5, v9
	v_cvt_pk_bf16_f32 v9, v9, v1
	global_store_short v[10:11], v9, off offset:128
	v_mul_f32_e32 v9, v15, v16
	v_mul_f32_e32 v9, v4, v9
	v_cvt_pk_bf16_f32 v9, v9, v1
	global_store_short v[10:11], v9, off offset:192
	ds_read2_b32 v[10:11], v8 offset0:1 offset1:33
	s_waitcnt lgkmcnt(0)
	v_mul_f32_e32 v12, v81, v11
	v_mul_f32_e32 v9, v97, v11
	v_fma_f32 v12, v113, v10, -v12
	v_fma_f32 v9, v129, v10, -v9
	v_mul_f32_e32 v13, v12, v12
	v_mul_f32_e32 v14, v49, v11
	v_fmac_f32_e32 v13, v9, v9
	v_fma_f32 v14, v65, v10, -v14
	v_mul_f32_e32 v11, v17, v11
	v_fmac_f32_e32 v13, v14, v14
	v_fma_f32 v15, v33, v10, -v11
	v_fmac_f32_e32 v13, v15, v15
	s_nop 1
	v_add_f32_dpp v10, v13, v13 quad_perm:[1,0,3,2] row_mask:0xf bank_mask:0xf
	s_nop 1
	v_add_f32_dpp v10, v10, v10 quad_perm:[2,3,0,1] row_mask:0xf bank_mask:0xf
	s_nop 1
	v_add_f32_dpp v10, v10, v10 row_half_mirror row_mask:0xf bank_mask:0xf
	s_nop 1
	v_add_f32_dpp v10, v10, v10 row_mirror row_mask:0xf bank_mask:0xf
	ds_swizzle_b32 v11, v10 offset:swizzle(SWAP,16)
	s_waitcnt lgkmcnt(0)
	v_add_f32_e32 v10, v10, v11
	v_fmamk_f32 v10, v10, 0x3c000000, v230
	v_cmp_gt_f32_e32 vcc, s59, v10
	v_mul_f32_e32 v11, 0x4f800000, v10
	s_nop 0
	v_cndmask_b32_e32 v10, v10, v11, vcc
	v_sqrt_f32_e32 v11, v10
	s_nop 0
	v_add_u32_e32 v13, -1, v11
	v_fma_f32 v16, -v13, v11, v10
	v_cmp_ge_f32_e64 s[8:9], 0, v16
	v_add_u32_e32 v16, 1, v11
	s_nop 0
	v_cndmask_b32_e64 v13, v11, v13, s[8:9]
	v_fma_f32 v11, -v16, v11, v10
	v_cmp_lt_f32_e64 s[8:9], 0, v11
	s_nop 1
	v_cndmask_b32_e64 v11, v13, v16, s[8:9]
	v_mul_f32_e32 v13, 0x37800000, v11
	v_cndmask_b32_e32 v11, v11, v13, vcc
	v_cmp_class_f32_e32 vcc, v10, v231
	s_nop 1
	v_cndmask_b32_e32 v10, v11, v10, vcc
	v_div_scale_f32 v11, s[0:1], v10, v10, 1.0
	v_rcp_f32_e32 v13, v11
	s_nop 0
	v_fma_f32 v16, -v11, v13, 1.0
	v_fmac_f32_e32 v13, v16, v13
	v_div_scale_f32 v16, vcc, 1.0, v10, 1.0
	v_mul_f32_e32 v17, v16, v13
	v_fma_f32 v32, -v11, v17, v16
	v_fmac_f32_e32 v17, v32, v13
	v_fma_f32 v11, -v11, v17, v16
	v_div_fmas_f32 v11, v11, v13, v17
	v_div_fixup_f32 v13, v11, v10, 1.0
	v_mul_f32_e32 v9, v9, v13
	v_or_b32_e32 v10, 0x800, v0
	v_mov_b32_e32 v11, v1
	v_mul_f32_e32 v9, v7, v9
	v_lshl_add_u64 v[10:11], v[2:3], 0, v[10:11]
	v_cvt_pk_bf16_f32 v9, v9, v1
	global_store_short v[10:11], v9, off
	v_mul_f32_e32 v9, v12, v13
	v_mul_f32_e32 v9, v6, v9
	v_cvt_pk_bf16_f32 v9, v9, v1
	global_store_short v[10:11], v9, off offset:64
	v_mul_f32_e32 v9, v14, v13
	v_mul_f32_e32 v9, v5, v9
	v_cvt_pk_bf16_f32 v9, v9, v1
	global_store_short v[10:11], v9, off offset:128
	v_mul_f32_e32 v9, v15, v13
	v_mul_f32_e32 v9, v4, v9
	v_cvt_pk_bf16_f32 v9, v9, v1
	global_store_short v[10:11], v9, off offset:192
	ds_read2_b32 v[10:11], v8 offset0:2 offset1:34
	s_waitcnt lgkmcnt(0)
	v_mul_f32_e32 v12, v82, v11
	v_mul_f32_e32 v9, v98, v11
	v_fma_f32 v12, v114, v10, -v12
	v_fma_f32 v9, v130, v10, -v9
	v_mul_f32_e32 v13, v12, v12
	v_mul_f32_e32 v14, v50, v11
	v_fmac_f32_e32 v13, v9, v9
	v_fma_f32 v14, v66, v10, -v14
	v_mul_f32_e32 v11, v18, v11
	v_fmac_f32_e32 v13, v14, v14
	v_fma_f32 v15, v34, v10, -v11
	v_fmac_f32_e32 v13, v15, v15
	s_nop 1
	v_add_f32_dpp v10, v13, v13 quad_perm:[1,0,3,2] row_mask:0xf bank_mask:0xf
	s_nop 1
	v_add_f32_dpp v10, v10, v10 quad_perm:[2,3,0,1] row_mask:0xf bank_mask:0xf
	s_nop 1
	v_add_f32_dpp v10, v10, v10 row_half_mirror row_mask:0xf bank_mask:0xf
	s_nop 1
	v_add_f32_dpp v10, v10, v10 row_mirror row_mask:0xf bank_mask:0xf
	ds_swizzle_b32 v11, v10 offset:swizzle(SWAP,16)
	s_waitcnt lgkmcnt(0)
	v_add_f32_e32 v10, v10, v11
	v_fmamk_f32 v10, v10, 0x3c000000, v230
	v_cmp_gt_f32_e32 vcc, s59, v10
	v_mul_f32_e32 v11, 0x4f800000, v10
	s_nop 0
	v_cndmask_b32_e32 v10, v10, v11, vcc
	v_sqrt_f32_e32 v11, v10
	s_nop 0
	v_add_u32_e32 v13, -1, v11
	v_fma_f32 v16, -v13, v11, v10
	v_cmp_ge_f32_e64 s[8:9], 0, v16
	v_add_u32_e32 v16, 1, v11
	s_nop 0
	v_cndmask_b32_e64 v13, v11, v13, s[8:9]
	v_fma_f32 v11, -v16, v11, v10
	v_cmp_lt_f32_e64 s[8:9], 0, v11
	s_nop 1
	v_cndmask_b32_e64 v11, v13, v16, s[8:9]
	v_mul_f32_e32 v13, 0x37800000, v11
	v_cndmask_b32_e32 v11, v11, v13, vcc
	v_cmp_class_f32_e32 vcc, v10, v231
	s_nop 1
	v_cndmask_b32_e32 v10, v11, v10, vcc
	v_div_scale_f32 v11, s[0:1], v10, v10, 1.0
	v_rcp_f32_e32 v13, v11
	s_nop 0
	v_fma_f32 v16, -v11, v13, 1.0
	v_fmac_f32_e32 v13, v16, v13
	v_div_scale_f32 v16, vcc, 1.0, v10, 1.0
	v_mul_f32_e32 v17, v16, v13
	v_fma_f32 v18, -v11, v17, v16
	v_fmac_f32_e32 v17, v18, v13
	v_fma_f32 v11, -v11, v17, v16
	v_div_fmas_f32 v11, v11, v13, v17
	v_div_fixup_f32 v13, v11, v10, 1.0
	v_mul_f32_e32 v9, v9, v13
	v_or_b32_e32 v10, 0x1000, v0
	v_mov_b32_e32 v11, v1
	v_mul_f32_e32 v9, v7, v9
	v_lshl_add_u64 v[10:11], v[2:3], 0, v[10:11]
	v_cvt_pk_bf16_f32 v9, v9, v1
	global_store_short v[10:11], v9, off
	v_mul_f32_e32 v9, v12, v13
	v_mul_f32_e32 v9, v6, v9
	v_cvt_pk_bf16_f32 v9, v9, v1
	global_store_short v[10:11], v9, off offset:64
	v_mul_f32_e32 v9, v14, v13
	v_mul_f32_e32 v9, v5, v9
	v_cvt_pk_bf16_f32 v9, v9, v1
	global_store_short v[10:11], v9, off offset:128
	v_mul_f32_e32 v9, v15, v13
	v_mul_f32_e32 v9, v4, v9
	v_cvt_pk_bf16_f32 v9, v9, v1
	global_store_short v[10:11], v9, off offset:192
	ds_read2_b32 v[10:11], v8 offset0:3 offset1:35
	s_waitcnt lgkmcnt(0)
	v_mul_f32_e32 v12, v83, v11
	v_mul_f32_e32 v9, v99, v11
	v_fma_f32 v12, v115, v10, -v12
	v_fma_f32 v9, v131, v10, -v9
	v_mul_f32_e32 v13, v12, v12
	v_mul_f32_e32 v14, v51, v11
	v_fmac_f32_e32 v13, v9, v9
	v_fma_f32 v14, v67, v10, -v14
	v_mul_f32_e32 v11, v19, v11
	v_fmac_f32_e32 v13, v14, v14
	v_fma_f32 v15, v35, v10, -v11
	v_fmac_f32_e32 v13, v15, v15
	s_nop 1
	v_add_f32_dpp v10, v13, v13 quad_perm:[1,0,3,2] row_mask:0xf bank_mask:0xf
	s_nop 1
	v_add_f32_dpp v10, v10, v10 quad_perm:[2,3,0,1] row_mask:0xf bank_mask:0xf
	s_nop 1
	v_add_f32_dpp v10, v10, v10 row_half_mirror row_mask:0xf bank_mask:0xf
	s_nop 1
	v_add_f32_dpp v10, v10, v10 row_mirror row_mask:0xf bank_mask:0xf
	ds_swizzle_b32 v11, v10 offset:swizzle(SWAP,16)
	s_waitcnt lgkmcnt(0)
	v_add_f32_e32 v10, v10, v11
	v_fmamk_f32 v10, v10, 0x3c000000, v230
	v_cmp_gt_f32_e32 vcc, s59, v10
	v_mul_f32_e32 v11, 0x4f800000, v10
	s_nop 0
	v_cndmask_b32_e32 v10, v10, v11, vcc
	v_sqrt_f32_e32 v11, v10
	s_nop 0
	v_add_u32_e32 v13, -1, v11
	v_fma_f32 v16, -v13, v11, v10
	v_cmp_ge_f32_e64 s[8:9], 0, v16
	v_add_u32_e32 v16, 1, v11
	s_nop 0
	v_cndmask_b32_e64 v13, v11, v13, s[8:9]
	v_fma_f32 v11, -v16, v11, v10
	v_cmp_lt_f32_e64 s[8:9], 0, v11
	s_nop 1
	v_cndmask_b32_e64 v11, v13, v16, s[8:9]
	v_mul_f32_e32 v13, 0x37800000, v11
	v_cndmask_b32_e32 v11, v11, v13, vcc
	v_cmp_class_f32_e32 vcc, v10, v231
	s_nop 1
	v_cndmask_b32_e32 v10, v11, v10, vcc
	v_div_scale_f32 v11, s[0:1], v10, v10, 1.0
	v_rcp_f32_e32 v13, v11
	s_nop 0
	v_fma_f32 v16, -v11, v13, 1.0
	v_fmac_f32_e32 v13, v16, v13
	v_div_scale_f32 v16, vcc, 1.0, v10, 1.0
	v_mul_f32_e32 v17, v16, v13
	v_fma_f32 v18, -v11, v17, v16
	v_fmac_f32_e32 v17, v18, v13
	v_fma_f32 v11, -v11, v17, v16
	v_div_fmas_f32 v11, v11, v13, v17
	v_div_fixup_f32 v13, v11, v10, 1.0
	v_mul_f32_e32 v9, v9, v13
	v_or_b32_e32 v10, 0x1800, v0
	v_mov_b32_e32 v11, v1
	v_mul_f32_e32 v9, v7, v9
	v_lshl_add_u64 v[10:11], v[2:3], 0, v[10:11]
	v_cvt_pk_bf16_f32 v9, v9, v1
	global_store_short v[10:11], v9, off
	v_mul_f32_e32 v9, v12, v13
	v_mul_f32_e32 v9, v6, v9
	v_cvt_pk_bf16_f32 v9, v9, v1
	global_store_short v[10:11], v9, off offset:64
	v_mul_f32_e32 v9, v14, v13
	v_mul_f32_e32 v9, v5, v9
	v_cvt_pk_bf16_f32 v9, v9, v1
	global_store_short v[10:11], v9, off offset:128
	v_mul_f32_e32 v9, v15, v13
	v_mul_f32_e32 v9, v4, v9
	v_cvt_pk_bf16_f32 v9, v9, v1
	global_store_short v[10:11], v9, off offset:192
	ds_read2_b32 v[10:11], v8 offset0:8 offset1:40
	s_waitcnt lgkmcnt(0)
	v_mul_f32_e32 v12, v84, v11
	v_mul_f32_e32 v9, v100, v11
	v_fma_f32 v12, v116, v10, -v12
	v_fma_f32 v9, v132, v10, -v9
	v_mul_f32_e32 v13, v12, v12
	v_mul_f32_e32 v14, v52, v11
	v_fmac_f32_e32 v13, v9, v9
	v_fma_f32 v14, v68, v10, -v14
	v_mul_f32_e32 v11, v20, v11
	v_fmac_f32_e32 v13, v14, v14
	v_fma_f32 v15, v36, v10, -v11
	v_fmac_f32_e32 v13, v15, v15
	s_nop 1
	v_add_f32_dpp v10, v13, v13 quad_perm:[1,0,3,2] row_mask:0xf bank_mask:0xf
	s_nop 1
	v_add_f32_dpp v10, v10, v10 quad_perm:[2,3,0,1] row_mask:0xf bank_mask:0xf
	s_nop 1
	v_add_f32_dpp v10, v10, v10 row_half_mirror row_mask:0xf bank_mask:0xf
	s_nop 1
	v_add_f32_dpp v10, v10, v10 row_mirror row_mask:0xf bank_mask:0xf
	ds_swizzle_b32 v11, v10 offset:swizzle(SWAP,16)
	s_waitcnt lgkmcnt(0)
	v_add_f32_e32 v10, v10, v11
	v_fmamk_f32 v10, v10, 0x3c000000, v230
	v_cmp_gt_f32_e32 vcc, s59, v10
	v_mul_f32_e32 v11, 0x4f800000, v10
	s_nop 0
	v_cndmask_b32_e32 v10, v10, v11, vcc
	v_sqrt_f32_e32 v11, v10
	s_nop 0
	v_add_u32_e32 v13, -1, v11
	v_fma_f32 v16, -v13, v11, v10
	v_cmp_ge_f32_e64 s[8:9], 0, v16
	v_add_u32_e32 v16, 1, v11
	s_nop 0
	v_cndmask_b32_e64 v13, v11, v13, s[8:9]
	v_fma_f32 v11, -v16, v11, v10
	v_cmp_lt_f32_e64 s[8:9], 0, v11
	s_nop 1
	v_cndmask_b32_e64 v11, v13, v16, s[8:9]
	v_mul_f32_e32 v13, 0x37800000, v11
	v_cndmask_b32_e32 v11, v11, v13, vcc
	v_cmp_class_f32_e32 vcc, v10, v231
	s_nop 1
	v_cndmask_b32_e32 v10, v11, v10, vcc
	v_div_scale_f32 v11, s[0:1], v10, v10, 1.0
	v_rcp_f32_e32 v13, v11
	s_nop 0
	v_fma_f32 v16, -v11, v13, 1.0
	v_fmac_f32_e32 v13, v16, v13
	v_div_scale_f32 v16, vcc, 1.0, v10, 1.0
	v_mul_f32_e32 v17, v16, v13
	v_fma_f32 v18, -v11, v17, v16
	v_fmac_f32_e32 v17, v18, v13
	v_fma_f32 v11, -v11, v17, v16
	v_div_fmas_f32 v11, v11, v13, v17
	v_div_fixup_f32 v13, v11, v10, 1.0
	v_mul_f32_e32 v9, v9, v13
	v_or_b32_e32 v10, 0x4000, v0
	v_mov_b32_e32 v11, v1
	v_mul_f32_e32 v9, v7, v9
	v_lshl_add_u64 v[10:11], v[2:3], 0, v[10:11]
	v_cvt_pk_bf16_f32 v9, v9, v1
	global_store_short v[10:11], v9, off
	v_mul_f32_e32 v9, v12, v13
	v_mul_f32_e32 v9, v6, v9
	v_cvt_pk_bf16_f32 v9, v9, v1
	global_store_short v[10:11], v9, off offset:64
	v_mul_f32_e32 v9, v14, v13
	v_mul_f32_e32 v9, v5, v9
	v_cvt_pk_bf16_f32 v9, v9, v1
	global_store_short v[10:11], v9, off offset:128
	v_mul_f32_e32 v9, v15, v13
	v_mul_f32_e32 v9, v4, v9
	v_cvt_pk_bf16_f32 v9, v9, v1
	global_store_short v[10:11], v9, off offset:192
	ds_read2_b32 v[10:11], v8 offset0:9 offset1:41
	s_waitcnt lgkmcnt(0)
	v_mul_f32_e32 v12, v85, v11
	v_mul_f32_e32 v9, v101, v11
	v_fma_f32 v12, v117, v10, -v12
	v_fma_f32 v9, v133, v10, -v9
	v_mul_f32_e32 v13, v12, v12
	v_mul_f32_e32 v14, v53, v11
	v_fmac_f32_e32 v13, v9, v9
	v_fma_f32 v14, v69, v10, -v14
	v_mul_f32_e32 v11, v21, v11
	v_fmac_f32_e32 v13, v14, v14
	v_fma_f32 v15, v37, v10, -v11
	v_fmac_f32_e32 v13, v15, v15
	s_nop 1
	v_add_f32_dpp v10, v13, v13 quad_perm:[1,0,3,2] row_mask:0xf bank_mask:0xf
	s_nop 1
	v_add_f32_dpp v10, v10, v10 quad_perm:[2,3,0,1] row_mask:0xf bank_mask:0xf
	s_nop 1
	v_add_f32_dpp v10, v10, v10 row_half_mirror row_mask:0xf bank_mask:0xf
	s_nop 1
	v_add_f32_dpp v10, v10, v10 row_mirror row_mask:0xf bank_mask:0xf
	ds_swizzle_b32 v11, v10 offset:swizzle(SWAP,16)
	s_waitcnt lgkmcnt(0)
	v_add_f32_e32 v10, v10, v11
	v_fmamk_f32 v10, v10, 0x3c000000, v230
	v_cmp_gt_f32_e32 vcc, s59, v10
	v_mul_f32_e32 v11, 0x4f800000, v10
	s_nop 0
	v_cndmask_b32_e32 v10, v10, v11, vcc
	v_sqrt_f32_e32 v11, v10
	s_nop 0
	v_add_u32_e32 v13, -1, v11
	v_fma_f32 v16, -v13, v11, v10
	v_cmp_ge_f32_e64 s[8:9], 0, v16
	v_add_u32_e32 v16, 1, v11
	s_nop 0
	v_cndmask_b32_e64 v13, v11, v13, s[8:9]
	v_fma_f32 v11, -v16, v11, v10
	v_cmp_lt_f32_e64 s[8:9], 0, v11
	s_nop 1
	v_cndmask_b32_e64 v11, v13, v16, s[8:9]
	v_mul_f32_e32 v13, 0x37800000, v11
	v_cndmask_b32_e32 v11, v11, v13, vcc
	v_cmp_class_f32_e32 vcc, v10, v231
	s_nop 1
	v_cndmask_b32_e32 v10, v11, v10, vcc
	v_div_scale_f32 v11, s[0:1], v10, v10, 1.0
	v_rcp_f32_e32 v13, v11
	s_nop 0
	v_fma_f32 v16, -v11, v13, 1.0
	v_fmac_f32_e32 v13, v16, v13
	v_div_scale_f32 v16, vcc, 1.0, v10, 1.0
	v_mul_f32_e32 v17, v16, v13
	v_fma_f32 v18, -v11, v17, v16
	v_fmac_f32_e32 v17, v18, v13
	v_fma_f32 v11, -v11, v17, v16
	v_div_fmas_f32 v11, v11, v13, v17
	v_div_fixup_f32 v13, v11, v10, 1.0
	v_mul_f32_e32 v9, v9, v13
	v_or_b32_e32 v10, 0x4800, v0
	v_mov_b32_e32 v11, v1
	v_mul_f32_e32 v9, v7, v9
	v_lshl_add_u64 v[10:11], v[2:3], 0, v[10:11]
	v_cvt_pk_bf16_f32 v9, v9, v1
	global_store_short v[10:11], v9, off
	v_mul_f32_e32 v9, v12, v13
	v_mul_f32_e32 v9, v6, v9
	v_cvt_pk_bf16_f32 v9, v9, v1
	global_store_short v[10:11], v9, off offset:64
	v_mul_f32_e32 v9, v14, v13
	v_mul_f32_e32 v9, v5, v9
	v_cvt_pk_bf16_f32 v9, v9, v1
	global_store_short v[10:11], v9, off offset:128
	v_mul_f32_e32 v9, v15, v13
	v_mul_f32_e32 v9, v4, v9
	v_cvt_pk_bf16_f32 v9, v9, v1
	global_store_short v[10:11], v9, off offset:192
	ds_read2_b32 v[10:11], v8 offset0:10 offset1:42
	s_waitcnt lgkmcnt(0)
	v_mul_f32_e32 v12, v86, v11
	v_mul_f32_e32 v9, v102, v11
	v_fma_f32 v12, v118, v10, -v12
	v_fma_f32 v9, v134, v10, -v9
	v_mul_f32_e32 v13, v12, v12
	v_mul_f32_e32 v14, v54, v11
	v_fmac_f32_e32 v13, v9, v9
	v_fma_f32 v14, v70, v10, -v14
	v_mul_f32_e32 v11, v22, v11
	v_fmac_f32_e32 v13, v14, v14
	v_fma_f32 v15, v38, v10, -v11
	v_fmac_f32_e32 v13, v15, v15
	s_nop 1
	v_add_f32_dpp v10, v13, v13 quad_perm:[1,0,3,2] row_mask:0xf bank_mask:0xf
	s_nop 1
	v_add_f32_dpp v10, v10, v10 quad_perm:[2,3,0,1] row_mask:0xf bank_mask:0xf
	s_nop 1
	v_add_f32_dpp v10, v10, v10 row_half_mirror row_mask:0xf bank_mask:0xf
	s_nop 1
	v_add_f32_dpp v10, v10, v10 row_mirror row_mask:0xf bank_mask:0xf
	ds_swizzle_b32 v11, v10 offset:swizzle(SWAP,16)
	s_waitcnt lgkmcnt(0)
	v_add_f32_e32 v10, v10, v11
	v_fmamk_f32 v10, v10, 0x3c000000, v230
	v_cmp_gt_f32_e32 vcc, s59, v10
	v_mul_f32_e32 v11, 0x4f800000, v10
	s_nop 0
	v_cndmask_b32_e32 v10, v10, v11, vcc
	v_sqrt_f32_e32 v11, v10
	s_nop 0
	v_add_u32_e32 v13, -1, v11
	v_fma_f32 v16, -v13, v11, v10
	v_cmp_ge_f32_e64 s[8:9], 0, v16
	v_add_u32_e32 v16, 1, v11
	s_nop 0
	v_cndmask_b32_e64 v13, v11, v13, s[8:9]
	v_fma_f32 v11, -v16, v11, v10
	v_cmp_lt_f32_e64 s[8:9], 0, v11
	s_nop 1
	v_cndmask_b32_e64 v11, v13, v16, s[8:9]
	v_mul_f32_e32 v13, 0x37800000, v11
	v_cndmask_b32_e32 v11, v11, v13, vcc
	v_cmp_class_f32_e32 vcc, v10, v231
	s_nop 1
	v_cndmask_b32_e32 v10, v11, v10, vcc
	v_div_scale_f32 v11, s[0:1], v10, v10, 1.0
	v_rcp_f32_e32 v13, v11
	s_nop 0
	v_fma_f32 v16, -v11, v13, 1.0
	v_fmac_f32_e32 v13, v16, v13
	v_div_scale_f32 v16, vcc, 1.0, v10, 1.0
	v_mul_f32_e32 v17, v16, v13
	v_fma_f32 v18, -v11, v17, v16
	v_fmac_f32_e32 v17, v18, v13
	v_fma_f32 v11, -v11, v17, v16
	v_div_fmas_f32 v11, v11, v13, v17
	v_div_fixup_f32 v13, v11, v10, 1.0
	v_mul_f32_e32 v9, v9, v13
	v_or_b32_e32 v10, 0x5000, v0
	v_mov_b32_e32 v11, v1
	v_mul_f32_e32 v9, v7, v9
	v_lshl_add_u64 v[10:11], v[2:3], 0, v[10:11]
	v_cvt_pk_bf16_f32 v9, v9, v1
	global_store_short v[10:11], v9, off
	v_mul_f32_e32 v9, v12, v13
	v_mul_f32_e32 v9, v6, v9
	v_cvt_pk_bf16_f32 v9, v9, v1
	global_store_short v[10:11], v9, off offset:64
	v_mul_f32_e32 v9, v14, v13
	v_mul_f32_e32 v9, v5, v9
	v_cvt_pk_bf16_f32 v9, v9, v1
	global_store_short v[10:11], v9, off offset:128
	v_mul_f32_e32 v9, v15, v13
	v_mul_f32_e32 v9, v4, v9
	v_cvt_pk_bf16_f32 v9, v9, v1
	global_store_short v[10:11], v9, off offset:192
	ds_read2_b32 v[10:11], v8 offset0:11 offset1:43
	s_waitcnt lgkmcnt(0)
	v_mul_f32_e32 v12, v87, v11
	v_mul_f32_e32 v9, v103, v11
	v_fma_f32 v12, v119, v10, -v12
	v_fma_f32 v9, v135, v10, -v9
	v_mul_f32_e32 v13, v12, v12
	v_mul_f32_e32 v14, v55, v11
	v_fmac_f32_e32 v13, v9, v9
	v_fma_f32 v14, v71, v10, -v14
	v_mul_f32_e32 v11, v23, v11
	v_fmac_f32_e32 v13, v14, v14
	v_fma_f32 v15, v39, v10, -v11
	v_fmac_f32_e32 v13, v15, v15
	s_nop 1
	v_add_f32_dpp v10, v13, v13 quad_perm:[1,0,3,2] row_mask:0xf bank_mask:0xf
	s_nop 1
	v_add_f32_dpp v10, v10, v10 quad_perm:[2,3,0,1] row_mask:0xf bank_mask:0xf
	s_nop 1
	v_add_f32_dpp v10, v10, v10 row_half_mirror row_mask:0xf bank_mask:0xf
	s_nop 1
	v_add_f32_dpp v10, v10, v10 row_mirror row_mask:0xf bank_mask:0xf
	ds_swizzle_b32 v11, v10 offset:swizzle(SWAP,16)
	s_waitcnt lgkmcnt(0)
	v_add_f32_e32 v10, v10, v11
	v_fmamk_f32 v10, v10, 0x3c000000, v230
	v_cmp_gt_f32_e32 vcc, s59, v10
	v_mul_f32_e32 v11, 0x4f800000, v10
	s_nop 0
	v_cndmask_b32_e32 v10, v10, v11, vcc
	v_sqrt_f32_e32 v11, v10
	s_nop 0
	v_add_u32_e32 v13, -1, v11
	v_fma_f32 v16, -v13, v11, v10
	v_cmp_ge_f32_e64 s[8:9], 0, v16
	v_add_u32_e32 v16, 1, v11
	s_nop 0
	v_cndmask_b32_e64 v13, v11, v13, s[8:9]
	v_fma_f32 v11, -v16, v11, v10
	v_cmp_lt_f32_e64 s[8:9], 0, v11
	s_nop 1
	v_cndmask_b32_e64 v11, v13, v16, s[8:9]
	v_mul_f32_e32 v13, 0x37800000, v11
	v_cndmask_b32_e32 v11, v11, v13, vcc
	v_cmp_class_f32_e32 vcc, v10, v231
	s_nop 1
	v_cndmask_b32_e32 v10, v11, v10, vcc
	v_div_scale_f32 v11, s[0:1], v10, v10, 1.0
	v_rcp_f32_e32 v13, v11
	s_nop 0
	v_fma_f32 v16, -v11, v13, 1.0
	v_fmac_f32_e32 v13, v16, v13
	v_div_scale_f32 v16, vcc, 1.0, v10, 1.0
	v_mul_f32_e32 v17, v16, v13
	v_fma_f32 v18, -v11, v17, v16
	v_fmac_f32_e32 v17, v18, v13
	v_fma_f32 v11, -v11, v17, v16
	v_div_fmas_f32 v11, v11, v13, v17
	v_div_fixup_f32 v13, v11, v10, 1.0
	v_mul_f32_e32 v9, v9, v13
	v_or_b32_e32 v10, 0x5800, v0
	v_mov_b32_e32 v11, v1
	v_mul_f32_e32 v9, v7, v9
	v_lshl_add_u64 v[10:11], v[2:3], 0, v[10:11]
	v_cvt_pk_bf16_f32 v9, v9, v1
	global_store_short v[10:11], v9, off
	v_mul_f32_e32 v9, v12, v13
	v_mul_f32_e32 v9, v6, v9
	v_cvt_pk_bf16_f32 v9, v9, v1
	global_store_short v[10:11], v9, off offset:64
	v_mul_f32_e32 v9, v14, v13
	v_mul_f32_e32 v9, v5, v9
	v_cvt_pk_bf16_f32 v9, v9, v1
	global_store_short v[10:11], v9, off offset:128
	v_mul_f32_e32 v9, v15, v13
	v_mul_f32_e32 v9, v4, v9
	v_cvt_pk_bf16_f32 v9, v9, v1
	global_store_short v[10:11], v9, off offset:192
	ds_read2_b32 v[10:11], v8 offset0:16 offset1:48
	s_waitcnt lgkmcnt(0)
	v_mul_f32_e32 v12, v88, v11
	v_mul_f32_e32 v9, v104, v11
	v_fma_f32 v12, v120, v10, -v12
	v_fma_f32 v9, v136, v10, -v9
	v_mul_f32_e32 v13, v12, v12
	v_mul_f32_e32 v14, v56, v11
	v_fmac_f32_e32 v13, v9, v9
	v_fma_f32 v14, v72, v10, -v14
	v_mul_f32_e32 v11, v24, v11
	v_fmac_f32_e32 v13, v14, v14
	v_fma_f32 v15, v40, v10, -v11
	v_fmac_f32_e32 v13, v15, v15
	s_nop 1
	v_add_f32_dpp v10, v13, v13 quad_perm:[1,0,3,2] row_mask:0xf bank_mask:0xf
	s_nop 1
	v_add_f32_dpp v10, v10, v10 quad_perm:[2,3,0,1] row_mask:0xf bank_mask:0xf
	s_nop 1
	v_add_f32_dpp v10, v10, v10 row_half_mirror row_mask:0xf bank_mask:0xf
	s_nop 1
	v_add_f32_dpp v10, v10, v10 row_mirror row_mask:0xf bank_mask:0xf
	ds_swizzle_b32 v11, v10 offset:swizzle(SWAP,16)
	s_waitcnt lgkmcnt(0)
	v_add_f32_e32 v10, v10, v11
	v_fmamk_f32 v10, v10, 0x3c000000, v230
	v_cmp_gt_f32_e32 vcc, s59, v10
	v_mul_f32_e32 v11, 0x4f800000, v10
	s_nop 0
	v_cndmask_b32_e32 v10, v10, v11, vcc
	v_sqrt_f32_e32 v11, v10
	s_nop 0
	v_add_u32_e32 v13, -1, v11
	v_fma_f32 v16, -v13, v11, v10
	v_cmp_ge_f32_e64 s[8:9], 0, v16
	v_add_u32_e32 v16, 1, v11
	s_nop 0
	v_cndmask_b32_e64 v13, v11, v13, s[8:9]
	v_fma_f32 v11, -v16, v11, v10
	v_cmp_lt_f32_e64 s[8:9], 0, v11
	s_nop 1
	v_cndmask_b32_e64 v11, v13, v16, s[8:9]
	v_mul_f32_e32 v13, 0x37800000, v11
	v_cndmask_b32_e32 v11, v11, v13, vcc
	v_cmp_class_f32_e32 vcc, v10, v231
	s_nop 1
	v_cndmask_b32_e32 v10, v11, v10, vcc
	v_div_scale_f32 v11, s[0:1], v10, v10, 1.0
	v_rcp_f32_e32 v13, v11
	s_nop 0
	v_fma_f32 v16, -v11, v13, 1.0
	v_fmac_f32_e32 v13, v16, v13
	v_div_scale_f32 v16, vcc, 1.0, v10, 1.0
	v_mul_f32_e32 v17, v16, v13
	v_fma_f32 v18, -v11, v17, v16
	v_fmac_f32_e32 v17, v18, v13
	v_fma_f32 v11, -v11, v17, v16
	v_div_fmas_f32 v11, v11, v13, v17
	v_div_fixup_f32 v13, v11, v10, 1.0
	v_mul_f32_e32 v9, v9, v13
	v_or_b32_e32 v10, 0x8000, v0
	v_mov_b32_e32 v11, v1
	v_mul_f32_e32 v9, v7, v9
	v_lshl_add_u64 v[10:11], v[2:3], 0, v[10:11]
	v_cvt_pk_bf16_f32 v9, v9, v1
	global_store_short v[10:11], v9, off
	v_mul_f32_e32 v9, v12, v13
	v_mul_f32_e32 v9, v6, v9
	v_cvt_pk_bf16_f32 v9, v9, v1
	global_store_short v[10:11], v9, off offset:64
	v_mul_f32_e32 v9, v14, v13
	v_mul_f32_e32 v9, v5, v9
	v_cvt_pk_bf16_f32 v9, v9, v1
	global_store_short v[10:11], v9, off offset:128
	v_mul_f32_e32 v9, v15, v13
	v_mul_f32_e32 v9, v4, v9
	v_cvt_pk_bf16_f32 v9, v9, v1
	global_store_short v[10:11], v9, off offset:192
	ds_read2_b32 v[10:11], v8 offset0:17 offset1:49
	s_waitcnt lgkmcnt(0)
	v_mul_f32_e32 v12, v89, v11
	v_mul_f32_e32 v9, v105, v11
	v_fma_f32 v12, v121, v10, -v12
	v_fma_f32 v9, v137, v10, -v9
	v_mul_f32_e32 v13, v12, v12
	v_mul_f32_e32 v14, v57, v11
	v_fmac_f32_e32 v13, v9, v9
	v_fma_f32 v14, v73, v10, -v14
	v_mul_f32_e32 v11, v25, v11
	v_fmac_f32_e32 v13, v14, v14
	v_fma_f32 v15, v41, v10, -v11
	v_fmac_f32_e32 v13, v15, v15
	s_nop 1
	v_add_f32_dpp v10, v13, v13 quad_perm:[1,0,3,2] row_mask:0xf bank_mask:0xf
	s_nop 1
	v_add_f32_dpp v10, v10, v10 quad_perm:[2,3,0,1] row_mask:0xf bank_mask:0xf
	s_nop 1
	v_add_f32_dpp v10, v10, v10 row_half_mirror row_mask:0xf bank_mask:0xf
	s_nop 1
	v_add_f32_dpp v10, v10, v10 row_mirror row_mask:0xf bank_mask:0xf
	ds_swizzle_b32 v11, v10 offset:swizzle(SWAP,16)
	s_waitcnt lgkmcnt(0)
	v_add_f32_e32 v10, v10, v11
	v_fmamk_f32 v10, v10, 0x3c000000, v230
	v_cmp_gt_f32_e32 vcc, s59, v10
	v_mul_f32_e32 v11, 0x4f800000, v10
	s_nop 0
	v_cndmask_b32_e32 v10, v10, v11, vcc
	v_sqrt_f32_e32 v11, v10
	s_nop 0
	v_add_u32_e32 v13, -1, v11
	v_fma_f32 v16, -v13, v11, v10
	v_cmp_ge_f32_e64 s[8:9], 0, v16
	v_add_u32_e32 v16, 1, v11
	s_nop 0
	v_cndmask_b32_e64 v13, v11, v13, s[8:9]
	v_fma_f32 v11, -v16, v11, v10
	v_cmp_lt_f32_e64 s[8:9], 0, v11
	s_nop 1
	v_cndmask_b32_e64 v11, v13, v16, s[8:9]
	v_mul_f32_e32 v13, 0x37800000, v11
	v_cndmask_b32_e32 v11, v11, v13, vcc
	v_cmp_class_f32_e32 vcc, v10, v231
	s_nop 1
	v_cndmask_b32_e32 v10, v11, v10, vcc
	v_div_scale_f32 v11, s[0:1], v10, v10, 1.0
	v_rcp_f32_e32 v13, v11
	s_nop 0
	v_fma_f32 v16, -v11, v13, 1.0
	v_fmac_f32_e32 v13, v16, v13
	v_div_scale_f32 v16, vcc, 1.0, v10, 1.0
	v_mul_f32_e32 v17, v16, v13
	v_fma_f32 v18, -v11, v17, v16
	v_fmac_f32_e32 v17, v18, v13
	v_fma_f32 v11, -v11, v17, v16
	v_div_fmas_f32 v11, v11, v13, v17
	v_div_fixup_f32 v13, v11, v10, 1.0
	v_mul_f32_e32 v9, v9, v13
	v_or_b32_e32 v10, 0x8800, v0
	v_mov_b32_e32 v11, v1
	v_mul_f32_e32 v9, v7, v9
	v_lshl_add_u64 v[10:11], v[2:3], 0, v[10:11]
	v_cvt_pk_bf16_f32 v9, v9, v1
	global_store_short v[10:11], v9, off
	v_mul_f32_e32 v9, v12, v13
	v_mul_f32_e32 v9, v6, v9
	v_cvt_pk_bf16_f32 v9, v9, v1
	global_store_short v[10:11], v9, off offset:64
	v_mul_f32_e32 v9, v14, v13
	v_mul_f32_e32 v9, v5, v9
	v_cvt_pk_bf16_f32 v9, v9, v1
	global_store_short v[10:11], v9, off offset:128
	v_mul_f32_e32 v9, v15, v13
	v_mul_f32_e32 v9, v4, v9
	v_cvt_pk_bf16_f32 v9, v9, v1
	global_store_short v[10:11], v9, off offset:192
	ds_read2_b32 v[10:11], v8 offset0:18 offset1:50
	s_waitcnt lgkmcnt(0)
	v_mul_f32_e32 v12, v90, v11
	v_mul_f32_e32 v9, v106, v11
	v_fma_f32 v12, v122, v10, -v12
	v_fma_f32 v9, v138, v10, -v9
	v_mul_f32_e32 v13, v12, v12
	v_mul_f32_e32 v14, v58, v11
	v_fmac_f32_e32 v13, v9, v9
	v_fma_f32 v14, v74, v10, -v14
	v_mul_f32_e32 v11, v26, v11
	v_fmac_f32_e32 v13, v14, v14
	v_fma_f32 v15, v42, v10, -v11
	v_fmac_f32_e32 v13, v15, v15
	s_nop 1
	v_add_f32_dpp v10, v13, v13 quad_perm:[1,0,3,2] row_mask:0xf bank_mask:0xf
	s_nop 1
	v_add_f32_dpp v10, v10, v10 quad_perm:[2,3,0,1] row_mask:0xf bank_mask:0xf
	s_nop 1
	v_add_f32_dpp v10, v10, v10 row_half_mirror row_mask:0xf bank_mask:0xf
	s_nop 1
	v_add_f32_dpp v10, v10, v10 row_mirror row_mask:0xf bank_mask:0xf
	ds_swizzle_b32 v11, v10 offset:swizzle(SWAP,16)
	s_waitcnt lgkmcnt(0)
	v_add_f32_e32 v10, v10, v11
	v_fmamk_f32 v10, v10, 0x3c000000, v230
	v_cmp_gt_f32_e32 vcc, s59, v10
	v_mul_f32_e32 v11, 0x4f800000, v10
	s_nop 0
	v_cndmask_b32_e32 v10, v10, v11, vcc
	v_sqrt_f32_e32 v11, v10
	s_nop 0
	v_add_u32_e32 v13, -1, v11
	v_fma_f32 v16, -v13, v11, v10
	v_cmp_ge_f32_e64 s[8:9], 0, v16
	v_add_u32_e32 v16, 1, v11
	s_nop 0
	v_cndmask_b32_e64 v13, v11, v13, s[8:9]
	v_fma_f32 v11, -v16, v11, v10
	v_cmp_lt_f32_e64 s[8:9], 0, v11
	s_nop 1
	v_cndmask_b32_e64 v11, v13, v16, s[8:9]
	v_mul_f32_e32 v13, 0x37800000, v11
	v_cndmask_b32_e32 v11, v11, v13, vcc
	v_cmp_class_f32_e32 vcc, v10, v231
	s_nop 1
	v_cndmask_b32_e32 v10, v11, v10, vcc
	v_div_scale_f32 v11, s[0:1], v10, v10, 1.0
	v_rcp_f32_e32 v13, v11
	s_nop 0
	v_fma_f32 v16, -v11, v13, 1.0
	v_fmac_f32_e32 v13, v16, v13
	v_div_scale_f32 v16, vcc, 1.0, v10, 1.0
	v_mul_f32_e32 v17, v16, v13
	v_fma_f32 v18, -v11, v17, v16
	v_fmac_f32_e32 v17, v18, v13
	v_fma_f32 v11, -v11, v17, v16
	v_div_fmas_f32 v11, v11, v13, v17
	v_div_fixup_f32 v13, v11, v10, 1.0
	v_mul_f32_e32 v9, v9, v13
	v_or_b32_e32 v10, 0x9000, v0
	v_mov_b32_e32 v11, v1
	v_mul_f32_e32 v9, v7, v9
	v_lshl_add_u64 v[10:11], v[2:3], 0, v[10:11]
	v_cvt_pk_bf16_f32 v9, v9, v1
	global_store_short v[10:11], v9, off
	v_mul_f32_e32 v9, v12, v13
	v_mul_f32_e32 v9, v6, v9
	v_cvt_pk_bf16_f32 v9, v9, v1
	global_store_short v[10:11], v9, off offset:64
	v_mul_f32_e32 v9, v14, v13
	v_mul_f32_e32 v9, v5, v9
	v_cvt_pk_bf16_f32 v9, v9, v1
	global_store_short v[10:11], v9, off offset:128
	v_mul_f32_e32 v9, v15, v13
	v_mul_f32_e32 v9, v4, v9
	v_cvt_pk_bf16_f32 v9, v9, v1
	global_store_short v[10:11], v9, off offset:192
	ds_read2_b32 v[10:11], v8 offset0:19 offset1:51
	s_waitcnt lgkmcnt(0)
	v_mul_f32_e32 v12, v91, v11
	v_mul_f32_e32 v9, v107, v11
	v_fma_f32 v12, v123, v10, -v12
	v_fma_f32 v9, v139, v10, -v9
	v_mul_f32_e32 v13, v12, v12
	v_mul_f32_e32 v14, v59, v11
	v_fmac_f32_e32 v13, v9, v9
	v_fma_f32 v14, v75, v10, -v14
	v_mul_f32_e32 v11, v27, v11
	v_fmac_f32_e32 v13, v14, v14
	v_fma_f32 v15, v43, v10, -v11
	v_fmac_f32_e32 v13, v15, v15
	s_nop 1
	v_add_f32_dpp v10, v13, v13 quad_perm:[1,0,3,2] row_mask:0xf bank_mask:0xf
	s_nop 1
	v_add_f32_dpp v10, v10, v10 quad_perm:[2,3,0,1] row_mask:0xf bank_mask:0xf
	s_nop 1
	v_add_f32_dpp v10, v10, v10 row_half_mirror row_mask:0xf bank_mask:0xf
	s_nop 1
	v_add_f32_dpp v10, v10, v10 row_mirror row_mask:0xf bank_mask:0xf
	ds_swizzle_b32 v11, v10 offset:swizzle(SWAP,16)
	s_waitcnt lgkmcnt(0)
	v_add_f32_e32 v10, v10, v11
	v_fmamk_f32 v10, v10, 0x3c000000, v230
	v_cmp_gt_f32_e32 vcc, s59, v10
	v_mul_f32_e32 v11, 0x4f800000, v10
	s_nop 0
	v_cndmask_b32_e32 v10, v10, v11, vcc
	v_sqrt_f32_e32 v11, v10
	s_nop 0
	v_add_u32_e32 v13, -1, v11
	v_fma_f32 v16, -v13, v11, v10
	v_cmp_ge_f32_e64 s[8:9], 0, v16
	v_add_u32_e32 v16, 1, v11
	s_nop 0
	v_cndmask_b32_e64 v13, v11, v13, s[8:9]
	v_fma_f32 v11, -v16, v11, v10
	v_cmp_lt_f32_e64 s[8:9], 0, v11
	s_nop 1
	v_cndmask_b32_e64 v11, v13, v16, s[8:9]
	v_mul_f32_e32 v13, 0x37800000, v11
	v_cndmask_b32_e32 v11, v11, v13, vcc
	v_cmp_class_f32_e32 vcc, v10, v231
	s_nop 1
	v_cndmask_b32_e32 v10, v11, v10, vcc
	v_div_scale_f32 v11, s[0:1], v10, v10, 1.0
	v_rcp_f32_e32 v13, v11
	s_nop 0
	v_fma_f32 v16, -v11, v13, 1.0
	v_fmac_f32_e32 v13, v16, v13
	v_div_scale_f32 v16, vcc, 1.0, v10, 1.0
	v_mul_f32_e32 v17, v16, v13
	v_fma_f32 v18, -v11, v17, v16
	v_fmac_f32_e32 v17, v18, v13
	v_fma_f32 v11, -v11, v17, v16
	v_div_fmas_f32 v11, v11, v13, v17
	v_div_fixup_f32 v13, v11, v10, 1.0
	v_mul_f32_e32 v9, v9, v13
	v_or_b32_e32 v10, 0x9800, v0
	v_mov_b32_e32 v11, v1
	v_mul_f32_e32 v9, v7, v9
	v_lshl_add_u64 v[10:11], v[2:3], 0, v[10:11]
	v_cvt_pk_bf16_f32 v9, v9, v1
	global_store_short v[10:11], v9, off
	v_mul_f32_e32 v9, v12, v13
	v_mul_f32_e32 v9, v6, v9
	v_cvt_pk_bf16_f32 v9, v9, v1
	global_store_short v[10:11], v9, off offset:64
	v_mul_f32_e32 v9, v14, v13
	v_mul_f32_e32 v9, v5, v9
	v_cvt_pk_bf16_f32 v9, v9, v1
	global_store_short v[10:11], v9, off offset:128
	v_mul_f32_e32 v9, v15, v13
	v_mul_f32_e32 v9, v4, v9
	v_cvt_pk_bf16_f32 v9, v9, v1
	global_store_short v[10:11], v9, off offset:192
	ds_read2_b32 v[10:11], v8 offset0:24 offset1:56
	s_waitcnt lgkmcnt(0)
	v_mul_f32_e32 v12, v92, v11
	v_mul_f32_e32 v9, v108, v11
	v_fma_f32 v12, v124, v10, -v12
	v_fma_f32 v9, v140, v10, -v9
	v_mul_f32_e32 v13, v12, v12
	v_mul_f32_e32 v14, v60, v11
	v_fmac_f32_e32 v13, v9, v9
	v_fma_f32 v14, v76, v10, -v14
	v_mul_f32_e32 v11, v28, v11
	v_fmac_f32_e32 v13, v14, v14
	v_fma_f32 v15, v44, v10, -v11
	v_fmac_f32_e32 v13, v15, v15
	s_nop 1
	v_add_f32_dpp v10, v13, v13 quad_perm:[1,0,3,2] row_mask:0xf bank_mask:0xf
	s_nop 1
	v_add_f32_dpp v10, v10, v10 quad_perm:[2,3,0,1] row_mask:0xf bank_mask:0xf
	s_nop 1
	v_add_f32_dpp v10, v10, v10 row_half_mirror row_mask:0xf bank_mask:0xf
	s_nop 1
	v_add_f32_dpp v10, v10, v10 row_mirror row_mask:0xf bank_mask:0xf
	ds_swizzle_b32 v11, v10 offset:swizzle(SWAP,16)
	s_waitcnt lgkmcnt(0)
	v_add_f32_e32 v10, v10, v11
	v_fmamk_f32 v10, v10, 0x3c000000, v230
	v_cmp_gt_f32_e32 vcc, s59, v10
	v_mul_f32_e32 v11, 0x4f800000, v10
	s_nop 0
	v_cndmask_b32_e32 v10, v10, v11, vcc
	v_sqrt_f32_e32 v11, v10
	s_nop 0
	v_add_u32_e32 v13, -1, v11
	v_fma_f32 v16, -v13, v11, v10
	v_cmp_ge_f32_e64 s[8:9], 0, v16
	v_add_u32_e32 v16, 1, v11
	s_nop 0
	v_cndmask_b32_e64 v13, v11, v13, s[8:9]
	v_fma_f32 v11, -v16, v11, v10
	v_cmp_lt_f32_e64 s[8:9], 0, v11
	s_nop 1
	v_cndmask_b32_e64 v11, v13, v16, s[8:9]
	v_mul_f32_e32 v13, 0x37800000, v11
	v_cndmask_b32_e32 v11, v11, v13, vcc
	v_cmp_class_f32_e32 vcc, v10, v231
	s_nop 1
	v_cndmask_b32_e32 v10, v11, v10, vcc
	v_div_scale_f32 v11, s[0:1], v10, v10, 1.0
	v_rcp_f32_e32 v13, v11
	s_nop 0
	v_fma_f32 v16, -v11, v13, 1.0
	v_fmac_f32_e32 v13, v16, v13
	v_div_scale_f32 v16, vcc, 1.0, v10, 1.0
	v_mul_f32_e32 v17, v16, v13
	v_fma_f32 v18, -v11, v17, v16
	v_fmac_f32_e32 v17, v18, v13
	v_fma_f32 v11, -v11, v17, v16
	v_div_fmas_f32 v11, v11, v13, v17
	v_div_fixup_f32 v13, v11, v10, 1.0
	v_mul_f32_e32 v9, v9, v13
	v_or_b32_e32 v10, 0xc000, v0
	v_mov_b32_e32 v11, v1
	v_mul_f32_e32 v9, v7, v9
	v_lshl_add_u64 v[10:11], v[2:3], 0, v[10:11]
	v_cvt_pk_bf16_f32 v9, v9, v1
	global_store_short v[10:11], v9, off
	v_mul_f32_e32 v9, v12, v13
	v_mul_f32_e32 v9, v6, v9
	v_cvt_pk_bf16_f32 v9, v9, v1
	global_store_short v[10:11], v9, off offset:64
	v_mul_f32_e32 v9, v14, v13
	v_mul_f32_e32 v9, v5, v9
	v_cvt_pk_bf16_f32 v9, v9, v1
	global_store_short v[10:11], v9, off offset:128
	v_mul_f32_e32 v9, v15, v13
	v_mul_f32_e32 v9, v4, v9
	v_cvt_pk_bf16_f32 v9, v9, v1
	global_store_short v[10:11], v9, off offset:192
	ds_read2_b32 v[10:11], v8 offset0:25 offset1:57
	s_waitcnt lgkmcnt(0)
	v_mul_f32_e32 v12, v93, v11
	v_mul_f32_e32 v9, v109, v11
	v_fma_f32 v12, v125, v10, -v12
	v_fma_f32 v9, v141, v10, -v9
	v_mul_f32_e32 v13, v12, v12
	v_mul_f32_e32 v14, v61, v11
	v_fmac_f32_e32 v13, v9, v9
	v_fma_f32 v14, v77, v10, -v14
	v_mul_f32_e32 v11, v29, v11
	v_fmac_f32_e32 v13, v14, v14
	v_fma_f32 v15, v45, v10, -v11
	v_fmac_f32_e32 v13, v15, v15
	s_nop 1
	v_add_f32_dpp v10, v13, v13 quad_perm:[1,0,3,2] row_mask:0xf bank_mask:0xf
	s_nop 1
	v_add_f32_dpp v10, v10, v10 quad_perm:[2,3,0,1] row_mask:0xf bank_mask:0xf
	s_nop 1
	v_add_f32_dpp v10, v10, v10 row_half_mirror row_mask:0xf bank_mask:0xf
	s_nop 1
	v_add_f32_dpp v10, v10, v10 row_mirror row_mask:0xf bank_mask:0xf
	ds_swizzle_b32 v11, v10 offset:swizzle(SWAP,16)
	s_waitcnt lgkmcnt(0)
	v_add_f32_e32 v10, v10, v11
	v_fmamk_f32 v10, v10, 0x3c000000, v230
	v_cmp_gt_f32_e32 vcc, s59, v10
	v_mul_f32_e32 v11, 0x4f800000, v10
	s_nop 0
	v_cndmask_b32_e32 v10, v10, v11, vcc
	v_sqrt_f32_e32 v11, v10
	s_nop 0
	v_add_u32_e32 v13, -1, v11
	v_fma_f32 v16, -v13, v11, v10
	v_cmp_ge_f32_e64 s[8:9], 0, v16
	v_add_u32_e32 v16, 1, v11
	s_nop 0
	v_cndmask_b32_e64 v13, v11, v13, s[8:9]
	v_fma_f32 v11, -v16, v11, v10
	v_cmp_lt_f32_e64 s[8:9], 0, v11
	s_nop 1
	v_cndmask_b32_e64 v11, v13, v16, s[8:9]
	v_mul_f32_e32 v13, 0x37800000, v11
	v_cndmask_b32_e32 v11, v11, v13, vcc
	v_cmp_class_f32_e32 vcc, v10, v231
	s_nop 1
	v_cndmask_b32_e32 v10, v11, v10, vcc
	v_div_scale_f32 v11, s[0:1], v10, v10, 1.0
	v_rcp_f32_e32 v13, v11
	s_nop 0
	v_fma_f32 v16, -v11, v13, 1.0
	v_fmac_f32_e32 v13, v16, v13
	v_div_scale_f32 v16, vcc, 1.0, v10, 1.0
	v_mul_f32_e32 v17, v16, v13
	v_fma_f32 v18, -v11, v17, v16
	v_fmac_f32_e32 v17, v18, v13
	v_fma_f32 v11, -v11, v17, v16
	v_div_fmas_f32 v11, v11, v13, v17
	v_div_fixup_f32 v13, v11, v10, 1.0
	v_mul_f32_e32 v9, v9, v13
	v_or_b32_e32 v10, 0xc800, v0
	v_mov_b32_e32 v11, v1
	v_mul_f32_e32 v9, v7, v9
	v_lshl_add_u64 v[10:11], v[2:3], 0, v[10:11]
	v_cvt_pk_bf16_f32 v9, v9, v1
	global_store_short v[10:11], v9, off
	v_mul_f32_e32 v9, v12, v13
	v_mul_f32_e32 v9, v6, v9
	v_cvt_pk_bf16_f32 v9, v9, v1
	global_store_short v[10:11], v9, off offset:64
	v_mul_f32_e32 v9, v14, v13
	v_mul_f32_e32 v9, v5, v9
	v_cvt_pk_bf16_f32 v9, v9, v1
	global_store_short v[10:11], v9, off offset:128
	v_mul_f32_e32 v9, v15, v13
	v_mul_f32_e32 v9, v4, v9
	v_cvt_pk_bf16_f32 v9, v9, v1
	global_store_short v[10:11], v9, off offset:192
	ds_read2_b32 v[10:11], v8 offset0:26 offset1:58
	s_waitcnt lgkmcnt(0)
	v_mul_f32_e32 v12, v94, v11
	v_mul_f32_e32 v9, v110, v11
	v_fma_f32 v12, v126, v10, -v12
	v_fma_f32 v9, v142, v10, -v9
	v_mul_f32_e32 v13, v12, v12
	v_mul_f32_e32 v14, v62, v11
	v_fmac_f32_e32 v13, v9, v9
	v_fma_f32 v14, v78, v10, -v14
	v_mul_f32_e32 v11, v30, v11
	v_fmac_f32_e32 v13, v14, v14
	v_fma_f32 v15, v46, v10, -v11
	v_fmac_f32_e32 v13, v15, v15
	s_nop 1
	v_add_f32_dpp v10, v13, v13 quad_perm:[1,0,3,2] row_mask:0xf bank_mask:0xf
	s_nop 1
	v_add_f32_dpp v10, v10, v10 quad_perm:[2,3,0,1] row_mask:0xf bank_mask:0xf
	s_nop 1
	v_add_f32_dpp v10, v10, v10 row_half_mirror row_mask:0xf bank_mask:0xf
	s_nop 1
	v_add_f32_dpp v10, v10, v10 row_mirror row_mask:0xf bank_mask:0xf
	ds_swizzle_b32 v11, v10 offset:swizzle(SWAP,16)
	s_waitcnt lgkmcnt(0)
	v_add_f32_e32 v10, v10, v11
	v_fmamk_f32 v10, v10, 0x3c000000, v230
	v_cmp_gt_f32_e32 vcc, s59, v10
	v_mul_f32_e32 v11, 0x4f800000, v10
	s_nop 0
	v_cndmask_b32_e32 v10, v10, v11, vcc
	v_sqrt_f32_e32 v11, v10
	s_nop 0
	v_add_u32_e32 v13, -1, v11
	v_fma_f32 v16, -v13, v11, v10
	v_cmp_ge_f32_e64 s[8:9], 0, v16
	v_add_u32_e32 v16, 1, v11
	s_nop 0
	v_cndmask_b32_e64 v13, v11, v13, s[8:9]
	v_fma_f32 v11, -v16, v11, v10
	v_cmp_lt_f32_e64 s[8:9], 0, v11
	s_nop 1
	v_cndmask_b32_e64 v11, v13, v16, s[8:9]
	v_mul_f32_e32 v13, 0x37800000, v11
	v_cndmask_b32_e32 v11, v11, v13, vcc
	v_cmp_class_f32_e32 vcc, v10, v231
	s_nop 1
	v_cndmask_b32_e32 v10, v11, v10, vcc
	v_div_scale_f32 v11, s[0:1], v10, v10, 1.0
	v_rcp_f32_e32 v13, v11
	s_nop 0
	v_fma_f32 v16, -v11, v13, 1.0
	v_fmac_f32_e32 v13, v16, v13
	v_div_scale_f32 v16, vcc, 1.0, v10, 1.0
	v_mul_f32_e32 v17, v16, v13
	v_fma_f32 v18, -v11, v17, v16
	v_fmac_f32_e32 v17, v18, v13
	v_fma_f32 v11, -v11, v17, v16
	v_div_fmas_f32 v11, v11, v13, v17
	v_div_fixup_f32 v13, v11, v10, 1.0
	v_mul_f32_e32 v9, v9, v13
	v_or_b32_e32 v10, 0xd000, v0
	v_mov_b32_e32 v11, v1
	v_mul_f32_e32 v9, v7, v9
	v_lshl_add_u64 v[10:11], v[2:3], 0, v[10:11]
	v_cvt_pk_bf16_f32 v9, v9, v1
	global_store_short v[10:11], v9, off
	v_mul_f32_e32 v9, v12, v13
	v_mul_f32_e32 v9, v6, v9
	v_cvt_pk_bf16_f32 v9, v9, v1
	global_store_short v[10:11], v9, off offset:64
	v_mul_f32_e32 v9, v14, v13
	v_mul_f32_e32 v9, v5, v9
	v_cvt_pk_bf16_f32 v9, v9, v1
	global_store_short v[10:11], v9, off offset:128
	v_mul_f32_e32 v9, v15, v13
	v_mul_f32_e32 v9, v4, v9
	v_cvt_pk_bf16_f32 v9, v9, v1
	global_store_short v[10:11], v9, off offset:192
	ds_read2_b32 v[8:9], v8 offset0:27 offset1:59
	v_or_b32_e32 v0, 0xd800, v0
	v_lshl_add_u64 v[2:3], v[2:3], 0, v[0:1]
	s_waitcnt lgkmcnt(0)
	v_mul_f32_e32 v11, v95, v9
	v_mul_f32_e32 v10, v111, v9
	v_fma_f32 v11, v127, v8, -v11
	v_fma_f32 v10, v143, v8, -v10
	v_mul_f32_e32 v12, v11, v11
	v_mul_f32_e32 v13, v63, v9
	v_fmac_f32_e32 v12, v10, v10
	v_fma_f32 v13, v79, v8, -v13
	v_mul_f32_e32 v9, v31, v9
	v_fmac_f32_e32 v12, v13, v13
	v_fma_f32 v8, v47, v8, -v9
	v_fmac_f32_e32 v12, v8, v8
	s_nop 1
	v_add_f32_dpp v9, v12, v12 quad_perm:[1,0,3,2] row_mask:0xf bank_mask:0xf
	s_nop 1
	v_add_f32_dpp v9, v9, v9 quad_perm:[2,3,0,1] row_mask:0xf bank_mask:0xf
	s_nop 1
	v_add_f32_dpp v9, v9, v9 row_half_mirror row_mask:0xf bank_mask:0xf
	s_nop 1
	v_add_f32_dpp v9, v9, v9 row_mirror row_mask:0xf bank_mask:0xf
	ds_swizzle_b32 v12, v9 offset:swizzle(SWAP,16)
	s_waitcnt lgkmcnt(0)
	v_add_f32_e32 v9, v9, v12
	v_fmamk_f32 v9, v9, 0x3c000000, v230
	v_cmp_gt_f32_e32 vcc, s59, v9
	v_mul_f32_e32 v12, 0x4f800000, v9
	s_nop 0
	v_cndmask_b32_e32 v9, v9, v12, vcc
	v_sqrt_f32_e32 v12, v9
	s_nop 0
	v_add_u32_e32 v14, -1, v12
	v_fma_f32 v15, -v14, v12, v9
	v_cmp_ge_f32_e64 s[8:9], 0, v15
	v_add_u32_e32 v15, 1, v12
	s_nop 0
	v_cndmask_b32_e64 v14, v12, v14, s[8:9]
	v_fma_f32 v12, -v15, v12, v9
	v_cmp_lt_f32_e64 s[8:9], 0, v12
	s_nop 1
	v_cndmask_b32_e64 v12, v14, v15, s[8:9]
	v_mul_f32_e32 v14, 0x37800000, v12
	v_cndmask_b32_e32 v12, v12, v14, vcc
	v_cmp_class_f32_e32 vcc, v9, v231
	s_nop 1
	v_cndmask_b32_e32 v9, v12, v9, vcc
	v_div_scale_f32 v12, s[0:1], v9, v9, 1.0
	v_rcp_f32_e32 v14, v12
	v_readlane_b32 s0, v249, 54
	s_add_i32 s42, s42, s0
	s_cmp_gt_i32 s42, 63
	v_fma_f32 v15, -v12, v14, 1.0
	v_fmac_f32_e32 v14, v15, v14
	v_div_scale_f32 v15, vcc, 1.0, v9, 1.0
	v_mul_f32_e32 v16, v15, v14
	v_fma_f32 v17, -v12, v16, v15
	v_fmac_f32_e32 v16, v17, v14
	v_fma_f32 v12, -v12, v16, v15
	v_div_fmas_f32 v12, v12, v14, v16
	v_div_fixup_f32 v9, v12, v9, 1.0
	v_mul_f32_e32 v0, v10, v9
	v_mul_f32_e32 v0, v7, v0
	v_cvt_pk_bf16_f32 v0, v0, v1
	global_store_short v[2:3], v0, off
	v_mul_f32_e32 v0, v11, v9
	v_mul_f32_e32 v0, v6, v0
	v_cvt_pk_bf16_f32 v0, v0, v1
	global_store_short v[2:3], v0, off offset:64
	v_mul_f32_e32 v0, v13, v9
	v_mul_f32_e32 v0, v5, v0
	v_cvt_pk_bf16_f32 v0, v0, v1
	global_store_short v[2:3], v0, off offset:128
	v_mul_f32_e32 v0, v8, v9
	v_mul_f32_e32 v0, v4, v0
	v_cvt_pk_bf16_f32 v0, v0, v1
	global_store_short v[2:3], v0, off offset:192
	s_cbranch_scc1 .LBB0_1321

.LBB0_2094:
	s_or_b64 exec, exec, s[0:1]
	v_readlane_b32 s80, v249, 5
	s_waitcnt lgkmcnt(0)
	v_lshlrev_b32_e32 v8, 2, v0
	v_lshl_add_u32 v4, v5, 4, v3
	v_readlane_b32 s81, v249, 6
	ds_read2_b32 v[6:7], v4 offset1:32
	s_nop 3
	global_load_dword v9, v8, s[80:81]
	global_load_dword v12, v8, s[80:81] offset:128
	global_load_dword v13, v8, s[80:81] offset:256
	global_load_dword v14, v8, s[80:81] offset:384
	v_ashrrev_i32_e32 v2, 1, v2
	v_and_b32_e32 v2, 0xffffffe0, v2
	s_lshl_b64 s[0:1], s[34:35], 25
	s_waitcnt lgkmcnt(0)
	v_mul_f32_e32 v3, v96, v7
	v_fma_f32 v8, v128, v6, -v3
	v_mul_f32_e32 v3, v80, v7
	v_fma_f32 v15, v112, v6, -v3
	v_mul_f32_e32 v3, v15, v15
	v_mul_f32_e32 v10, v32, v7
	v_fmac_f32_e32 v3, v8, v8
	v_fma_f32 v32, v64, v6, -v10
	v_mul_f32_e32 v7, v16, v7
	v_fmac_f32_e32 v3, v32, v32
	v_fma_f32 v16, v48, v6, -v7
	v_fmac_f32_e32 v3, v16, v16
	ds_swizzle_b32 v6, v3 offset:swizzle(SWAP,1)
	v_add_u32_e32 v2, s63, v2
	s_add_u32 s0, s70, s0
	s_addc_u32 s1, s71, s1
	v_lshlrev_b32_e32 v0, 1, v0
	s_waitcnt lgkmcnt(0)
	v_add_f32_e32 v3, v3, v6
	ds_swizzle_b32 v6, v3 offset:swizzle(SWAP,2)
	v_readlane_b32 s82, v249, 7
	v_readlane_b32 s83, v249, 8
	v_readlane_b32 s84, v249, 9
	v_readlane_b32 s85, v249, 10
	s_waitcnt lgkmcnt(0)
	v_add_f32_e32 v3, v3, v6
	ds_swizzle_b32 v6, v3 offset:swizzle(SWAP,4)
	v_readlane_b32 s86, v249, 11
	v_readlane_b32 s87, v249, 12
	v_readlane_b32 s88, v249, 13
	v_readlane_b32 s89, v249, 14
	s_waitcnt lgkmcnt(0)
	v_add_f32_e32 v3, v3, v6
	ds_swizzle_b32 v6, v3 offset:swizzle(SWAP,8)
	v_readlane_b32 s90, v249, 15
	v_readlane_b32 s91, v249, 16
	v_readlane_b32 s92, v249, 17
	v_readlane_b32 s93, v249, 18
	s_waitcnt lgkmcnt(0)
	v_add_f32_e32 v6, v3, v6
	ds_swizzle_b32 v7, v6 offset:swizzle(SWAP,16)
	v_ashrrev_i32_e32 v3, 31, v2
	v_lshlrev_b64 v[2:3], 11, v[2:3]
	v_lshl_add_u64 v[2:3], s[0:1], 0, v[2:3]
	v_readlane_b32 s0, v249, 55
	s_waitcnt lgkmcnt(0)
	v_add_f32_e32 v6, v6, v7
	v_fmamk_f32 v6, v6, 0x3c000000, v230
	v_mul_f32_e32 v7, 0x4f800000, v6
	v_cmp_gt_f32_e32 vcc, s57, v6
	v_readlane_b32 s1, v249, 56
	v_readlane_b32 s94, v249, 19
	v_cndmask_b32_e32 v6, v6, v7, vcc
	v_sqrt_f32_e32 v7, v6
	v_lshl_add_u64 v[2:3], s[0:1], 1, v[2:3]
	v_lshl_add_u64 v[2:3], v[2:3], 0, v[0:1]
	v_lshlrev_b32_e32 v0, 13, v5
	v_add_u32_e32 v5, -1, v7
	v_add_u32_e32 v10, 1, v7
	v_fma_f32 v11, -v5, v7, v6
	v_fma_f32 v48, -v10, v7, v6
	v_cmp_ge_f32_e64 s[4:5], 0, v11
	v_readlane_b32 s95, v249, 20
	s_nop 0
	v_cndmask_b32_e64 v5, v7, v5, s[4:5]
	v_cmp_lt_f32_e64 s[4:5], 0, v48
	s_nop 1
	v_cndmask_b32_e64 v5, v5, v10, s[4:5]
	v_mul_f32_e32 v7, 0x37800000, v5
	v_cndmask_b32_e32 v5, v5, v7, vcc
	v_cmp_class_f32_e32 vcc, v6, v231
	v_lshl_add_u64 v[10:11], v[2:3], 0, v[0:1]
	s_nop 0
	v_cndmask_b32_e32 v5, v5, v6, vcc
	v_div_scale_f32 v6, s[0:1], v5, v5, 1.0
	v_rcp_f32_e32 v7, v6
	v_div_scale_f32 v48, vcc, 1.0, v5, 1.0
	v_fma_f32 v64, -v6, v7, 1.0
	v_fmac_f32_e32 v7, v64, v7
	v_mul_f32_e32 v64, v48, v7
	v_fma_f32 v80, -v6, v64, v48
	v_fmac_f32_e32 v64, v80, v7
	v_fma_f32 v6, -v6, v64, v48
	v_div_fmas_f32 v6, v6, v7, v64
	v_div_fixup_f32 v48, v6, v5, 1.0
	v_mul_f32_e32 v64, v8, v48
	s_waitcnt vmcnt(0)
	v_mul_f32_e32 v7, 0x3f4ccccd, v9
	v_mul_f32_e32 v9, v7, v64
	v_mul_f32_e32 v15, v15, v48
	v_mul_f32_e32 v8, 0x3f4ccccd, v12
	v_cvt_pk_bf16_f32 v9, v9, v1
	v_mul_f32_e32 v12, v8, v15
	global_store_short v[10:11], v9, off
	v_cvt_pk_bf16_f32 v9, v12, v1
	v_mul_f32_e32 v6, 0x3f4ccccd, v13
	global_store_short v[10:11], v9, off offset:64
	v_mul_f32_e32 v9, v32, v48
	v_mul_f32_e32 v9, v6, v9
	v_cvt_pk_bf16_f32 v9, v9, v1
	v_mul_f32_e32 v5, 0x3f4ccccd, v14
	global_store_short v[10:11], v9, off offset:128
	v_mul_f32_e32 v9, v16, v48
	v_mul_f32_e32 v9, v5, v9
	v_cvt_pk_bf16_f32 v9, v9, v1
	ds_read2_b32 v[12:13], v4 offset0:1 offset1:33
	global_store_short v[10:11], v9, off offset:192
	s_waitcnt lgkmcnt(0)
	v_mul_f32_e32 v15, v81, v13
	v_mul_f32_e32 v14, v97, v13
	v_fma_f32 v15, v113, v12, -v15
	v_fma_f32 v14, v129, v12, -v14
	v_mul_f32_e32 v16, v15, v15
	v_mul_f32_e32 v32, v33, v13
	v_fmac_f32_e32 v16, v14, v14
	v_fma_f32 v32, v65, v12, -v32
	v_mul_f32_e32 v13, v17, v13
	v_fmac_f32_e32 v16, v32, v32
	v_fma_f32 v17, v49, v12, -v13
	v_fmac_f32_e32 v16, v17, v17
	s_nop 1
	v_add_f32_dpp v12, v16, v16 quad_perm:[1,0,3,2] row_mask:0xf bank_mask:0xf
	s_nop 1
	v_add_f32_dpp v12, v12, v12 quad_perm:[2,3,0,1] row_mask:0xf bank_mask:0xf
	s_nop 1
	v_add_f32_dpp v12, v12, v12 row_half_mirror row_mask:0xf bank_mask:0xf
	s_nop 1
	v_add_f32_dpp v12, v12, v12 row_mirror row_mask:0xf bank_mask:0xf
	ds_swizzle_b32 v13, v12 offset:swizzle(SWAP,16)
	s_waitcnt lgkmcnt(0)
	v_add_f32_e32 v12, v12, v13
	v_fmamk_f32 v12, v12, 0x3c000000, v230
	v_mul_f32_e32 v13, 0x4f800000, v12
	v_cmp_gt_f32_e32 vcc, s57, v12
	s_nop 1
	v_cndmask_b32_e32 v16, v12, v13, vcc
	v_sqrt_f32_e32 v33, v16
	v_mov_b32_e32 v13, v1
	v_or_b32_e32 v12, 0x800, v0
	v_lshl_add_u64 v[12:13], v[2:3], 0, v[12:13]
	v_add_u32_e32 v48, -1, v33
	v_add_u32_e32 v49, 1, v33
	v_fma_f32 v64, -v48, v33, v16
	v_fma_f32 v65, -v49, v33, v16
	v_cmp_ge_f32_e64 s[4:5], 0, v64
	s_nop 1
	v_cndmask_b32_e64 v33, v33, v48, s[4:5]
	v_cmp_lt_f32_e64 s[4:5], 0, v65
	s_nop 1
	v_cndmask_b32_e64 v33, v33, v49, s[4:5]
	v_mul_f32_e32 v48, 0x37800000, v33
	v_cndmask_b32_e32 v33, v33, v48, vcc
	v_cmp_class_f32_e32 vcc, v16, v231
	s_nop 1
	v_cndmask_b32_e32 v16, v33, v16, vcc
	v_div_scale_f32 v33, s[0:1], v16, v16, 1.0
	v_rcp_f32_e32 v48, v33
	v_div_scale_f32 v9, vcc, 1.0, v16, 1.0
	v_fma_f32 v10, -v33, v48, 1.0
	v_fmac_f32_e32 v48, v10, v48
	v_mul_f32_e32 v10, v9, v48
	v_fma_f32 v11, -v33, v10, v9
	v_fmac_f32_e32 v10, v11, v48
	v_fma_f32 v9, -v33, v10, v9
	v_div_fmas_f32 v9, v9, v48, v10
	v_div_fixup_f32 v9, v9, v16, 1.0
	v_mul_f32_e32 v10, v14, v9
	v_mul_f32_e32 v10, v7, v10
	v_mul_f32_e32 v11, v15, v9
	v_cvt_pk_bf16_f32 v10, v10, v1
	v_mul_f32_e32 v11, v8, v11
	global_store_short v[12:13], v10, off
	v_cvt_pk_bf16_f32 v10, v11, v1
	global_store_short v[12:13], v10, off offset:64
	v_mul_f32_e32 v10, v32, v9
	v_mul_f32_e32 v10, v6, v10
	v_mul_f32_e32 v9, v17, v9
	v_cvt_pk_bf16_f32 v10, v10, v1
	v_mul_f32_e32 v9, v5, v9
	global_store_short v[12:13], v10, off offset:128
	v_cvt_pk_bf16_f32 v9, v9, v1
	ds_read2_b32 v[10:11], v4 offset0:2 offset1:34
	global_store_short v[12:13], v9, off offset:192
	s_waitcnt lgkmcnt(0)
	v_mul_f32_e32 v15, v82, v11
	v_mul_f32_e32 v14, v98, v11
	v_fma_f32 v15, v114, v10, -v15
	v_fma_f32 v14, v130, v10, -v14
	v_mul_f32_e32 v16, v15, v15
	v_mul_f32_e32 v17, v34, v11
	v_fmac_f32_e32 v16, v14, v14
	v_fma_f32 v17, v66, v10, -v17
	v_mul_f32_e32 v11, v18, v11
	v_fmac_f32_e32 v16, v17, v17
	v_fma_f32 v18, v50, v10, -v11
	v_fmac_f32_e32 v16, v18, v18
	s_nop 1
	v_add_f32_dpp v10, v16, v16 quad_perm:[1,0,3,2] row_mask:0xf bank_mask:0xf
	s_nop 1
	v_add_f32_dpp v10, v10, v10 quad_perm:[2,3,0,1] row_mask:0xf bank_mask:0xf
	s_nop 1
	v_add_f32_dpp v10, v10, v10 row_half_mirror row_mask:0xf bank_mask:0xf
	s_nop 1
	v_add_f32_dpp v10, v10, v10 row_mirror row_mask:0xf bank_mask:0xf
	ds_swizzle_b32 v11, v10 offset:swizzle(SWAP,16)
	s_waitcnt lgkmcnt(0)
	v_add_f32_e32 v10, v10, v11
	v_fmamk_f32 v10, v10, 0x3c000000, v230
	v_mul_f32_e32 v11, 0x4f800000, v10
	v_cmp_gt_f32_e32 vcc, s57, v10
	s_nop 1
	v_cndmask_b32_e32 v16, v10, v11, vcc
	v_sqrt_f32_e32 v32, v16
	v_mov_b32_e32 v11, v1
	v_or_b32_e32 v10, 0x1000, v0
	v_lshl_add_u64 v[10:11], v[2:3], 0, v[10:11]
	v_add_u32_e32 v33, -1, v32
	v_add_u32_e32 v34, 1, v32
	v_fma_f32 v48, -v33, v32, v16
	v_fma_f32 v49, -v34, v32, v16
	v_cmp_ge_f32_e64 s[4:5], 0, v48
	s_nop 1
	v_cndmask_b32_e64 v32, v32, v33, s[4:5]
	v_cmp_lt_f32_e64 s[4:5], 0, v49
	s_nop 1
	v_cndmask_b32_e64 v32, v32, v34, s[4:5]
	v_mul_f32_e32 v33, 0x37800000, v32
	v_cndmask_b32_e32 v32, v32, v33, vcc
	v_cmp_class_f32_e32 vcc, v16, v231
	s_nop 1
	v_cndmask_b32_e32 v16, v32, v16, vcc
	v_div_scale_f32 v32, s[0:1], v16, v16, 1.0
	v_rcp_f32_e32 v33, v32
	v_div_scale_f32 v9, vcc, 1.0, v16, 1.0
	v_fma_f32 v12, -v32, v33, 1.0
	v_fmac_f32_e32 v33, v12, v33
	v_mul_f32_e32 v12, v9, v33
	v_fma_f32 v13, -v32, v12, v9
	v_fmac_f32_e32 v12, v13, v33
	v_fma_f32 v9, -v32, v12, v9
	v_div_fmas_f32 v9, v9, v33, v12
	v_div_fixup_f32 v9, v9, v16, 1.0
	v_mul_f32_e32 v12, v14, v9
	v_mul_f32_e32 v12, v7, v12
	v_mul_f32_e32 v13, v15, v9
	v_cvt_pk_bf16_f32 v12, v12, v1
	v_mul_f32_e32 v13, v8, v13
	global_store_short v[10:11], v12, off
	v_cvt_pk_bf16_f32 v12, v13, v1
	global_store_short v[10:11], v12, off offset:64
	v_mul_f32_e32 v12, v17, v9
	v_mul_f32_e32 v12, v6, v12
	v_mul_f32_e32 v9, v18, v9
	v_cvt_pk_bf16_f32 v12, v12, v1
	v_mul_f32_e32 v9, v5, v9
	global_store_short v[10:11], v12, off offset:128
	v_cvt_pk_bf16_f32 v9, v9, v1
	ds_read2_b32 v[12:13], v4 offset0:3 offset1:35
	global_store_short v[10:11], v9, off offset:192
	s_waitcnt lgkmcnt(0)
	v_mul_f32_e32 v15, v83, v13
	v_mul_f32_e32 v14, v99, v13
	v_fma_f32 v15, v115, v12, -v15
	v_fma_f32 v14, v131, v12, -v14
	v_mul_f32_e32 v16, v15, v15
	v_mul_f32_e32 v17, v35, v13
	v_fmac_f32_e32 v16, v14, v14
	v_fma_f32 v17, v67, v12, -v17
	v_mul_f32_e32 v13, v19, v13
	v_fmac_f32_e32 v16, v17, v17
	v_fma_f32 v18, v51, v12, -v13
	v_fmac_f32_e32 v16, v18, v18
	s_nop 1
	v_add_f32_dpp v12, v16, v16 quad_perm:[1,0,3,2] row_mask:0xf bank_mask:0xf
	s_nop 1
	v_add_f32_dpp v12, v12, v12 quad_perm:[2,3,0,1] row_mask:0xf bank_mask:0xf
	s_nop 1
	v_add_f32_dpp v12, v12, v12 row_half_mirror row_mask:0xf bank_mask:0xf
	s_nop 1
	v_add_f32_dpp v12, v12, v12 row_mirror row_mask:0xf bank_mask:0xf
	ds_swizzle_b32 v13, v12 offset:swizzle(SWAP,16)
	s_waitcnt lgkmcnt(0)
	v_add_f32_e32 v12, v12, v13
	v_fmamk_f32 v12, v12, 0x3c000000, v230
	v_mul_f32_e32 v13, 0x4f800000, v12
	v_cmp_gt_f32_e32 vcc, s57, v12
	s_nop 1
	v_cndmask_b32_e32 v16, v12, v13, vcc
	v_sqrt_f32_e32 v19, v16
	v_mov_b32_e32 v13, v1
	v_or_b32_e32 v12, 0x1800, v0
	v_lshl_add_u64 v[12:13], v[2:3], 0, v[12:13]
	v_add_u32_e32 v32, -1, v19
	v_add_u32_e32 v33, 1, v19
	v_fma_f32 v34, -v32, v19, v16
	v_fma_f32 v35, -v33, v19, v16
	v_cmp_ge_f32_e64 s[4:5], 0, v34
	s_nop 1
	v_cndmask_b32_e64 v19, v19, v32, s[4:5]
	v_cmp_lt_f32_e64 s[4:5], 0, v35
	s_nop 1
	v_cndmask_b32_e64 v19, v19, v33, s[4:5]
	v_mul_f32_e32 v32, 0x37800000, v19
	v_cndmask_b32_e32 v19, v19, v32, vcc
	v_cmp_class_f32_e32 vcc, v16, v231
	s_nop 1
	v_cndmask_b32_e32 v16, v19, v16, vcc
	v_div_scale_f32 v19, s[0:1], v16, v16, 1.0
	v_rcp_f32_e32 v32, v19
	v_div_scale_f32 v9, vcc, 1.0, v16, 1.0
	v_fma_f32 v10, -v19, v32, 1.0
	v_fmac_f32_e32 v32, v10, v32
	v_mul_f32_e32 v10, v9, v32
	v_fma_f32 v11, -v19, v10, v9
	v_fmac_f32_e32 v10, v11, v32
	v_fma_f32 v9, -v19, v10, v9
	v_div_fmas_f32 v9, v9, v32, v10
	v_div_fixup_f32 v9, v9, v16, 1.0
	v_mul_f32_e32 v10, v14, v9
	v_mul_f32_e32 v10, v7, v10
	v_mul_f32_e32 v11, v15, v9
	v_cvt_pk_bf16_f32 v10, v10, v1
	v_mul_f32_e32 v11, v8, v11
	global_store_short v[12:13], v10, off
	v_cvt_pk_bf16_f32 v10, v11, v1
	global_store_short v[12:13], v10, off offset:64
	v_mul_f32_e32 v10, v17, v9
	v_mul_f32_e32 v10, v6, v10
	v_mul_f32_e32 v9, v18, v9
	v_cvt_pk_bf16_f32 v10, v10, v1
	v_mul_f32_e32 v9, v5, v9
	global_store_short v[12:13], v10, off offset:128
	v_cvt_pk_bf16_f32 v9, v9, v1
	ds_read2_b32 v[10:11], v4 offset0:8 offset1:40
	global_store_short v[12:13], v9, off offset:192
	s_waitcnt lgkmcnt(0)
	v_mul_f32_e32 v15, v84, v11
	v_mul_f32_e32 v14, v100, v11
	v_fma_f32 v15, v116, v10, -v15
	v_fma_f32 v14, v132, v10, -v14
	v_mul_f32_e32 v16, v15, v15
	v_mul_f32_e32 v17, v36, v11
	v_fmac_f32_e32 v16, v14, v14
	v_fma_f32 v17, v68, v10, -v17
	v_mul_f32_e32 v11, v20, v11
	v_fmac_f32_e32 v16, v17, v17
	v_fma_f32 v18, v52, v10, -v11
	v_fmac_f32_e32 v16, v18, v18
	s_nop 1
	v_add_f32_dpp v10, v16, v16 quad_perm:[1,0,3,2] row_mask:0xf bank_mask:0xf
	s_nop 1
	v_add_f32_dpp v10, v10, v10 quad_perm:[2,3,0,1] row_mask:0xf bank_mask:0xf
	s_nop 1
	v_add_f32_dpp v10, v10, v10 row_half_mirror row_mask:0xf bank_mask:0xf
	s_nop 1
	v_add_f32_dpp v10, v10, v10 row_mirror row_mask:0xf bank_mask:0xf
	ds_swizzle_b32 v11, v10 offset:swizzle(SWAP,16)
	s_waitcnt lgkmcnt(0)
	v_add_f32_e32 v10, v10, v11
	v_fmamk_f32 v10, v10, 0x3c000000, v230
	v_mul_f32_e32 v11, 0x4f800000, v10
	v_cmp_gt_f32_e32 vcc, s57, v10
	s_nop 1
	v_cndmask_b32_e32 v16, v10, v11, vcc
	v_sqrt_f32_e32 v19, v16
	v_mov_b32_e32 v11, v1
	v_or_b32_e32 v10, 0x4000, v0
	v_lshl_add_u64 v[10:11], v[2:3], 0, v[10:11]
	v_add_u32_e32 v20, -1, v19
	v_add_u32_e32 v32, 1, v19
	v_fma_f32 v33, -v20, v19, v16
	v_fma_f32 v34, -v32, v19, v16
	v_cmp_ge_f32_e64 s[4:5], 0, v33
	s_nop 1
	v_cndmask_b32_e64 v19, v19, v20, s[4:5]
	v_cmp_lt_f32_e64 s[4:5], 0, v34
	s_nop 1
	v_cndmask_b32_e64 v19, v19, v32, s[4:5]
	v_mul_f32_e32 v20, 0x37800000, v19
	v_cndmask_b32_e32 v19, v19, v20, vcc
	v_cmp_class_f32_e32 vcc, v16, v231
	s_nop 1
	v_cndmask_b32_e32 v16, v19, v16, vcc
	v_div_scale_f32 v19, s[0:1], v16, v16, 1.0
	v_rcp_f32_e32 v20, v19
	v_div_scale_f32 v9, vcc, 1.0, v16, 1.0
	v_fma_f32 v12, -v19, v20, 1.0
	v_fmac_f32_e32 v20, v12, v20
	v_mul_f32_e32 v12, v9, v20
	v_fma_f32 v13, -v19, v12, v9
	v_fmac_f32_e32 v12, v13, v20
	v_fma_f32 v9, -v19, v12, v9
	v_div_fmas_f32 v9, v9, v20, v12
	v_div_fixup_f32 v9, v9, v16, 1.0
	v_mul_f32_e32 v12, v14, v9
	v_mul_f32_e32 v12, v7, v12
	v_mul_f32_e32 v13, v15, v9
	v_cvt_pk_bf16_f32 v12, v12, v1
	v_mul_f32_e32 v13, v8, v13
	global_store_short v[10:11], v12, off
	v_cvt_pk_bf16_f32 v12, v13, v1
	global_store_short v[10:11], v12, off offset:64
	v_mul_f32_e32 v12, v17, v9
	v_mul_f32_e32 v12, v6, v12
	v_mul_f32_e32 v9, v18, v9
	v_cvt_pk_bf16_f32 v12, v12, v1
	v_mul_f32_e32 v9, v5, v9
	global_store_short v[10:11], v12, off offset:128
	v_cvt_pk_bf16_f32 v9, v9, v1
	ds_read2_b32 v[12:13], v4 offset0:9 offset1:41
	global_store_short v[10:11], v9, off offset:192
	s_waitcnt lgkmcnt(0)
	v_mul_f32_e32 v15, v85, v13
	v_mul_f32_e32 v14, v101, v13
	v_fma_f32 v15, v117, v12, -v15
	v_fma_f32 v14, v133, v12, -v14
	v_mul_f32_e32 v16, v15, v15
	v_mul_f32_e32 v17, v37, v13
	v_fmac_f32_e32 v16, v14, v14
	v_fma_f32 v17, v69, v12, -v17
	v_mul_f32_e32 v13, v21, v13
	v_fmac_f32_e32 v16, v17, v17
	v_fma_f32 v18, v53, v12, -v13
	v_fmac_f32_e32 v16, v18, v18
	s_nop 1
	v_add_f32_dpp v12, v16, v16 quad_perm:[1,0,3,2] row_mask:0xf bank_mask:0xf
	s_nop 1
	v_add_f32_dpp v12, v12, v12 quad_perm:[2,3,0,1] row_mask:0xf bank_mask:0xf
	s_nop 1
	v_add_f32_dpp v12, v12, v12 row_half_mirror row_mask:0xf bank_mask:0xf
	s_nop 1
	v_add_f32_dpp v12, v12, v12 row_mirror row_mask:0xf bank_mask:0xf
	ds_swizzle_b32 v13, v12 offset:swizzle(SWAP,16)
	s_waitcnt lgkmcnt(0)
	v_add_f32_e32 v12, v12, v13
	v_fmamk_f32 v12, v12, 0x3c000000, v230
	v_mul_f32_e32 v13, 0x4f800000, v12
	v_cmp_gt_f32_e32 vcc, s57, v12
	s_nop 1
	v_cndmask_b32_e32 v16, v12, v13, vcc
	v_sqrt_f32_e32 v19, v16
	v_mov_b32_e32 v13, v1
	v_or_b32_e32 v12, 0x4800, v0
	v_lshl_add_u64 v[12:13], v[2:3], 0, v[12:13]
	v_add_u32_e32 v20, -1, v19
	v_add_u32_e32 v21, 1, v19
	v_fma_f32 v32, -v20, v19, v16
	v_fma_f32 v33, -v21, v19, v16
	v_cmp_ge_f32_e64 s[4:5], 0, v32
	s_nop 1
	v_cndmask_b32_e64 v19, v19, v20, s[4:5]
	v_cmp_lt_f32_e64 s[4:5], 0, v33
	s_nop 1
	v_cndmask_b32_e64 v19, v19, v21, s[4:5]
	v_mul_f32_e32 v20, 0x37800000, v19
	v_cndmask_b32_e32 v19, v19, v20, vcc
	v_cmp_class_f32_e32 vcc, v16, v231
	s_nop 1
	v_cndmask_b32_e32 v16, v19, v16, vcc
	v_div_scale_f32 v19, s[0:1], v16, v16, 1.0
	v_rcp_f32_e32 v20, v19
	v_div_scale_f32 v9, vcc, 1.0, v16, 1.0
	v_fma_f32 v10, -v19, v20, 1.0
	v_fmac_f32_e32 v20, v10, v20
	v_mul_f32_e32 v10, v9, v20
	v_fma_f32 v11, -v19, v10, v9
	v_fmac_f32_e32 v10, v11, v20
	v_fma_f32 v9, -v19, v10, v9
	v_div_fmas_f32 v9, v9, v20, v10
	v_div_fixup_f32 v9, v9, v16, 1.0
	v_mul_f32_e32 v10, v14, v9
	v_mul_f32_e32 v10, v7, v10
	v_mul_f32_e32 v11, v15, v9
	v_cvt_pk_bf16_f32 v10, v10, v1
	v_mul_f32_e32 v11, v8, v11
	global_store_short v[12:13], v10, off
	v_cvt_pk_bf16_f32 v10, v11, v1
	global_store_short v[12:13], v10, off offset:64
	v_mul_f32_e32 v10, v17, v9
	v_mul_f32_e32 v10, v6, v10
	v_mul_f32_e32 v9, v18, v9
	v_cvt_pk_bf16_f32 v10, v10, v1
	v_mul_f32_e32 v9, v5, v9
	global_store_short v[12:13], v10, off offset:128
	v_cvt_pk_bf16_f32 v9, v9, v1
	ds_read2_b32 v[10:11], v4 offset0:10 offset1:42
	global_store_short v[12:13], v9, off offset:192
	s_waitcnt lgkmcnt(0)
	v_mul_f32_e32 v15, v86, v11
	v_mul_f32_e32 v14, v102, v11
	v_fma_f32 v15, v118, v10, -v15
	v_fma_f32 v14, v134, v10, -v14
	v_mul_f32_e32 v16, v15, v15
	v_mul_f32_e32 v17, v38, v11
	v_fmac_f32_e32 v16, v14, v14
	v_fma_f32 v17, v70, v10, -v17
	v_mul_f32_e32 v11, v22, v11
	v_fmac_f32_e32 v16, v17, v17
	v_fma_f32 v18, v54, v10, -v11
	v_fmac_f32_e32 v16, v18, v18
	s_nop 1
	v_add_f32_dpp v10, v16, v16 quad_perm:[1,0,3,2] row_mask:0xf bank_mask:0xf
	s_nop 1
	v_add_f32_dpp v10, v10, v10 quad_perm:[2,3,0,1] row_mask:0xf bank_mask:0xf
	s_nop 1
	v_add_f32_dpp v10, v10, v10 row_half_mirror row_mask:0xf bank_mask:0xf
	s_nop 1
	v_add_f32_dpp v10, v10, v10 row_mirror row_mask:0xf bank_mask:0xf
	ds_swizzle_b32 v11, v10 offset:swizzle(SWAP,16)
	s_waitcnt lgkmcnt(0)
	v_add_f32_e32 v10, v10, v11
	v_fmamk_f32 v10, v10, 0x3c000000, v230
	v_mul_f32_e32 v11, 0x4f800000, v10
	v_cmp_gt_f32_e32 vcc, s57, v10
	s_nop 1
	v_cndmask_b32_e32 v16, v10, v11, vcc
	v_sqrt_f32_e32 v19, v16
	v_mov_b32_e32 v11, v1
	v_or_b32_e32 v10, 0x5000, v0
	v_lshl_add_u64 v[10:11], v[2:3], 0, v[10:11]
	v_add_u32_e32 v20, -1, v19
	v_add_u32_e32 v21, 1, v19
	v_fma_f32 v22, -v20, v19, v16
	v_fma_f32 v32, -v21, v19, v16
	v_cmp_ge_f32_e64 s[4:5], 0, v22
	s_nop 1
	v_cndmask_b32_e64 v19, v19, v20, s[4:5]
	v_cmp_lt_f32_e64 s[4:5], 0, v32
	s_nop 1
	v_cndmask_b32_e64 v19, v19, v21, s[4:5]
	v_mul_f32_e32 v20, 0x37800000, v19
	v_cndmask_b32_e32 v19, v19, v20, vcc
	v_cmp_class_f32_e32 vcc, v16, v231
	s_nop 1
	v_cndmask_b32_e32 v16, v19, v16, vcc
	v_div_scale_f32 v19, s[0:1], v16, v16, 1.0
	v_rcp_f32_e32 v20, v19
	v_div_scale_f32 v9, vcc, 1.0, v16, 1.0
	v_fma_f32 v12, -v19, v20, 1.0
	v_fmac_f32_e32 v20, v12, v20
	v_mul_f32_e32 v12, v9, v20
	v_fma_f32 v13, -v19, v12, v9
	v_fmac_f32_e32 v12, v13, v20
	v_fma_f32 v9, -v19, v12, v9
	v_div_fmas_f32 v9, v9, v20, v12
	v_div_fixup_f32 v9, v9, v16, 1.0
	v_mul_f32_e32 v12, v14, v9
	v_mul_f32_e32 v12, v7, v12
	v_mul_f32_e32 v13, v15, v9
	v_cvt_pk_bf16_f32 v12, v12, v1
	v_mul_f32_e32 v13, v8, v13
	global_store_short v[10:11], v12, off
	v_cvt_pk_bf16_f32 v12, v13, v1
	global_store_short v[10:11], v12, off offset:64
	v_mul_f32_e32 v12, v17, v9
	v_mul_f32_e32 v12, v6, v12
	v_mul_f32_e32 v9, v18, v9
	v_cvt_pk_bf16_f32 v12, v12, v1
	v_mul_f32_e32 v9, v5, v9
	global_store_short v[10:11], v12, off offset:128
	v_cvt_pk_bf16_f32 v9, v9, v1
	ds_read2_b32 v[12:13], v4 offset0:11 offset1:43
	global_store_short v[10:11], v9, off offset:192
	s_waitcnt lgkmcnt(0)
	v_mul_f32_e32 v15, v87, v13
	v_mul_f32_e32 v14, v103, v13
	v_fma_f32 v15, v119, v12, -v15
	v_fma_f32 v14, v135, v12, -v14
	v_mul_f32_e32 v16, v15, v15
	v_mul_f32_e32 v17, v39, v13
	v_fmac_f32_e32 v16, v14, v14
	v_fma_f32 v17, v71, v12, -v17
	v_mul_f32_e32 v13, v23, v13
	v_fmac_f32_e32 v16, v17, v17
	v_fma_f32 v18, v55, v12, -v13
	v_fmac_f32_e32 v16, v18, v18
	s_nop 1
	v_add_f32_dpp v12, v16, v16 quad_perm:[1,0,3,2] row_mask:0xf bank_mask:0xf
	s_nop 1
	v_add_f32_dpp v12, v12, v12 quad_perm:[2,3,0,1] row_mask:0xf bank_mask:0xf
	s_nop 1
	v_add_f32_dpp v12, v12, v12 row_half_mirror row_mask:0xf bank_mask:0xf
	s_nop 1
	v_add_f32_dpp v12, v12, v12 row_mirror row_mask:0xf bank_mask:0xf
	ds_swizzle_b32 v13, v12 offset:swizzle(SWAP,16)
	s_waitcnt lgkmcnt(0)
	v_add_f32_e32 v12, v12, v13
	v_fmamk_f32 v12, v12, 0x3c000000, v230
	v_mul_f32_e32 v13, 0x4f800000, v12
	v_cmp_gt_f32_e32 vcc, s57, v12
	s_nop 1
	v_cndmask_b32_e32 v16, v12, v13, vcc
	v_sqrt_f32_e32 v19, v16
	v_mov_b32_e32 v13, v1
	v_or_b32_e32 v12, 0x5800, v0
	v_lshl_add_u64 v[12:13], v[2:3], 0, v[12:13]
	v_add_u32_e32 v20, -1, v19
	v_add_u32_e32 v21, 1, v19
	v_fma_f32 v22, -v20, v19, v16
	v_fma_f32 v23, -v21, v19, v16
	v_cmp_ge_f32_e64 s[4:5], 0, v22
	s_nop 1
	v_cndmask_b32_e64 v19, v19, v20, s[4:5]
	v_cmp_lt_f32_e64 s[4:5], 0, v23
	s_nop 1
	v_cndmask_b32_e64 v19, v19, v21, s[4:5]
	v_mul_f32_e32 v20, 0x37800000, v19
	v_cndmask_b32_e32 v19, v19, v20, vcc
	v_cmp_class_f32_e32 vcc, v16, v231
	s_nop 1
	v_cndmask_b32_e32 v16, v19, v16, vcc
	v_div_scale_f32 v19, s[0:1], v16, v16, 1.0
	v_rcp_f32_e32 v20, v19
	v_div_scale_f32 v9, vcc, 1.0, v16, 1.0
	v_fma_f32 v10, -v19, v20, 1.0
	v_fmac_f32_e32 v20, v10, v20
	v_mul_f32_e32 v10, v9, v20
	v_fma_f32 v11, -v19, v10, v9
	v_fmac_f32_e32 v10, v11, v20
	v_fma_f32 v9, -v19, v10, v9
	v_div_fmas_f32 v9, v9, v20, v10
	v_div_fixup_f32 v9, v9, v16, 1.0
	v_mul_f32_e32 v10, v14, v9
	v_mul_f32_e32 v10, v7, v10
	v_mul_f32_e32 v11, v15, v9
	v_cvt_pk_bf16_f32 v10, v10, v1
	v_mul_f32_e32 v11, v8, v11
	global_store_short v[12:13], v10, off
	v_cvt_pk_bf16_f32 v10, v11, v1
	global_store_short v[12:13], v10, off offset:64
	v_mul_f32_e32 v10, v17, v9
	v_mul_f32_e32 v10, v6, v10
	v_mul_f32_e32 v9, v18, v9
	v_cvt_pk_bf16_f32 v10, v10, v1
	v_mul_f32_e32 v9, v5, v9
	global_store_short v[12:13], v10, off offset:128
	v_cvt_pk_bf16_f32 v9, v9, v1
	ds_read2_b32 v[10:11], v4 offset0:16 offset1:48
	global_store_short v[12:13], v9, off offset:192
	s_waitcnt lgkmcnt(0)
	v_mul_f32_e32 v15, v88, v11
	v_mul_f32_e32 v14, v104, v11
	v_fma_f32 v15, v120, v10, -v15
	v_fma_f32 v14, v136, v10, -v14
	v_mul_f32_e32 v16, v15, v15
	v_mul_f32_e32 v17, v40, v11
	v_fmac_f32_e32 v16, v14, v14
	v_fma_f32 v17, v72, v10, -v17
	v_mul_f32_e32 v11, v24, v11
	v_fmac_f32_e32 v16, v17, v17
	v_fma_f32 v18, v56, v10, -v11
	v_fmac_f32_e32 v16, v18, v18
	s_nop 1
	v_add_f32_dpp v10, v16, v16 quad_perm:[1,0,3,2] row_mask:0xf bank_mask:0xf
	s_nop 1
	v_add_f32_dpp v10, v10, v10 quad_perm:[2,3,0,1] row_mask:0xf bank_mask:0xf
	s_nop 1
	v_add_f32_dpp v10, v10, v10 row_half_mirror row_mask:0xf bank_mask:0xf
	s_nop 1
	v_add_f32_dpp v10, v10, v10 row_mirror row_mask:0xf bank_mask:0xf
	ds_swizzle_b32 v11, v10 offset:swizzle(SWAP,16)
	s_waitcnt lgkmcnt(0)
	v_add_f32_e32 v10, v10, v11
	v_fmamk_f32 v10, v10, 0x3c000000, v230
	v_mul_f32_e32 v11, 0x4f800000, v10
	v_cmp_gt_f32_e32 vcc, s57, v10
	s_nop 1
	v_cndmask_b32_e32 v16, v10, v11, vcc
	v_sqrt_f32_e32 v19, v16
	v_mov_b32_e32 v11, v1
	v_or_b32_e32 v10, 0x8000, v0
	v_lshl_add_u64 v[10:11], v[2:3], 0, v[10:11]
	v_add_u32_e32 v20, -1, v19
	v_add_u32_e32 v21, 1, v19
	v_fma_f32 v22, -v20, v19, v16
	v_fma_f32 v23, -v21, v19, v16
	v_cmp_ge_f32_e64 s[4:5], 0, v22
	s_nop 1
	v_cndmask_b32_e64 v19, v19, v20, s[4:5]
	v_cmp_lt_f32_e64 s[4:5], 0, v23
	s_nop 1
	v_cndmask_b32_e64 v19, v19, v21, s[4:5]
	v_mul_f32_e32 v20, 0x37800000, v19
	v_cndmask_b32_e32 v19, v19, v20, vcc
	v_cmp_class_f32_e32 vcc, v16, v231
	s_nop 1
	v_cndmask_b32_e32 v16, v19, v16, vcc
	v_div_scale_f32 v19, s[0:1], v16, v16, 1.0
	v_rcp_f32_e32 v20, v19
	v_div_scale_f32 v9, vcc, 1.0, v16, 1.0
	v_fma_f32 v12, -v19, v20, 1.0
	v_fmac_f32_e32 v20, v12, v20
	v_mul_f32_e32 v12, v9, v20
	v_fma_f32 v13, -v19, v12, v9
	v_fmac_f32_e32 v12, v13, v20
	v_fma_f32 v9, -v19, v12, v9
	v_div_fmas_f32 v9, v9, v20, v12
	v_div_fixup_f32 v9, v9, v16, 1.0
	v_mul_f32_e32 v12, v14, v9
	v_mul_f32_e32 v12, v7, v12
	v_mul_f32_e32 v13, v15, v9
	v_cvt_pk_bf16_f32 v12, v12, v1
	v_mul_f32_e32 v13, v8, v13
	global_store_short v[10:11], v12, off
	v_cvt_pk_bf16_f32 v12, v13, v1
	global_store_short v[10:11], v12, off offset:64
	v_mul_f32_e32 v12, v17, v9
	v_mul_f32_e32 v12, v6, v12
	v_mul_f32_e32 v9, v18, v9
	v_cvt_pk_bf16_f32 v12, v12, v1
	v_mul_f32_e32 v9, v5, v9
	global_store_short v[10:11], v12, off offset:128
	v_cvt_pk_bf16_f32 v9, v9, v1
	ds_read2_b32 v[12:13], v4 offset0:17 offset1:49
	global_store_short v[10:11], v9, off offset:192
	s_waitcnt lgkmcnt(0)
	v_mul_f32_e32 v15, v89, v13
	v_mul_f32_e32 v14, v105, v13
	v_fma_f32 v15, v121, v12, -v15
	v_fma_f32 v14, v137, v12, -v14
	v_mul_f32_e32 v16, v15, v15
	v_mul_f32_e32 v17, v41, v13
	v_fmac_f32_e32 v16, v14, v14
	v_fma_f32 v17, v73, v12, -v17
	v_mul_f32_e32 v13, v25, v13
	v_fmac_f32_e32 v16, v17, v17
	v_fma_f32 v18, v57, v12, -v13
	v_fmac_f32_e32 v16, v18, v18
	s_nop 1
	v_add_f32_dpp v12, v16, v16 quad_perm:[1,0,3,2] row_mask:0xf bank_mask:0xf
	s_nop 1
	v_add_f32_dpp v12, v12, v12 quad_perm:[2,3,0,1] row_mask:0xf bank_mask:0xf
	s_nop 1
	v_add_f32_dpp v12, v12, v12 row_half_mirror row_mask:0xf bank_mask:0xf
	s_nop 1
	v_add_f32_dpp v12, v12, v12 row_mirror row_mask:0xf bank_mask:0xf
	ds_swizzle_b32 v13, v12 offset:swizzle(SWAP,16)
	s_waitcnt lgkmcnt(0)
	v_add_f32_e32 v12, v12, v13
	v_fmamk_f32 v12, v12, 0x3c000000, v230
	v_mul_f32_e32 v13, 0x4f800000, v12
	v_cmp_gt_f32_e32 vcc, s57, v12
	s_nop 1
	v_cndmask_b32_e32 v16, v12, v13, vcc
	v_sqrt_f32_e32 v19, v16
	v_mov_b32_e32 v13, v1
	v_or_b32_e32 v12, 0x8800, v0
	v_lshl_add_u64 v[12:13], v[2:3], 0, v[12:13]
	v_add_u32_e32 v20, -1, v19
	v_add_u32_e32 v21, 1, v19
	v_fma_f32 v22, -v20, v19, v16
	v_fma_f32 v23, -v21, v19, v16
	v_cmp_ge_f32_e64 s[4:5], 0, v22
	s_nop 1
	v_cndmask_b32_e64 v19, v19, v20, s[4:5]
	v_cmp_lt_f32_e64 s[4:5], 0, v23
	s_nop 1
	v_cndmask_b32_e64 v19, v19, v21, s[4:5]
	v_mul_f32_e32 v20, 0x37800000, v19
	v_cndmask_b32_e32 v19, v19, v20, vcc
	v_cmp_class_f32_e32 vcc, v16, v231
	s_nop 1
	v_cndmask_b32_e32 v16, v19, v16, vcc
	v_div_scale_f32 v19, s[0:1], v16, v16, 1.0
	v_rcp_f32_e32 v20, v19
	v_div_scale_f32 v9, vcc, 1.0, v16, 1.0
	v_fma_f32 v10, -v19, v20, 1.0
	v_fmac_f32_e32 v20, v10, v20
	v_mul_f32_e32 v10, v9, v20
	v_fma_f32 v11, -v19, v10, v9
	v_fmac_f32_e32 v10, v11, v20
	v_fma_f32 v9, -v19, v10, v9
	v_div_fmas_f32 v9, v9, v20, v10
	v_div_fixup_f32 v9, v9, v16, 1.0
	v_mul_f32_e32 v10, v14, v9
	v_mul_f32_e32 v10, v7, v10
	v_mul_f32_e32 v11, v15, v9
	v_cvt_pk_bf16_f32 v10, v10, v1
	v_mul_f32_e32 v11, v8, v11
	global_store_short v[12:13], v10, off
	v_cvt_pk_bf16_f32 v10, v11, v1
	global_store_short v[12:13], v10, off offset:64
	v_mul_f32_e32 v10, v17, v9
	v_mul_f32_e32 v10, v6, v10
	v_mul_f32_e32 v9, v18, v9
	v_cvt_pk_bf16_f32 v10, v10, v1
	v_mul_f32_e32 v9, v5, v9
	global_store_short v[12:13], v10, off offset:128
	v_cvt_pk_bf16_f32 v9, v9, v1
	ds_read2_b32 v[10:11], v4 offset0:18 offset1:50
	global_store_short v[12:13], v9, off offset:192
	s_waitcnt lgkmcnt(0)
	v_mul_f32_e32 v15, v90, v11
	v_mul_f32_e32 v14, v106, v11
	v_fma_f32 v15, v122, v10, -v15
	v_fma_f32 v14, v138, v10, -v14
	v_mul_f32_e32 v16, v15, v15
	v_mul_f32_e32 v17, v42, v11
	v_fmac_f32_e32 v16, v14, v14
	v_fma_f32 v17, v74, v10, -v17
	v_mul_f32_e32 v11, v26, v11
	v_fmac_f32_e32 v16, v17, v17
	v_fma_f32 v18, v58, v10, -v11
	v_fmac_f32_e32 v16, v18, v18
	s_nop 1
	v_add_f32_dpp v10, v16, v16 quad_perm:[1,0,3,2] row_mask:0xf bank_mask:0xf
	s_nop 1
	v_add_f32_dpp v10, v10, v10 quad_perm:[2,3,0,1] row_mask:0xf bank_mask:0xf
	s_nop 1
	v_add_f32_dpp v10, v10, v10 row_half_mirror row_mask:0xf bank_mask:0xf
	s_nop 1
	v_add_f32_dpp v10, v10, v10 row_mirror row_mask:0xf bank_mask:0xf
	ds_swizzle_b32 v11, v10 offset:swizzle(SWAP,16)
	s_waitcnt lgkmcnt(0)
	v_add_f32_e32 v10, v10, v11
	v_fmamk_f32 v10, v10, 0x3c000000, v230
	v_mul_f32_e32 v11, 0x4f800000, v10
	v_cmp_gt_f32_e32 vcc, s57, v10
	s_nop 1
	v_cndmask_b32_e32 v16, v10, v11, vcc
	v_sqrt_f32_e32 v19, v16
	v_mov_b32_e32 v11, v1
	v_or_b32_e32 v10, 0x9000, v0
	v_lshl_add_u64 v[10:11], v[2:3], 0, v[10:11]
	v_add_u32_e32 v20, -1, v19
	v_add_u32_e32 v21, 1, v19
	v_fma_f32 v22, -v20, v19, v16
	v_fma_f32 v23, -v21, v19, v16
	v_cmp_ge_f32_e64 s[4:5], 0, v22
	s_nop 1
	v_cndmask_b32_e64 v19, v19, v20, s[4:5]
	v_cmp_lt_f32_e64 s[4:5], 0, v23
	s_nop 1
	v_cndmask_b32_e64 v19, v19, v21, s[4:5]
	v_mul_f32_e32 v20, 0x37800000, v19
	v_cndmask_b32_e32 v19, v19, v20, vcc
	v_cmp_class_f32_e32 vcc, v16, v231
	s_nop 1
	v_cndmask_b32_e32 v16, v19, v16, vcc
	v_div_scale_f32 v19, s[0:1], v16, v16, 1.0
	v_rcp_f32_e32 v20, v19
	v_div_scale_f32 v9, vcc, 1.0, v16, 1.0
	v_fma_f32 v12, -v19, v20, 1.0
	v_fmac_f32_e32 v20, v12, v20
	v_mul_f32_e32 v12, v9, v20
	v_fma_f32 v13, -v19, v12, v9
	v_fmac_f32_e32 v12, v13, v20
	v_fma_f32 v9, -v19, v12, v9
	v_div_fmas_f32 v9, v9, v20, v12
	v_div_fixup_f32 v9, v9, v16, 1.0
	v_mul_f32_e32 v12, v14, v9
	v_mul_f32_e32 v12, v7, v12
	v_mul_f32_e32 v13, v15, v9
	v_cvt_pk_bf16_f32 v12, v12, v1
	v_mul_f32_e32 v13, v8, v13
	global_store_short v[10:11], v12, off
	v_cvt_pk_bf16_f32 v12, v13, v1
	global_store_short v[10:11], v12, off offset:64
	v_mul_f32_e32 v12, v17, v9
	v_mul_f32_e32 v12, v6, v12
	v_mul_f32_e32 v9, v18, v9
	v_cvt_pk_bf16_f32 v12, v12, v1
	v_mul_f32_e32 v9, v5, v9
	global_store_short v[10:11], v12, off offset:128
	v_cvt_pk_bf16_f32 v9, v9, v1
	ds_read2_b32 v[12:13], v4 offset0:19 offset1:51
	global_store_short v[10:11], v9, off offset:192
	s_waitcnt lgkmcnt(0)
	v_mul_f32_e32 v15, v91, v13
	v_mul_f32_e32 v14, v107, v13
	v_fma_f32 v15, v123, v12, -v15
	v_fma_f32 v14, v139, v12, -v14
	v_mul_f32_e32 v16, v15, v15
	v_mul_f32_e32 v17, v43, v13
	v_fmac_f32_e32 v16, v14, v14
	v_fma_f32 v17, v75, v12, -v17
	v_mul_f32_e32 v13, v27, v13
	v_fmac_f32_e32 v16, v17, v17
	v_fma_f32 v18, v59, v12, -v13
	v_fmac_f32_e32 v16, v18, v18
	s_nop 1
	v_add_f32_dpp v12, v16, v16 quad_perm:[1,0,3,2] row_mask:0xf bank_mask:0xf
	s_nop 1
	v_add_f32_dpp v12, v12, v12 quad_perm:[2,3,0,1] row_mask:0xf bank_mask:0xf
	s_nop 1
	v_add_f32_dpp v12, v12, v12 row_half_mirror row_mask:0xf bank_mask:0xf
	s_nop 1
	v_add_f32_dpp v12, v12, v12 row_mirror row_mask:0xf bank_mask:0xf
	ds_swizzle_b32 v13, v12 offset:swizzle(SWAP,16)
	s_waitcnt lgkmcnt(0)
	v_add_f32_e32 v12, v12, v13
	v_fmamk_f32 v12, v12, 0x3c000000, v230
	v_mul_f32_e32 v13, 0x4f800000, v12
	v_cmp_gt_f32_e32 vcc, s57, v12
	s_nop 1
	v_cndmask_b32_e32 v16, v12, v13, vcc
	v_sqrt_f32_e32 v19, v16
	v_mov_b32_e32 v13, v1
	v_or_b32_e32 v12, 0x9800, v0
	v_lshl_add_u64 v[12:13], v[2:3], 0, v[12:13]
	v_add_u32_e32 v20, -1, v19
	v_add_u32_e32 v21, 1, v19
	v_fma_f32 v22, -v20, v19, v16
	v_fma_f32 v23, -v21, v19, v16
	v_cmp_ge_f32_e64 s[4:5], 0, v22
	s_nop 1
	v_cndmask_b32_e64 v19, v19, v20, s[4:5]
	v_cmp_lt_f32_e64 s[4:5], 0, v23
	s_nop 1
	v_cndmask_b32_e64 v19, v19, v21, s[4:5]
	v_mul_f32_e32 v20, 0x37800000, v19
	v_cndmask_b32_e32 v19, v19, v20, vcc
	v_cmp_class_f32_e32 vcc, v16, v231
	s_nop 1
	v_cndmask_b32_e32 v16, v19, v16, vcc
	v_div_scale_f32 v19, s[0:1], v16, v16, 1.0
	v_rcp_f32_e32 v20, v19
	v_div_scale_f32 v9, vcc, 1.0, v16, 1.0
	v_fma_f32 v10, -v19, v20, 1.0
	v_fmac_f32_e32 v20, v10, v20
	v_mul_f32_e32 v10, v9, v20
	v_fma_f32 v11, -v19, v10, v9
	v_fmac_f32_e32 v10, v11, v20
	v_fma_f32 v9, -v19, v10, v9
	v_div_fmas_f32 v9, v9, v20, v10
	v_div_fixup_f32 v9, v9, v16, 1.0
	v_mul_f32_e32 v10, v14, v9
	v_mul_f32_e32 v10, v7, v10
	v_mul_f32_e32 v11, v15, v9
	v_cvt_pk_bf16_f32 v10, v10, v1
	v_mul_f32_e32 v11, v8, v11
	global_store_short v[12:13], v10, off
	v_cvt_pk_bf16_f32 v10, v11, v1
	global_store_short v[12:13], v10, off offset:64
	v_mul_f32_e32 v10, v17, v9
	v_mul_f32_e32 v10, v6, v10
	v_mul_f32_e32 v9, v18, v9
	v_cvt_pk_bf16_f32 v10, v10, v1
	v_mul_f32_e32 v9, v5, v9
	global_store_short v[12:13], v10, off offset:128
	v_cvt_pk_bf16_f32 v9, v9, v1
	ds_read2_b32 v[10:11], v4 offset0:24 offset1:56
	global_store_short v[12:13], v9, off offset:192
	s_waitcnt lgkmcnt(0)
	v_mul_f32_e32 v15, v92, v11
	v_mul_f32_e32 v14, v108, v11
	v_fma_f32 v15, v124, v10, -v15
	v_fma_f32 v14, v140, v10, -v14
	v_mul_f32_e32 v16, v15, v15
	v_mul_f32_e32 v17, v44, v11
	v_fmac_f32_e32 v16, v14, v14
	v_fma_f32 v17, v76, v10, -v17
	v_mul_f32_e32 v11, v28, v11
	v_fmac_f32_e32 v16, v17, v17
	v_fma_f32 v18, v60, v10, -v11
	v_fmac_f32_e32 v16, v18, v18
	s_nop 1
	v_add_f32_dpp v10, v16, v16 quad_perm:[1,0,3,2] row_mask:0xf bank_mask:0xf
	s_nop 1
	v_add_f32_dpp v10, v10, v10 quad_perm:[2,3,0,1] row_mask:0xf bank_mask:0xf
	s_nop 1
	v_add_f32_dpp v10, v10, v10 row_half_mirror row_mask:0xf bank_mask:0xf
	s_nop 1
	v_add_f32_dpp v10, v10, v10 row_mirror row_mask:0xf bank_mask:0xf
	ds_swizzle_b32 v11, v10 offset:swizzle(SWAP,16)
	s_waitcnt lgkmcnt(0)
	v_add_f32_e32 v10, v10, v11
	v_fmamk_f32 v10, v10, 0x3c000000, v230
	v_mul_f32_e32 v11, 0x4f800000, v10
	v_cmp_gt_f32_e32 vcc, s57, v10
	s_nop 1
	v_cndmask_b32_e32 v16, v10, v11, vcc
	v_sqrt_f32_e32 v19, v16
	v_mov_b32_e32 v11, v1
	v_or_b32_e32 v10, 0xc000, v0
	v_lshl_add_u64 v[10:11], v[2:3], 0, v[10:11]
	v_add_u32_e32 v20, -1, v19
	v_add_u32_e32 v21, 1, v19
	v_fma_f32 v22, -v20, v19, v16
	v_fma_f32 v23, -v21, v19, v16
	v_cmp_ge_f32_e64 s[4:5], 0, v22
	s_nop 1
	v_cndmask_b32_e64 v19, v19, v20, s[4:5]
	v_cmp_lt_f32_e64 s[4:5], 0, v23
	s_nop 1
	v_cndmask_b32_e64 v19, v19, v21, s[4:5]
	v_mul_f32_e32 v20, 0x37800000, v19
	v_cndmask_b32_e32 v19, v19, v20, vcc
	v_cmp_class_f32_e32 vcc, v16, v231
	s_nop 1
	v_cndmask_b32_e32 v16, v19, v16, vcc
	v_div_scale_f32 v19, s[0:1], v16, v16, 1.0
	v_rcp_f32_e32 v20, v19
	v_div_scale_f32 v9, vcc, 1.0, v16, 1.0
	v_fma_f32 v12, -v19, v20, 1.0
	v_fmac_f32_e32 v20, v12, v20
	v_mul_f32_e32 v12, v9, v20
	v_fma_f32 v13, -v19, v12, v9
	v_fmac_f32_e32 v12, v13, v20
	v_fma_f32 v9, -v19, v12, v9
	v_div_fmas_f32 v9, v9, v20, v12
	v_div_fixup_f32 v9, v9, v16, 1.0
	v_mul_f32_e32 v12, v14, v9
	v_mul_f32_e32 v12, v7, v12
	v_mul_f32_e32 v13, v15, v9
	v_cvt_pk_bf16_f32 v12, v12, v1
	v_mul_f32_e32 v13, v8, v13
	global_store_short v[10:11], v12, off
	v_cvt_pk_bf16_f32 v12, v13, v1
	global_store_short v[10:11], v12, off offset:64
	v_mul_f32_e32 v12, v17, v9
	v_mul_f32_e32 v12, v6, v12
	v_mul_f32_e32 v9, v18, v9
	v_cvt_pk_bf16_f32 v12, v12, v1
	v_mul_f32_e32 v9, v5, v9
	global_store_short v[10:11], v12, off offset:128
	v_cvt_pk_bf16_f32 v9, v9, v1
	ds_read2_b32 v[12:13], v4 offset0:25 offset1:57
	global_store_short v[10:11], v9, off offset:192
	s_waitcnt lgkmcnt(0)
	v_mul_f32_e32 v15, v93, v13
	v_mul_f32_e32 v14, v109, v13
	v_fma_f32 v15, v125, v12, -v15
	v_fma_f32 v14, v141, v12, -v14
	v_mul_f32_e32 v16, v15, v15
	v_mul_f32_e32 v17, v45, v13
	v_fmac_f32_e32 v16, v14, v14
	v_fma_f32 v17, v77, v12, -v17
	v_mul_f32_e32 v13, v29, v13
	v_fmac_f32_e32 v16, v17, v17
	v_fma_f32 v18, v61, v12, -v13
	v_fmac_f32_e32 v16, v18, v18
	s_nop 1
	v_add_f32_dpp v12, v16, v16 quad_perm:[1,0,3,2] row_mask:0xf bank_mask:0xf
	s_nop 1
	v_add_f32_dpp v12, v12, v12 quad_perm:[2,3,0,1] row_mask:0xf bank_mask:0xf
	s_nop 1
	v_add_f32_dpp v12, v12, v12 row_half_mirror row_mask:0xf bank_mask:0xf
	s_nop 1
	v_add_f32_dpp v12, v12, v12 row_mirror row_mask:0xf bank_mask:0xf
	ds_swizzle_b32 v13, v12 offset:swizzle(SWAP,16)
	s_waitcnt lgkmcnt(0)
	v_add_f32_e32 v12, v12, v13
	v_fmamk_f32 v12, v12, 0x3c000000, v230
	v_mul_f32_e32 v13, 0x4f800000, v12
	v_cmp_gt_f32_e32 vcc, s57, v12
	s_nop 1
	v_cndmask_b32_e32 v16, v12, v13, vcc
	v_sqrt_f32_e32 v19, v16
	v_mov_b32_e32 v13, v1
	v_or_b32_e32 v12, 0xc800, v0
	v_lshl_add_u64 v[12:13], v[2:3], 0, v[12:13]
	v_add_u32_e32 v20, -1, v19
	v_add_u32_e32 v21, 1, v19
	v_fma_f32 v22, -v20, v19, v16
	v_fma_f32 v23, -v21, v19, v16
	v_cmp_ge_f32_e64 s[4:5], 0, v22
	s_nop 1
	v_cndmask_b32_e64 v19, v19, v20, s[4:5]
	v_cmp_lt_f32_e64 s[4:5], 0, v23
	s_nop 1
	v_cndmask_b32_e64 v19, v19, v21, s[4:5]
	v_mul_f32_e32 v20, 0x37800000, v19
	v_cndmask_b32_e32 v19, v19, v20, vcc
	v_cmp_class_f32_e32 vcc, v16, v231
	s_nop 1
	v_cndmask_b32_e32 v16, v19, v16, vcc
	v_div_scale_f32 v19, s[0:1], v16, v16, 1.0
	v_rcp_f32_e32 v20, v19
	v_div_scale_f32 v9, vcc, 1.0, v16, 1.0
	v_fma_f32 v10, -v19, v20, 1.0
	v_fmac_f32_e32 v20, v10, v20
	v_mul_f32_e32 v10, v9, v20
	v_fma_f32 v11, -v19, v10, v9
	v_fmac_f32_e32 v10, v11, v20
	v_fma_f32 v9, -v19, v10, v9
	v_div_fmas_f32 v9, v9, v20, v10
	v_div_fixup_f32 v9, v9, v16, 1.0
	v_mul_f32_e32 v10, v14, v9
	v_mul_f32_e32 v10, v7, v10
	v_mul_f32_e32 v11, v15, v9
	v_cvt_pk_bf16_f32 v10, v10, v1
	v_mul_f32_e32 v11, v8, v11
	global_store_short v[12:13], v10, off
	v_cvt_pk_bf16_f32 v10, v11, v1
	global_store_short v[12:13], v10, off offset:64
	v_mul_f32_e32 v10, v17, v9
	v_mul_f32_e32 v10, v6, v10
	v_mul_f32_e32 v9, v18, v9
	v_cvt_pk_bf16_f32 v10, v10, v1
	v_mul_f32_e32 v9, v5, v9
	global_store_short v[12:13], v10, off offset:128
	v_cvt_pk_bf16_f32 v9, v9, v1
	ds_read2_b32 v[10:11], v4 offset0:26 offset1:58
	global_store_short v[12:13], v9, off offset:192
	s_waitcnt lgkmcnt(0)
	v_mul_f32_e32 v15, v94, v11
	v_mul_f32_e32 v14, v110, v11
	v_fma_f32 v15, v126, v10, -v15
	v_fma_f32 v14, v142, v10, -v14
	v_mul_f32_e32 v16, v15, v15
	v_mul_f32_e32 v17, v46, v11
	v_fmac_f32_e32 v16, v14, v14
	v_fma_f32 v17, v78, v10, -v17
	v_mul_f32_e32 v11, v30, v11
	v_fmac_f32_e32 v16, v17, v17
	v_fma_f32 v18, v62, v10, -v11
	v_fmac_f32_e32 v16, v18, v18
	s_nop 1
	v_add_f32_dpp v10, v16, v16 quad_perm:[1,0,3,2] row_mask:0xf bank_mask:0xf
	s_nop 1
	v_add_f32_dpp v10, v10, v10 quad_perm:[2,3,0,1] row_mask:0xf bank_mask:0xf
	s_nop 1
	v_add_f32_dpp v10, v10, v10 row_half_mirror row_mask:0xf bank_mask:0xf
	s_nop 1
	v_add_f32_dpp v10, v10, v10 row_mirror row_mask:0xf bank_mask:0xf
	ds_swizzle_b32 v11, v10 offset:swizzle(SWAP,16)
	s_waitcnt lgkmcnt(0)
	v_add_f32_e32 v10, v10, v11
	v_fmamk_f32 v10, v10, 0x3c000000, v230
	v_mul_f32_e32 v11, 0x4f800000, v10
	v_cmp_gt_f32_e32 vcc, s57, v10
	s_nop 1
	v_cndmask_b32_e32 v16, v10, v11, vcc
	v_sqrt_f32_e32 v19, v16
	v_mov_b32_e32 v11, v1
	v_or_b32_e32 v10, 0xd000, v0
	v_lshl_add_u64 v[10:11], v[2:3], 0, v[10:11]
	v_add_u32_e32 v20, -1, v19
	v_add_u32_e32 v21, 1, v19
	v_fma_f32 v22, -v20, v19, v16
	v_fma_f32 v23, -v21, v19, v16
	v_cmp_ge_f32_e64 s[4:5], 0, v22
	v_or_b32_e32 v0, 0xd800, v0
	v_lshl_add_u64 v[2:3], v[2:3], 0, v[0:1]
	v_cndmask_b32_e64 v19, v19, v20, s[4:5]
	v_cmp_lt_f32_e64 s[4:5], 0, v23
	s_nop 1
	v_cndmask_b32_e64 v19, v19, v21, s[4:5]
	v_mul_f32_e32 v20, 0x37800000, v19
	v_cndmask_b32_e32 v19, v19, v20, vcc
	v_cmp_class_f32_e32 vcc, v16, v231
	s_nop 1
	v_cndmask_b32_e32 v16, v19, v16, vcc
	v_div_scale_f32 v19, s[0:1], v16, v16, 1.0
	v_rcp_f32_e32 v20, v19
	v_div_scale_f32 v9, vcc, 1.0, v16, 1.0
	v_fma_f32 v12, -v19, v20, 1.0
	v_fmac_f32_e32 v20, v12, v20
	v_mul_f32_e32 v12, v9, v20
	v_fma_f32 v13, -v19, v12, v9
	v_fmac_f32_e32 v12, v13, v20
	v_fma_f32 v9, -v19, v12, v9
	v_div_fmas_f32 v9, v9, v20, v12
	v_div_fixup_f32 v9, v9, v16, 1.0
	v_mul_f32_e32 v12, v14, v9
	v_mul_f32_e32 v12, v7, v12
	v_mul_f32_e32 v13, v15, v9
	v_cvt_pk_bf16_f32 v12, v12, v1
	v_mul_f32_e32 v13, v8, v13
	global_store_short v[10:11], v12, off
	v_cvt_pk_bf16_f32 v12, v13, v1
	global_store_short v[10:11], v12, off offset:64
	v_mul_f32_e32 v12, v17, v9
	v_mul_f32_e32 v12, v6, v12
	v_mul_f32_e32 v9, v18, v9
	v_cvt_pk_bf16_f32 v12, v12, v1
	v_mul_f32_e32 v9, v5, v9
	global_store_short v[10:11], v12, off offset:128
	v_cvt_pk_bf16_f32 v9, v9, v1
	ds_read2_b32 v[12:13], v4 offset0:27 offset1:59
	global_store_short v[10:11], v9, off offset:192
	s_waitcnt lgkmcnt(0)
	v_mul_f32_e32 v14, v95, v13
	v_mul_f32_e32 v4, v111, v13
	v_fma_f32 v14, v127, v12, -v14
	v_fma_f32 v4, v143, v12, -v4
	v_mul_f32_e32 v15, v14, v14
	v_mul_f32_e32 v16, v47, v13
	v_fmac_f32_e32 v15, v4, v4
	v_fma_f32 v16, v79, v12, -v16
	v_mul_f32_e32 v13, v31, v13
	v_fmac_f32_e32 v15, v16, v16
	v_fma_f32 v12, v63, v12, -v13
	v_fmac_f32_e32 v15, v12, v12
	s_nop 1
	v_add_f32_dpp v13, v15, v15 quad_perm:[1,0,3,2] row_mask:0xf bank_mask:0xf
	s_nop 1
	v_add_f32_dpp v13, v13, v13 quad_perm:[2,3,0,1] row_mask:0xf bank_mask:0xf
	s_nop 1
	v_add_f32_dpp v13, v13, v13 row_half_mirror row_mask:0xf bank_mask:0xf
	s_nop 1
	v_add_f32_dpp v13, v13, v13 row_mirror row_mask:0xf bank_mask:0xf
	ds_swizzle_b32 v15, v13 offset:swizzle(SWAP,16)
	s_waitcnt lgkmcnt(0)
	v_add_f32_e32 v13, v13, v15
	v_fmamk_f32 v13, v13, 0x3c000000, v230
	v_mul_f32_e32 v15, 0x4f800000, v13
	v_cmp_gt_f32_e32 vcc, s57, v13
	s_nop 1
	v_cndmask_b32_e32 v13, v13, v15, vcc
	v_sqrt_f32_e32 v15, v13
	s_nop 0
	v_add_u32_e32 v0, -1, v15
	v_add_u32_e32 v17, 1, v15
	v_fma_f32 v18, -v0, v15, v13
	v_fma_f32 v19, -v17, v15, v13
	v_cmp_ge_f32_e64 s[4:5], 0, v18
	s_nop 1
	v_cndmask_b32_e64 v0, v15, v0, s[4:5]
	v_cmp_lt_f32_e64 s[4:5], 0, v19
	s_nop 1
	v_cndmask_b32_e64 v0, v0, v17, s[4:5]
	v_mul_f32_e32 v15, 0x37800000, v0
	v_cndmask_b32_e32 v0, v0, v15, vcc
	v_cmp_class_f32_e32 vcc, v13, v231
	s_nop 1
	v_cndmask_b32_e32 v0, v0, v13, vcc
	v_div_scale_f32 v13, s[0:1], v0, v0, 1.0
	v_rcp_f32_e32 v15, v13
	v_div_scale_f32 v9, vcc, 1.0, v0, 1.0
	v_readlane_b32 s0, v249, 54
	v_fma_f32 v10, -v13, v15, 1.0
	v_fmac_f32_e32 v15, v10, v15
	v_mul_f32_e32 v10, v9, v15
	v_fma_f32 v11, -v13, v10, v9
	v_fmac_f32_e32 v10, v11, v15
	v_fma_f32 v9, -v13, v10, v9
	v_div_fmas_f32 v9, v9, v15, v10
	v_div_fixup_f32 v0, v9, v0, 1.0
	v_mul_f32_e32 v4, v4, v0
	v_mul_f32_e32 v4, v7, v4
	v_mul_f32_e32 v9, v14, v0
	v_cvt_pk_bf16_f32 v4, v4, v1
	v_mul_f32_e32 v7, v8, v9
	global_store_short v[2:3], v4, off
	v_cvt_pk_bf16_f32 v4, v7, v1
	global_store_short v[2:3], v4, off offset:64
	v_mul_f32_e32 v4, v16, v0
	v_mul_f32_e32 v0, v12, v0
	s_add_i32 s62, s62, s0
	v_mul_f32_e32 v4, v6, v4
	v_mul_f32_e32 v0, v5, v0
	s_cmp_gt_i32 s62, 63
	v_cvt_pk_bf16_f32 v4, v4, v1
	global_store_short v[2:3], v4, off offset:128
	v_cvt_pk_bf16_f32 v0, v0, v1
	global_store_short v[2:3], v0, off offset:192
	s_cbranch_scc1 .LBB0_2175
